# GEMM SP2 loops: hand-off barrier moved up before the last 2 MFMAs of each compute block, tail MFMAs at s_setprio 2 (on top of P5 load restructure)
# speedup vs baseline: 1.0016x; 1.0016x over previous
; #define PG8_STAGE(bufoff, gbase, voff) do { _Pragma("unroll") for (int _i = 0; _i < 2; ++_i) \
;         __builtin_amdgcn_global_load_lds((const unsigned*)((const char*)(gbase) + (voff)[_i]), (LAS unsigned*)(lds + (bufoff) + ldsw + _i * 8192), 16, 0, 0); } while (0)
; #define PG8_LDA(dst, b, h) do { _Pragma("unroll") for (int m = 0; m < 4; ++m) _Pragma("unroll") for (int k = 0; k < 2; ++k) dst[m][k] = *(const LAS bf16x8*)(lds + PG8_SA(b, h) + aoff + m * 2048 + k * 1024); } while (0)
; #define PG8_LDB(dst, b, h) do { _Pragma("unroll") for (int n = 0; n < 2; ++n) _Pragma("unroll") for (int k = 0; k < 2; ++k) dst[n][k] = *(const LAS bf16x8*)(lds + PG8_SB(b, h) + boff + n * 2048 + k * 1024); } while (0)
; #define PG8_MMA(ai, bj, At, Bt) do { __builtin_amdgcn_s_setprio(1); _Pragma("unroll") for (int m = 0; m < 4; ++m) _Pragma("unroll") for (int n = 0; n < 2; ++n) _Pragma("unroll") for (int k = 0; k < 2; ++k) \
;         acc[ai][bj][m][n] = __builtin_amdgcn_mfma_f32_16x16x32_bf16(Bt[n][k], At[m][k], acc[ai][bj][m][n], 0, 0, 0); __builtin_amdgcn_s_setprio(0); } while (0)
; #define PG8_WAIT_V(n) asm volatile("s_waitcnt vmcnt(" #n ")" ::: "memory")
; #define PG8_WAIT_L(n) asm volatile("s_waitcnt lgkmcnt(" #n ")" ::: "memory")
; #define PG8_BAR __builtin_amdgcn_s_barrier()
; #define PG8_SCHED __builtin_amdgcn_sched_barrier(0)
; template <class Epi, class Sched, bool ALIGN_EPI = true, bool SP2 = true>
; __device__ __forceinline__ void gemm_phase(LAS unsigned char* lds, const bf16_t* Ag, const bf16_t* Btg, const int K, const int lda, const int ldb, const Sched& S, const Epi& E) {
;     ...
;             const bool last = (t == nt - 2);
;             const char* a1 = cA + (size_t)(t + 1) * kstep;
;             const char* a2 = last ? nA : cA + (size_t)(t + 2) * kstep; const char* b2 = last ? nB : cB + (size_t)(t + 2) * kstep;
;             const char* a3 = a2 + kstep; const char* b3 = b2 + kstep;
;             if constexpr (SP2) {
;             PG8_LDB(B0, 0, 0); PG8_LDB(B1, 0, 1); PG8_SCHED; PG8_LDA(At, 0, 0); PG8_STAGE(PG8_SA(1, 1), a1 + hstepA, voffA);
;             PG8_WAIT_V(8); PG8_WAIT_L(0); PG8_BAR; PG8_MMA(0, 0, At, B0); PG8_MMA(0, 1, At, B1); PG8_BAR; PG8_SCHED;
;             PG8_LDA(At, 0, 1); PG8_STAGE(PG8_SB(0, 0), b2, voffB); PG8_STAGE(PG8_SB(0, 1), b2 + hstepB, voffB); PG8_STAGE(PG8_SA(0, 0), a2, voffA);
.LBB0_119:
	ds_read_b128 v[152:155], v149
	ds_read_b128 v[156:159], v149 offset:1024
	ds_read_b128 v[160:163], v149 offset:2048
	ds_read_b128 v[164:167], v149 offset:3072
	ds_read_b128 v[168:171], v150
	ds_read_b128 v[172:175], v150 offset:1024
	ds_read_b128 v[178:181], v150 offset:2048
	ds_read_b128 v[182:185], v150 offset:3072
	s_add_u32 s10, s34, 0xfff80080
	s_addc_u32 s11, s35, -1
	s_cmp_eq_u32 s60, 28
	s_cselect_b32 s51, s8, s11
	s_cselect_b32 s50, s9, s10
	s_cselect_b32 s39, s33, s59
	s_cselect_b32 s38, s6, s7
	v_lshl_add_u64 v[146:147], s[34:35], 0, v[138:139]
	s_add_i32 m0, s46, 0xc000
	ds_read_b128 v[186:189], v151
	ds_read_b128 v[190:193], v151 offset:1024
	ds_read_b128 v[194:197], v151 offset:2048
	ds_read_b128 v[198:201], v151 offset:3072
	ds_read_b128 v[202:205], v151 offset:4096
	ds_read_b128 v[206:209], v151 offset:5120
	ds_read_b128 v[210:213], v151 offset:6144
	ds_read_b128 v[214:217], v151 offset:7168
	global_load_lds_dwordx4 v[146:147], off
	v_lshl_add_u64 v[146:147], s[34:35], 0, v[140:141]
	s_add_i32 m0, s46, 0xe000
	s_nop 0
	global_load_lds_dwordx4 v[146:147], off
	s_waitcnt vmcnt(8)
	s_waitcnt lgkmcnt(0)
	s_barrier
	s_setprio 1
	s_waitcnt lgkmcnt(0)
	v_mfma_f32_16x16x32_bf16 v[124:127], v[152:155], v[186:189], v[124:127]
	v_mfma_f32_16x16x32_bf16 v[116:119], v[160:163], v[186:189], v[116:119]
	v_mfma_f32_16x16x32_bf16 v[108:111], v[152:155], v[194:197], v[108:111]
	v_mfma_f32_16x16x32_bf16 v[100:103], v[160:163], v[194:197], v[100:103]
	v_mfma_f32_16x16x32_bf16 v[92:95], v[152:155], v[202:205], v[92:95]
	v_mfma_f32_16x16x32_bf16 v[84:87], v[160:163], v[202:205], v[84:87]
	v_mfma_f32_16x16x32_bf16 v[76:79], v[152:155], v[210:213], v[76:79]
	v_mfma_f32_16x16x32_bf16 v[68:71], v[160:163], v[210:213], v[68:71]
	v_mfma_f32_16x16x32_bf16 v[124:127], v[156:159], v[190:193], v[124:127]
	v_mfma_f32_16x16x32_bf16 v[116:119], v[164:167], v[190:193], v[116:119]
	v_mfma_f32_16x16x32_bf16 v[108:111], v[156:159], v[198:201], v[108:111]
	v_mfma_f32_16x16x32_bf16 v[100:103], v[164:167], v[198:201], v[100:103]
	v_mfma_f32_16x16x32_bf16 v[92:95], v[156:159], v[206:209], v[92:95]
	v_mfma_f32_16x16x32_bf16 v[84:87], v[164:167], v[206:209], v[84:87]
	v_mfma_f32_16x16x32_bf16 v[76:79], v[156:159], v[214:217], v[76:79]
	v_mfma_f32_16x16x32_bf16 v[68:71], v[164:167], v[214:217], v[68:71]
	s_setprio 0
	s_setprio 1
	v_mfma_f32_16x16x32_bf16 v[120:123], v[168:171], v[186:189], v[120:123]
	v_mfma_f32_16x16x32_bf16 v[112:115], v[178:181], v[186:189], v[112:115]
	v_mfma_f32_16x16x32_bf16 v[104:107], v[168:171], v[194:197], v[104:107]
	v_mfma_f32_16x16x32_bf16 v[96:99], v[178:181], v[194:197], v[96:99]
	v_mfma_f32_16x16x32_bf16 v[88:91], v[168:171], v[202:205], v[88:91]
	v_mfma_f32_16x16x32_bf16 v[80:83], v[178:181], v[202:205], v[80:83]
	v_mfma_f32_16x16x32_bf16 v[72:75], v[168:171], v[210:213], v[72:75]
	v_mfma_f32_16x16x32_bf16 v[64:67], v[178:181], v[210:213], v[64:67]
	v_mfma_f32_16x16x32_bf16 v[120:123], v[172:175], v[190:193], v[120:123]
	v_mfma_f32_16x16x32_bf16 v[112:115], v[182:185], v[190:193], v[112:115]
	v_mfma_f32_16x16x32_bf16 v[104:107], v[172:175], v[198:201], v[104:107]
	v_mfma_f32_16x16x32_bf16 v[96:99], v[182:185], v[198:201], v[96:99]
	v_mfma_f32_16x16x32_bf16 v[88:91], v[172:175], v[206:209], v[88:91]
	v_mfma_f32_16x16x32_bf16 v[80:83], v[182:185], v[206:209], v[80:83]
	s_setprio 2
	s_barrier
	v_mfma_f32_16x16x32_bf16 v[72:75], v[172:175], v[214:217], v[72:75]
	v_mfma_f32_16x16x32_bf16 v[64:67], v[182:185], v[214:217], v[64:67]
	s_setprio 0
	s_add_i32 s10, s57, s37
	v_lshl_add_u64 v[146:147], s[38:39], 0, v[132:133]
	s_mov_b32 m0, s10
	ds_read_b128 v[186:189], v151 offset:16384
	ds_read_b128 v[190:193], v151 offset:17408
	ds_read_b128 v[194:197], v151 offset:18432
	ds_read_b128 v[198:201], v151 offset:19456
	ds_read_b128 v[202:205], v151 offset:20480
	ds_read_b128 v[206:209], v151 offset:21504
	ds_read_b128 v[210:213], v151 offset:22528
	ds_read_b128 v[214:217], v151 offset:23552
	global_load_lds_dwordx4 v[146:147], off
	s_add_i32 m0, s10, 0x2000
	s_add_u32 s62, s38, 0x80000
	v_lshl_add_u64 v[218:219], s[38:39], 0, v[128:129]
	s_addc_u32 s63, s39, 0
	s_add_i32 s10, s58, s37
	global_load_lds_dwordx4 v[218:219], off
	v_lshl_add_u64 v[220:221], s[62:63], 0, v[132:133]
	s_mov_b32 m0, s10
	v_lshl_add_u64 v[222:223], s[50:51], 0, v[130:131]
	global_load_lds_dwordx4 v[220:221], off
	v_lshl_add_u64 v[220:221], s[62:63], 0, v[128:129]
	s_add_i32 m0, s10, 0x2000
	s_nop 0
	global_load_lds_dwordx4 v[220:221], off
	v_lshl_add_u64 v[220:221], s[50:51], 0, v[134:135]
	s_mov_b32 m0, s46
	s_nop 0
	global_load_lds_dwordx4 v[220:221], off
	s_mov_b32 m0, s47
	s_nop 0
	global_load_lds_dwordx4 v[222:223], off
	s_waitcnt vmcnt(8)
	s_waitcnt lgkmcnt(0)
	s_barrier
; #define PG8_STAGE(bufoff, gbase, voff) do { _Pragma("unroll") for (int _i = 0; _i < 2; ++_i) \
;         __builtin_amdgcn_global_load_lds((const unsigned*)((const char*)(gbase) + (voff)[_i]), (LAS unsigned*)(lds + (bufoff) + ldsw + _i * 8192), 16, 0, 0); } while (0)
; #define PG8_LDA(dst, b, h) do { _Pragma("unroll") for (int m = 0; m < 4; ++m) _Pragma("unroll") for (int k = 0; k < 2; ++k) dst[m][k] = *(const LAS bf16x8*)(lds + PG8_SA(b, h) + aoff + m * 2048 + k * 1024); } while (0)
; #define PG8_LDB(dst, b, h) do { _Pragma("unroll") for (int n = 0; n < 2; ++n) _Pragma("unroll") for (int k = 0; k < 2; ++k) dst[n][k] = *(const LAS bf16x8*)(lds + PG8_SB(b, h) + boff + n * 2048 + k * 1024); } while (0)
; #define PG8_MMA(ai, bj, At, Bt) do { __builtin_amdgcn_s_setprio(1); _Pragma("unroll") for (int m = 0; m < 4; ++m) _Pragma("unroll") for (int n = 0; n < 2; ++n) _Pragma("unroll") for (int k = 0; k < 2; ++k) \
;         acc[ai][bj][m][n] = __builtin_amdgcn_mfma_f32_16x16x32_bf16(Bt[n][k], At[m][k], acc[ai][bj][m][n], 0, 0, 0); __builtin_amdgcn_s_setprio(0); } while (0)
; #define PG8_WAIT_V(n) asm volatile("s_waitcnt vmcnt(" #n ")" ::: "memory")
; #define PG8_WAIT_L(n) asm volatile("s_waitcnt lgkmcnt(" #n ")" ::: "memory")
; #define PG8_BAR __builtin_amdgcn_s_barrier()
; #define PG8_SCHED __builtin_amdgcn_sched_barrier(0)
; template <class Epi, class Sched, bool ALIGN_EPI = true, bool SP2 = true>
; __device__ __forceinline__ void gemm_phase(LAS unsigned char* lds, const bf16_t* Ag, const bf16_t* Btg, const int K, const int lda, const int ldb, const Sched& S, const Epi& E) {
;     ...
;             PG8_WAIT_V(8); PG8_WAIT_L(0); PG8_BAR; PG8_MMA(1, 0, At, B0); PG8_MMA(1, 1, At, B1); PG8_BAR; PG8_SCHED;
;             PG8_LDB(B0, 1, 0); PG8_LDB(B1, 1, 1); PG8_SCHED; PG8_LDA(At, 1, 0); PG8_STAGE(PG8_SA(0, 1), a2 + hstepA, voffA);
;             PG8_WAIT_V(8); PG8_WAIT_L(0); PG8_BAR; PG8_MMA(0, 0, At, B0); PG8_MMA(0, 1, At, B1); PG8_BAR; PG8_SCHED;
	s_setprio 1
	s_waitcnt lgkmcnt(0)
	v_mfma_f32_16x16x32_bf16 v[60:63], v[152:155], v[186:189], v[60:63]
	v_mfma_f32_16x16x32_bf16 v[52:55], v[160:163], v[186:189], v[52:55]
	v_mfma_f32_16x16x32_bf16 v[44:47], v[152:155], v[194:197], v[44:47]
	v_mfma_f32_16x16x32_bf16 v[36:39], v[160:163], v[194:197], v[36:39]
	v_mfma_f32_16x16x32_bf16 v[28:31], v[152:155], v[202:205], v[28:31]
	v_mfma_f32_16x16x32_bf16 v[20:23], v[160:163], v[202:205], v[20:23]
	v_mfma_f32_16x16x32_bf16 v[12:15], v[152:155], v[210:213], v[12:15]
	v_mfma_f32_16x16x32_bf16 v[4:7], v[160:163], v[210:213], v[4:7]
	v_mfma_f32_16x16x32_bf16 v[60:63], v[156:159], v[190:193], v[60:63]
	v_mfma_f32_16x16x32_bf16 v[52:55], v[164:167], v[190:193], v[52:55]
	v_mfma_f32_16x16x32_bf16 v[44:47], v[156:159], v[198:201], v[44:47]
	v_mfma_f32_16x16x32_bf16 v[36:39], v[164:167], v[198:201], v[36:39]
	v_mfma_f32_16x16x32_bf16 v[28:31], v[156:159], v[206:209], v[28:31]
	v_mfma_f32_16x16x32_bf16 v[20:23], v[164:167], v[206:209], v[20:23]
	v_mfma_f32_16x16x32_bf16 v[12:15], v[156:159], v[214:217], v[12:15]
	v_mfma_f32_16x16x32_bf16 v[4:7], v[164:167], v[214:217], v[4:7]
	s_setprio 0
	s_setprio 1
	v_mfma_f32_16x16x32_bf16 v[56:59], v[168:171], v[186:189], v[56:59]
	v_mfma_f32_16x16x32_bf16 v[48:51], v[178:181], v[186:189], v[48:51]
	v_mfma_f32_16x16x32_bf16 v[40:43], v[168:171], v[194:197], v[40:43]
	v_mfma_f32_16x16x32_bf16 v[32:35], v[178:181], v[194:197], v[32:35]
	v_mfma_f32_16x16x32_bf16 v[24:27], v[168:171], v[202:205], v[24:27]
	v_mfma_f32_16x16x32_bf16 v[16:19], v[178:181], v[202:205], v[16:19]
	v_mfma_f32_16x16x32_bf16 v[8:11], v[168:171], v[210:213], v[8:11]
	v_mfma_f32_16x16x32_bf16 v[0:3], v[178:181], v[210:213], v[0:3]
	v_mfma_f32_16x16x32_bf16 v[56:59], v[172:175], v[190:193], v[56:59]
	v_mfma_f32_16x16x32_bf16 v[48:51], v[182:185], v[190:193], v[48:51]
	v_mfma_f32_16x16x32_bf16 v[40:43], v[172:175], v[198:201], v[40:43]
	v_mfma_f32_16x16x32_bf16 v[32:35], v[182:185], v[198:201], v[32:35]
	v_mfma_f32_16x16x32_bf16 v[24:27], v[172:175], v[206:209], v[24:27]
	v_mfma_f32_16x16x32_bf16 v[16:19], v[182:185], v[206:209], v[16:19]
	s_setprio 2
	s_barrier
	v_mfma_f32_16x16x32_bf16 v[8:11], v[172:175], v[214:217], v[8:11]
	v_mfma_f32_16x16x32_bf16 v[0:3], v[182:185], v[214:217], v[0:3]
	s_setprio 0
	s_add_i32 s10, 0, 0x18000
	s_add_i32 s11, 0, 0x1c000
	v_add_u32_e32 v164, s10, v148
	v_add_u32_e32 v182, s11, v148
	ds_read_b128 v[152:155], v164
	ds_read_b128 v[156:159], v164 offset:1024
	ds_read_b128 v[160:163], v164 offset:2048
	ds_read_b128 v[164:167], v164 offset:3072
	ds_read_b128 v[168:171], v182
	ds_read_b128 v[172:175], v182 offset:1024
	ds_read_b128 v[178:181], v182 offset:2048
	ds_read_b128 v[182:185], v182 offset:3072
	s_add_u32 s50, s50, 0x80000
	s_addc_u32 s51, s51, 0
	s_mov_b32 m0, s52
	v_lshl_add_u64 v[224:225], s[50:51], 0, v[134:135]
	ds_read_b128 v[186:189], v151 offset:32768
	ds_read_b128 v[190:193], v151 offset:33792
	ds_read_b128 v[194:197], v151 offset:34816
	ds_read_b128 v[198:201], v151 offset:35840
	ds_read_b128 v[202:205], v151 offset:36864
	ds_read_b128 v[206:209], v151 offset:37888
	ds_read_b128 v[210:213], v151 offset:38912
	ds_read_b128 v[214:217], v151 offset:39936
	global_load_lds_dwordx4 v[224:225], off
	v_lshl_add_u64 v[224:225], s[50:51], 0, v[130:131]
	s_mov_b32 m0, s53
	s_nop 0
	global_load_lds_dwordx4 v[224:225], off
	s_waitcnt vmcnt(8)
	s_waitcnt lgkmcnt(0)
	s_barrier
	s_setprio 1
	s_waitcnt lgkmcnt(0)
	v_mfma_f32_16x16x32_bf16 v[124:127], v[152:155], v[186:189], v[124:127]
	v_mfma_f32_16x16x32_bf16 v[116:119], v[160:163], v[186:189], v[116:119]
	v_mfma_f32_16x16x32_bf16 v[108:111], v[152:155], v[194:197], v[108:111]
	v_mfma_f32_16x16x32_bf16 v[100:103], v[160:163], v[194:197], v[100:103]
	v_mfma_f32_16x16x32_bf16 v[92:95], v[152:155], v[202:205], v[92:95]
	v_mfma_f32_16x16x32_bf16 v[84:87], v[160:163], v[202:205], v[84:87]
	v_mfma_f32_16x16x32_bf16 v[76:79], v[152:155], v[210:213], v[76:79]
	v_mfma_f32_16x16x32_bf16 v[68:71], v[160:163], v[210:213], v[68:71]
	v_mfma_f32_16x16x32_bf16 v[124:127], v[156:159], v[190:193], v[124:127]
	v_mfma_f32_16x16x32_bf16 v[116:119], v[164:167], v[190:193], v[116:119]
	v_mfma_f32_16x16x32_bf16 v[108:111], v[156:159], v[198:201], v[108:111]
	v_mfma_f32_16x16x32_bf16 v[100:103], v[164:167], v[198:201], v[100:103]
	v_mfma_f32_16x16x32_bf16 v[92:95], v[156:159], v[206:209], v[92:95]
	v_mfma_f32_16x16x32_bf16 v[84:87], v[164:167], v[206:209], v[84:87]
	v_mfma_f32_16x16x32_bf16 v[76:79], v[156:159], v[214:217], v[76:79]
	v_mfma_f32_16x16x32_bf16 v[68:71], v[164:167], v[214:217], v[68:71]
	s_setprio 0
	s_setprio 1
	v_mfma_f32_16x16x32_bf16 v[120:123], v[168:171], v[186:189], v[120:123]
	v_mfma_f32_16x16x32_bf16 v[112:115], v[178:181], v[186:189], v[112:115]
	v_mfma_f32_16x16x32_bf16 v[104:107], v[168:171], v[194:197], v[104:107]
	v_mfma_f32_16x16x32_bf16 v[96:99], v[178:181], v[194:197], v[96:99]
	v_mfma_f32_16x16x32_bf16 v[88:91], v[168:171], v[202:205], v[88:91]
	v_mfma_f32_16x16x32_bf16 v[80:83], v[178:181], v[202:205], v[80:83]
	v_mfma_f32_16x16x32_bf16 v[72:75], v[168:171], v[210:213], v[72:75]
	v_mfma_f32_16x16x32_bf16 v[64:67], v[178:181], v[210:213], v[64:67]
	v_mfma_f32_16x16x32_bf16 v[120:123], v[172:175], v[190:193], v[120:123]
	v_mfma_f32_16x16x32_bf16 v[112:115], v[182:185], v[190:193], v[112:115]
	v_mfma_f32_16x16x32_bf16 v[104:107], v[172:175], v[198:201], v[104:107]
	v_mfma_f32_16x16x32_bf16 v[96:99], v[182:185], v[198:201], v[96:99]
	v_mfma_f32_16x16x32_bf16 v[88:91], v[172:175], v[206:209], v[88:91]
	v_mfma_f32_16x16x32_bf16 v[80:83], v[182:185], v[206:209], v[80:83]
	s_setprio 2
	s_barrier
; #define PG8_STAGE(bufoff, gbase, voff) do { _Pragma("unroll") for (int _i = 0; _i < 2; ++_i) \
;         __builtin_amdgcn_global_load_lds((const unsigned*)((const char*)(gbase) + (voff)[_i]), (LAS unsigned*)(lds + (bufoff) + ldsw + _i * 8192), 16, 0, 0); } while (0)
; #define PG8_LDA(dst, b, h) do { _Pragma("unroll") for (int m = 0; m < 4; ++m) _Pragma("unroll") for (int k = 0; k < 2; ++k) dst[m][k] = *(const LAS bf16x8*)(lds + PG8_SA(b, h) + aoff + m * 2048 + k * 1024); } while (0)
; #define PG8_MMA(ai, bj, At, Bt) do { __builtin_amdgcn_s_setprio(1); _Pragma("unroll") for (int m = 0; m < 4; ++m) _Pragma("unroll") for (int n = 0; n < 2; ++n) _Pragma("unroll") for (int k = 0; k < 2; ++k) \
;         acc[ai][bj][m][n] = __builtin_amdgcn_mfma_f32_16x16x32_bf16(Bt[n][k], At[m][k], acc[ai][bj][m][n], 0, 0, 0); __builtin_amdgcn_s_setprio(0); } while (0)
; #define PG8_WAIT_V(n) asm volatile("s_waitcnt vmcnt(" #n ")" ::: "memory")
; #define PG8_WAIT_L(n) asm volatile("s_waitcnt lgkmcnt(" #n ")" ::: "memory")
; #define PG8_BAR __builtin_amdgcn_s_barrier()
; #define PG8_SCHED __builtin_amdgcn_sched_barrier(0)
; template <class Epi, class Sched, bool ALIGN_EPI = true, bool SP2 = true>
; __device__ __forceinline__ void gemm_phase(LAS unsigned char* lds, const bf16_t* Ag, const bf16_t* Btg, const int K, const int lda, const int ldb, const Sched& S, const Epi& E) {
;     ...
;             PG8_LDA(At, 1, 1); PG8_STAGE(PG8_SB(1, 0), b3, voffB); PG8_STAGE(PG8_SB(1, 1), b3 + hstepB, voffB); PG8_STAGE(PG8_SA(1, 0), a3, voffA);
;             PG8_WAIT_V(8); PG8_WAIT_L(0); PG8_BAR; PG8_MMA(1, 0, At, B0); PG8_MMA(1, 1, At, B1); PG8_BAR; PG8_SCHED;
	v_mfma_f32_16x16x32_bf16 v[72:75], v[172:175], v[214:217], v[72:75]
	v_mfma_f32_16x16x32_bf16 v[64:67], v[182:185], v[214:217], v[64:67]
	s_setprio 0
	s_add_i32 s10, s10, s37
	v_lshl_add_u64 v[146:147], v[146:147], 0, s[16:17]
	s_mov_b32 m0, s10
	ds_read_b128 v[186:189], v151 offset:49152
	ds_read_b128 v[190:193], v151 offset:50176
	ds_read_b128 v[194:197], v151 offset:51200
	ds_read_b128 v[198:201], v151 offset:52224
	ds_read_b128 v[202:205], v151 offset:53248
	ds_read_b128 v[206:209], v151 offset:54272
	ds_read_b128 v[210:213], v151 offset:55296
	ds_read_b128 v[214:217], v151 offset:56320
	global_load_lds_dwordx4 v[146:147], off
	s_add_i32 m0, s10, 0x2000
	s_add_u32 s38, s38, 0x80080
	v_lshl_add_u64 v[146:147], v[218:219], 0, s[16:17]
	s_addc_u32 s39, s39, 0
	s_add_i32 s10, s11, s37
	global_load_lds_dwordx4 v[146:147], off
	v_lshl_add_u64 v[146:147], s[38:39], 0, v[132:133]
	s_mov_b32 m0, s10
	s_nop 0
	global_load_lds_dwordx4 v[146:147], off
	v_lshl_add_u64 v[146:147], s[38:39], 0, v[128:129]
	s_add_i32 m0, s10, 0x2000
	s_nop 0
	global_load_lds_dwordx4 v[146:147], off
	v_lshl_add_u64 v[146:147], v[220:221], 0, s[16:17]
	s_mov_b32 m0, s54
	s_nop 0
	global_load_lds_dwordx4 v[146:147], off
	v_lshl_add_u64 v[146:147], v[222:223], 0, s[16:17]
	s_mov_b32 m0, s55
	s_nop 0
	global_load_lds_dwordx4 v[146:147], off
	s_waitcnt vmcnt(8)
	s_waitcnt lgkmcnt(0)
	s_barrier
	s_setprio 1
	s_waitcnt lgkmcnt(0)
	v_mfma_f32_16x16x32_bf16 v[60:63], v[152:155], v[186:189], v[60:63]
	v_mfma_f32_16x16x32_bf16 v[52:55], v[160:163], v[186:189], v[52:55]
	v_mfma_f32_16x16x32_bf16 v[44:47], v[152:155], v[194:197], v[44:47]
	v_mfma_f32_16x16x32_bf16 v[36:39], v[160:163], v[194:197], v[36:39]
	v_mfma_f32_16x16x32_bf16 v[28:31], v[152:155], v[202:205], v[28:31]
	v_mfma_f32_16x16x32_bf16 v[20:23], v[160:163], v[202:205], v[20:23]
	v_mfma_f32_16x16x32_bf16 v[12:15], v[152:155], v[210:213], v[12:15]
	v_mfma_f32_16x16x32_bf16 v[4:7], v[160:163], v[210:213], v[4:7]
	v_mfma_f32_16x16x32_bf16 v[60:63], v[156:159], v[190:193], v[60:63]
	v_mfma_f32_16x16x32_bf16 v[52:55], v[164:167], v[190:193], v[52:55]
	v_mfma_f32_16x16x32_bf16 v[44:47], v[156:159], v[198:201], v[44:47]
	v_mfma_f32_16x16x32_bf16 v[36:39], v[164:167], v[198:201], v[36:39]
	v_mfma_f32_16x16x32_bf16 v[28:31], v[156:159], v[206:209], v[28:31]
	v_mfma_f32_16x16x32_bf16 v[20:23], v[164:167], v[206:209], v[20:23]
	v_mfma_f32_16x16x32_bf16 v[12:15], v[156:159], v[214:217], v[12:15]
	v_mfma_f32_16x16x32_bf16 v[4:7], v[164:167], v[214:217], v[4:7]
	s_setprio 0
	s_setprio 1
	v_mfma_f32_16x16x32_bf16 v[56:59], v[168:171], v[186:189], v[56:59]
	v_mfma_f32_16x16x32_bf16 v[48:51], v[178:181], v[186:189], v[48:51]
	v_mfma_f32_16x16x32_bf16 v[40:43], v[168:171], v[194:197], v[40:43]
	v_mfma_f32_16x16x32_bf16 v[32:35], v[178:181], v[194:197], v[32:35]
	v_mfma_f32_16x16x32_bf16 v[24:27], v[168:171], v[202:205], v[24:27]
	v_mfma_f32_16x16x32_bf16 v[16:19], v[178:181], v[202:205], v[16:19]
	v_mfma_f32_16x16x32_bf16 v[8:11], v[168:171], v[210:213], v[8:11]
	v_mfma_f32_16x16x32_bf16 v[0:3], v[178:181], v[210:213], v[0:3]
	v_mfma_f32_16x16x32_bf16 v[56:59], v[172:175], v[190:193], v[56:59]
	v_mfma_f32_16x16x32_bf16 v[48:51], v[182:185], v[190:193], v[48:51]
	v_mfma_f32_16x16x32_bf16 v[40:43], v[172:175], v[198:201], v[40:43]
	v_mfma_f32_16x16x32_bf16 v[32:35], v[182:185], v[198:201], v[32:35]
	v_mfma_f32_16x16x32_bf16 v[24:27], v[172:175], v[206:209], v[24:27]
	v_mfma_f32_16x16x32_bf16 v[16:19], v[182:185], v[206:209], v[16:19]
	s_setprio 2
	s_barrier
	v_mfma_f32_16x16x32_bf16 v[8:11], v[172:175], v[214:217], v[8:11]
	v_mfma_f32_16x16x32_bf16 v[0:3], v[182:185], v[214:217], v[0:3]
	s_setprio 0
	s_add_i32 s60, s60, 2
	s_add_u32 s34, s34, 0x100
	s_addc_u32 s35, s35, 0
	s_add_u32 s7, s7, 0x100
	s_addc_u32 s59, s59, 0
	s_cmp_gt_u32 s60, 29
	s_cbranch_scc0 .LBB0_119
	s_and_b64 vcc, exec, s[18:19]
	s_cbranch_vccz .LBB0_122
	s_barrier

; #define PG8_STAGE(bufoff, gbase, voff) do { _Pragma("unroll") for (int _i = 0; _i < 2; ++_i) \
;         __builtin_amdgcn_global_load_lds((const unsigned*)((const char*)(gbase) + (voff)[_i]), (LAS unsigned*)(lds + (bufoff) + ldsw + _i * 8192), 16, 0, 0); } while (0)
; #define PG8_LDA(dst, b, h) do { _Pragma("unroll") for (int m = 0; m < 4; ++m) _Pragma("unroll") for (int k = 0; k < 2; ++k) dst[m][k] = *(const LAS bf16x8*)(lds + PG8_SA(b, h) + aoff + m * 2048 + k * 1024); } while (0)
; #define PG8_LDB(dst, b, h) do { _Pragma("unroll") for (int n = 0; n < 2; ++n) _Pragma("unroll") for (int k = 0; k < 2; ++k) dst[n][k] = *(const LAS bf16x8*)(lds + PG8_SB(b, h) + boff + n * 2048 + k * 1024); } while (0)
; #define PG8_MMA(ai, bj, At, Bt) do { __builtin_amdgcn_s_setprio(1); _Pragma("unroll") for (int m = 0; m < 4; ++m) _Pragma("unroll") for (int n = 0; n < 2; ++n) _Pragma("unroll") for (int k = 0; k < 2; ++k) \
;         acc[ai][bj][m][n] = __builtin_amdgcn_mfma_f32_16x16x32_bf16(Bt[n][k], At[m][k], acc[ai][bj][m][n], 0, 0, 0); __builtin_amdgcn_s_setprio(0); } while (0)
; #define PG8_WAIT_V(n) asm volatile("s_waitcnt vmcnt(" #n ")" ::: "memory")
; #define PG8_WAIT_L(n) asm volatile("s_waitcnt lgkmcnt(" #n ")" ::: "memory")
; #define PG8_BAR __builtin_amdgcn_s_barrier()
; #define PG8_SCHED __builtin_amdgcn_sched_barrier(0)
; template <class Epi, class Sched, bool ALIGN_EPI = true, bool SP2 = true>
; __device__ __forceinline__ void gemm_phase(LAS unsigned char* lds, const bf16_t* Ag, const bf16_t* Btg, const int K, const int lda, const int ldb, const Sched& S, const Epi& E) {
;     ...
;             const bool last = (t == nt - 2);
;             const char* a1 = cA + (size_t)(t + 1) * kstep;
;             const char* a2 = last ? nA : cA + (size_t)(t + 2) * kstep; const char* b2 = last ? nB : cB + (size_t)(t + 2) * kstep;
;             const char* a3 = a2 + kstep; const char* b3 = b2 + kstep;
;             if constexpr (SP2) {
;             PG8_LDB(B0, 0, 0); PG8_LDB(B1, 0, 1); PG8_SCHED; PG8_LDA(At, 0, 0); PG8_STAGE(PG8_SA(1, 1), a1 + hstepA, voffA);
;             PG8_WAIT_V(8); PG8_WAIT_L(0); PG8_BAR; PG8_MMA(0, 0, At, B0); PG8_MMA(0, 1, At, B1); PG8_BAR; PG8_SCHED;
;             PG8_LDA(At, 0, 1); PG8_STAGE(PG8_SB(0, 0), b2, voffB); PG8_STAGE(PG8_SB(0, 1), b2 + hstepB, voffB); PG8_STAGE(PG8_SA(0, 0), a2, voffA);
.LBB0_199:
	ds_read_b128 v[146:149], v151
	ds_read_b128 v[154:157], v151 offset:1024
	ds_read_b128 v[158:161], v151 offset:2048
	ds_read_b128 v[162:165], v151 offset:3072
	ds_read_b128 v[166:169], v152
	ds_read_b128 v[170:173], v152 offset:1024
	ds_read_b128 v[178:181], v152 offset:2048
	ds_read_b128 v[182:185], v152 offset:3072
	s_add_u32 s1, s84, 0xffea0080
	s_addc_u32 s10, s85, -1
	s_cmpk_eq_i32 s0, 0x54
	s_cselect_b32 s71, vcc_lo, s10
	s_cselect_b32 s70, vcc_hi, s1
	s_cselect_b32 s67, s6, s73
	s_cselect_b32 s66, s7, s72
	v_lshl_add_u64 v[174:175], s[84:85], 0, v[138:139]
	s_add_i32 m0, s40, 0xc000
	ds_read_b128 v[186:189], v153
	ds_read_b128 v[190:193], v153 offset:1024
	ds_read_b128 v[194:197], v153 offset:2048
	ds_read_b128 v[198:201], v153 offset:3072
	ds_read_b128 v[202:205], v153 offset:4096
	ds_read_b128 v[206:209], v153 offset:5120
	ds_read_b128 v[210:213], v153 offset:6144
	ds_read_b128 v[214:217], v153 offset:7168
	global_load_lds_dwordx4 v[174:175], off
	v_lshl_add_u64 v[174:175], s[84:85], 0, v[140:141]
	s_add_i32 m0, s40, 0xe000
	s_nop 0
	global_load_lds_dwordx4 v[174:175], off
	s_waitcnt vmcnt(8)
	s_waitcnt lgkmcnt(0)
	s_barrier
	s_setprio 1
	s_waitcnt lgkmcnt(0)
	v_mfma_f32_16x16x32_bf16 v[124:127], v[146:149], v[186:189], v[124:127]
	v_mfma_f32_16x16x32_bf16 v[120:123], v[158:161], v[186:189], v[120:123]
	v_mfma_f32_16x16x32_bf16 v[116:119], v[146:149], v[194:197], v[116:119]
	v_mfma_f32_16x16x32_bf16 v[104:107], v[158:161], v[194:197], v[104:107]
	v_mfma_f32_16x16x32_bf16 v[100:103], v[146:149], v[202:205], v[100:103]
	v_mfma_f32_16x16x32_bf16 v[88:91], v[158:161], v[202:205], v[88:91]
	v_mfma_f32_16x16x32_bf16 v[84:87], v[146:149], v[210:213], v[84:87]
	v_mfma_f32_16x16x32_bf16 v[72:75], v[158:161], v[210:213], v[72:75]
	v_mfma_f32_16x16x32_bf16 v[124:127], v[154:157], v[190:193], v[124:127]
	v_mfma_f32_16x16x32_bf16 v[120:123], v[162:165], v[190:193], v[120:123]
	v_mfma_f32_16x16x32_bf16 v[116:119], v[154:157], v[198:201], v[116:119]
	v_mfma_f32_16x16x32_bf16 v[104:107], v[162:165], v[198:201], v[104:107]
	v_mfma_f32_16x16x32_bf16 v[100:103], v[154:157], v[206:209], v[100:103]
	v_mfma_f32_16x16x32_bf16 v[88:91], v[162:165], v[206:209], v[88:91]
	v_mfma_f32_16x16x32_bf16 v[84:87], v[154:157], v[214:217], v[84:87]
	v_mfma_f32_16x16x32_bf16 v[72:75], v[162:165], v[214:217], v[72:75]
	s_setprio 0
	s_setprio 1
	v_mfma_f32_16x16x32_bf16 v[112:115], v[166:169], v[186:189], v[112:115]
	v_mfma_f32_16x16x32_bf16 v[108:111], v[178:181], v[186:189], v[108:111]
	v_mfma_f32_16x16x32_bf16 v[96:99], v[166:169], v[194:197], v[96:99]
	v_mfma_f32_16x16x32_bf16 v[92:95], v[178:181], v[194:197], v[92:95]
	v_mfma_f32_16x16x32_bf16 v[80:83], v[166:169], v[202:205], v[80:83]
	v_mfma_f32_16x16x32_bf16 v[76:79], v[178:181], v[202:205], v[76:79]
	v_mfma_f32_16x16x32_bf16 v[68:71], v[166:169], v[210:213], v[68:71]
	v_mfma_f32_16x16x32_bf16 v[64:67], v[178:181], v[210:213], v[64:67]
	v_mfma_f32_16x16x32_bf16 v[112:115], v[170:173], v[190:193], v[112:115]
	v_mfma_f32_16x16x32_bf16 v[108:111], v[182:185], v[190:193], v[108:111]
	v_mfma_f32_16x16x32_bf16 v[96:99], v[170:173], v[198:201], v[96:99]
	v_mfma_f32_16x16x32_bf16 v[92:95], v[182:185], v[198:201], v[92:95]
	v_mfma_f32_16x16x32_bf16 v[80:83], v[170:173], v[206:209], v[80:83]
	v_mfma_f32_16x16x32_bf16 v[76:79], v[182:185], v[206:209], v[76:79]
	s_setprio 2
	s_barrier
	v_mfma_f32_16x16x32_bf16 v[68:71], v[170:173], v[214:217], v[68:71]
	v_mfma_f32_16x16x32_bf16 v[64:67], v[182:185], v[214:217], v[64:67]
	s_setprio 0
	s_add_i32 s1, s79, s37
	v_lshl_add_u64 v[174:175], s[66:67], 0, v[130:131]
	s_mov_b32 m0, s1
	ds_read_b128 v[186:189], v153 offset:16384
	ds_read_b128 v[190:193], v153 offset:17408
	ds_read_b128 v[194:197], v153 offset:18432
	ds_read_b128 v[198:201], v153 offset:19456
	ds_read_b128 v[202:205], v153 offset:20480
	ds_read_b128 v[206:209], v153 offset:21504
	ds_read_b128 v[210:213], v153 offset:22528
	ds_read_b128 v[214:217], v153 offset:23552
	global_load_lds_dwordx4 v[174:175], off
	s_add_i32 m0, s1, 0x2000
	s_add_u32 s10, s66, 0x160000
	v_lshl_add_u64 v[218:219], s[66:67], 0, v[134:135]
	s_addc_u32 s11, s67, 0
	s_add_i32 s1, s82, s37
	global_load_lds_dwordx4 v[218:219], off
	v_lshl_add_u64 v[220:221], s[10:11], 0, v[130:131]
	s_mov_b32 m0, s1
	v_lshl_add_u64 v[222:223], s[70:71], 0, v[132:133]
	global_load_lds_dwordx4 v[220:221], off
	v_lshl_add_u64 v[220:221], s[10:11], 0, v[134:135]
	s_add_i32 m0, s1, 0x2000
	s_nop 0
	global_load_lds_dwordx4 v[220:221], off
	v_lshl_add_u64 v[220:221], s[70:71], 0, v[128:129]
	s_mov_b32 m0, s40
	s_nop 0
	global_load_lds_dwordx4 v[220:221], off
	s_mov_b32 m0, s41
	s_nop 0
	global_load_lds_dwordx4 v[222:223], off
	s_waitcnt vmcnt(8)
	s_waitcnt lgkmcnt(0)
	s_barrier
; #define PG8_STAGE(bufoff, gbase, voff) do { _Pragma("unroll") for (int _i = 0; _i < 2; ++_i) \
;         __builtin_amdgcn_global_load_lds((const unsigned*)((const char*)(gbase) + (voff)[_i]), (LAS unsigned*)(lds + (bufoff) + ldsw + _i * 8192), 16, 0, 0); } while (0)
; #define PG8_LDA(dst, b, h) do { _Pragma("unroll") for (int m = 0; m < 4; ++m) _Pragma("unroll") for (int k = 0; k < 2; ++k) dst[m][k] = *(const LAS bf16x8*)(lds + PG8_SA(b, h) + aoff + m * 2048 + k * 1024); } while (0)
; #define PG8_LDB(dst, b, h) do { _Pragma("unroll") for (int n = 0; n < 2; ++n) _Pragma("unroll") for (int k = 0; k < 2; ++k) dst[n][k] = *(const LAS bf16x8*)(lds + PG8_SB(b, h) + boff + n * 2048 + k * 1024); } while (0)
; #define PG8_MMA(ai, bj, At, Bt) do { __builtin_amdgcn_s_setprio(1); _Pragma("unroll") for (int m = 0; m < 4; ++m) _Pragma("unroll") for (int n = 0; n < 2; ++n) _Pragma("unroll") for (int k = 0; k < 2; ++k) \
;         acc[ai][bj][m][n] = __builtin_amdgcn_mfma_f32_16x16x32_bf16(Bt[n][k], At[m][k], acc[ai][bj][m][n], 0, 0, 0); __builtin_amdgcn_s_setprio(0); } while (0)
; #define PG8_WAIT_V(n) asm volatile("s_waitcnt vmcnt(" #n ")" ::: "memory")
; #define PG8_WAIT_L(n) asm volatile("s_waitcnt lgkmcnt(" #n ")" ::: "memory")
; #define PG8_BAR __builtin_amdgcn_s_barrier()
; #define PG8_SCHED __builtin_amdgcn_sched_barrier(0)
; template <class Epi, class Sched, bool ALIGN_EPI = true, bool SP2 = true>
; __device__ __forceinline__ void gemm_phase(LAS unsigned char* lds, const bf16_t* Ag, const bf16_t* Btg, const int K, const int lda, const int ldb, const Sched& S, const Epi& E) {
;     ...
;             PG8_WAIT_V(8); PG8_WAIT_L(0); PG8_BAR; PG8_MMA(1, 0, At, B0); PG8_MMA(1, 1, At, B1); PG8_BAR; PG8_SCHED;
;             PG8_LDB(B0, 1, 0); PG8_LDB(B1, 1, 1); PG8_SCHED; PG8_LDA(At, 1, 0); PG8_STAGE(PG8_SA(0, 1), a2 + hstepA, voffA);
;             PG8_WAIT_V(8); PG8_WAIT_L(0); PG8_BAR; PG8_MMA(0, 0, At, B0); PG8_MMA(0, 1, At, B1); PG8_BAR; PG8_SCHED;
	s_setprio 1
	s_waitcnt lgkmcnt(0)
	v_mfma_f32_16x16x32_bf16 v[60:63], v[146:149], v[186:189], v[60:63]
	v_mfma_f32_16x16x32_bf16 v[56:59], v[158:161], v[186:189], v[56:59]
	v_mfma_f32_16x16x32_bf16 v[52:55], v[146:149], v[194:197], v[52:55]
	v_mfma_f32_16x16x32_bf16 v[40:43], v[158:161], v[194:197], v[40:43]
	v_mfma_f32_16x16x32_bf16 v[36:39], v[146:149], v[202:205], v[36:39]
	v_mfma_f32_16x16x32_bf16 v[24:27], v[158:161], v[202:205], v[24:27]
	v_mfma_f32_16x16x32_bf16 v[16:19], v[146:149], v[210:213], v[16:19]
	v_mfma_f32_16x16x32_bf16 v[8:11], v[158:161], v[210:213], v[8:11]
	v_mfma_f32_16x16x32_bf16 v[60:63], v[154:157], v[190:193], v[60:63]
	v_mfma_f32_16x16x32_bf16 v[56:59], v[162:165], v[190:193], v[56:59]
	v_mfma_f32_16x16x32_bf16 v[52:55], v[154:157], v[198:201], v[52:55]
	v_mfma_f32_16x16x32_bf16 v[40:43], v[162:165], v[198:201], v[40:43]
	v_mfma_f32_16x16x32_bf16 v[36:39], v[154:157], v[206:209], v[36:39]
	v_mfma_f32_16x16x32_bf16 v[24:27], v[162:165], v[206:209], v[24:27]
	v_mfma_f32_16x16x32_bf16 v[16:19], v[154:157], v[214:217], v[16:19]
	v_mfma_f32_16x16x32_bf16 v[8:11], v[162:165], v[214:217], v[8:11]
	s_setprio 0
	s_setprio 1
	v_mfma_f32_16x16x32_bf16 v[48:51], v[166:169], v[186:189], v[48:51]
	v_mfma_f32_16x16x32_bf16 v[44:47], v[178:181], v[186:189], v[44:47]
	v_mfma_f32_16x16x32_bf16 v[32:35], v[166:169], v[194:197], v[32:35]
	v_mfma_f32_16x16x32_bf16 v[28:31], v[178:181], v[194:197], v[28:31]
	v_mfma_f32_16x16x32_bf16 v[20:23], v[166:169], v[202:205], v[20:23]
	v_mfma_f32_16x16x32_bf16 v[12:15], v[178:181], v[202:205], v[12:15]
	v_mfma_f32_16x16x32_bf16 v[4:7], v[166:169], v[210:213], v[4:7]
	v_mfma_f32_16x16x32_bf16 v[0:3], v[178:181], v[210:213], v[0:3]
	v_mfma_f32_16x16x32_bf16 v[48:51], v[170:173], v[190:193], v[48:51]
	v_mfma_f32_16x16x32_bf16 v[44:47], v[182:185], v[190:193], v[44:47]
	v_mfma_f32_16x16x32_bf16 v[32:35], v[170:173], v[198:201], v[32:35]
	v_mfma_f32_16x16x32_bf16 v[28:31], v[182:185], v[198:201], v[28:31]
	v_mfma_f32_16x16x32_bf16 v[20:23], v[170:173], v[206:209], v[20:23]
	v_mfma_f32_16x16x32_bf16 v[12:15], v[182:185], v[206:209], v[12:15]
	s_setprio 2
	s_barrier
	v_mfma_f32_16x16x32_bf16 v[4:7], v[170:173], v[214:217], v[4:7]
	v_mfma_f32_16x16x32_bf16 v[0:3], v[182:185], v[214:217], v[0:3]
	s_setprio 0
	s_add_i32 s1, 0, 0x18000
	s_add_i32 s12, 0, 0x1c000
	v_add_u32_e32 v162, s1, v150
	v_add_u32_e32 v182, s12, v150
	ds_read_b128 v[146:149], v162
	ds_read_b128 v[154:157], v162 offset:1024
	ds_read_b128 v[158:161], v162 offset:2048
	ds_read_b128 v[162:165], v162 offset:3072
	ds_read_b128 v[166:169], v182
	ds_read_b128 v[170:173], v182 offset:1024
	ds_read_b128 v[178:181], v182 offset:2048
	ds_read_b128 v[182:185], v182 offset:3072
	s_add_u32 s10, s70, 0x160000
	s_addc_u32 s11, s71, 0
	s_mov_b32 m0, s46
	v_lshl_add_u64 v[224:225], s[10:11], 0, v[128:129]
	ds_read_b128 v[186:189], v153 offset:32768
	ds_read_b128 v[190:193], v153 offset:33792
	ds_read_b128 v[194:197], v153 offset:34816
	ds_read_b128 v[198:201], v153 offset:35840
	ds_read_b128 v[202:205], v153 offset:36864
	ds_read_b128 v[206:209], v153 offset:37888
	ds_read_b128 v[210:213], v153 offset:38912
	ds_read_b128 v[214:217], v153 offset:39936
	global_load_lds_dwordx4 v[224:225], off
	v_lshl_add_u64 v[224:225], s[10:11], 0, v[132:133]
	s_mov_b32 m0, s47
	s_nop 0
	global_load_lds_dwordx4 v[224:225], off
	s_waitcnt vmcnt(8)
	s_waitcnt lgkmcnt(0)
	s_barrier
	s_setprio 1
	s_waitcnt lgkmcnt(0)
	v_mfma_f32_16x16x32_bf16 v[124:127], v[146:149], v[186:189], v[124:127]
	v_mfma_f32_16x16x32_bf16 v[120:123], v[158:161], v[186:189], v[120:123]
	v_mfma_f32_16x16x32_bf16 v[116:119], v[146:149], v[194:197], v[116:119]
	v_mfma_f32_16x16x32_bf16 v[104:107], v[158:161], v[194:197], v[104:107]
	v_mfma_f32_16x16x32_bf16 v[100:103], v[146:149], v[202:205], v[100:103]
	v_mfma_f32_16x16x32_bf16 v[88:91], v[158:161], v[202:205], v[88:91]
	v_mfma_f32_16x16x32_bf16 v[84:87], v[146:149], v[210:213], v[84:87]
	v_mfma_f32_16x16x32_bf16 v[72:75], v[158:161], v[210:213], v[72:75]
	v_mfma_f32_16x16x32_bf16 v[124:127], v[154:157], v[190:193], v[124:127]
	v_mfma_f32_16x16x32_bf16 v[120:123], v[162:165], v[190:193], v[120:123]
	v_mfma_f32_16x16x32_bf16 v[116:119], v[154:157], v[198:201], v[116:119]
	v_mfma_f32_16x16x32_bf16 v[104:107], v[162:165], v[198:201], v[104:107]
	v_mfma_f32_16x16x32_bf16 v[100:103], v[154:157], v[206:209], v[100:103]
	v_mfma_f32_16x16x32_bf16 v[88:91], v[162:165], v[206:209], v[88:91]
	v_mfma_f32_16x16x32_bf16 v[84:87], v[154:157], v[214:217], v[84:87]
	v_mfma_f32_16x16x32_bf16 v[72:75], v[162:165], v[214:217], v[72:75]
	s_setprio 0
	s_setprio 1
	v_mfma_f32_16x16x32_bf16 v[112:115], v[166:169], v[186:189], v[112:115]
	v_mfma_f32_16x16x32_bf16 v[108:111], v[178:181], v[186:189], v[108:111]
	v_mfma_f32_16x16x32_bf16 v[96:99], v[166:169], v[194:197], v[96:99]
	v_mfma_f32_16x16x32_bf16 v[92:95], v[178:181], v[194:197], v[92:95]
	v_mfma_f32_16x16x32_bf16 v[80:83], v[166:169], v[202:205], v[80:83]
	v_mfma_f32_16x16x32_bf16 v[76:79], v[178:181], v[202:205], v[76:79]
	v_mfma_f32_16x16x32_bf16 v[68:71], v[166:169], v[210:213], v[68:71]
	v_mfma_f32_16x16x32_bf16 v[64:67], v[178:181], v[210:213], v[64:67]
	v_mfma_f32_16x16x32_bf16 v[112:115], v[170:173], v[190:193], v[112:115]
	v_mfma_f32_16x16x32_bf16 v[108:111], v[182:185], v[190:193], v[108:111]
	v_mfma_f32_16x16x32_bf16 v[96:99], v[170:173], v[198:201], v[96:99]
	v_mfma_f32_16x16x32_bf16 v[92:95], v[182:185], v[198:201], v[92:95]
	v_mfma_f32_16x16x32_bf16 v[80:83], v[170:173], v[206:209], v[80:83]
	v_mfma_f32_16x16x32_bf16 v[76:79], v[182:185], v[206:209], v[76:79]
	s_setprio 2
	s_barrier
; #define PG8_STAGE(bufoff, gbase, voff) do { _Pragma("unroll") for (int _i = 0; _i < 2; ++_i) \
;         __builtin_amdgcn_global_load_lds((const unsigned*)((const char*)(gbase) + (voff)[_i]), (LAS unsigned*)(lds + (bufoff) + ldsw + _i * 8192), 16, 0, 0); } while (0)
; #define PG8_LDA(dst, b, h) do { _Pragma("unroll") for (int m = 0; m < 4; ++m) _Pragma("unroll") for (int k = 0; k < 2; ++k) dst[m][k] = *(const LAS bf16x8*)(lds + PG8_SA(b, h) + aoff + m * 2048 + k * 1024); } while (0)
; #define PG8_MMA(ai, bj, At, Bt) do { __builtin_amdgcn_s_setprio(1); _Pragma("unroll") for (int m = 0; m < 4; ++m) _Pragma("unroll") for (int n = 0; n < 2; ++n) _Pragma("unroll") for (int k = 0; k < 2; ++k) \
;         acc[ai][bj][m][n] = __builtin_amdgcn_mfma_f32_16x16x32_bf16(Bt[n][k], At[m][k], acc[ai][bj][m][n], 0, 0, 0); __builtin_amdgcn_s_setprio(0); } while (0)
; #define PG8_WAIT_V(n) asm volatile("s_waitcnt vmcnt(" #n ")" ::: "memory")
; #define PG8_WAIT_L(n) asm volatile("s_waitcnt lgkmcnt(" #n ")" ::: "memory")
; #define PG8_BAR __builtin_amdgcn_s_barrier()
; #define PG8_SCHED __builtin_amdgcn_sched_barrier(0)
; template <class Epi, class Sched, bool ALIGN_EPI = true, bool SP2 = true>
; __device__ __forceinline__ void gemm_phase(LAS unsigned char* lds, const bf16_t* Ag, const bf16_t* Btg, const int K, const int lda, const int ldb, const Sched& S, const Epi& E) {
;     ...
;             PG8_LDA(At, 1, 1); PG8_STAGE(PG8_SB(1, 0), b3, voffB); PG8_STAGE(PG8_SB(1, 1), b3 + hstepB, voffB); PG8_STAGE(PG8_SA(1, 0), a3, voffA);
;             PG8_WAIT_V(8); PG8_WAIT_L(0); PG8_BAR; PG8_MMA(1, 0, At, B0); PG8_MMA(1, 1, At, B1); PG8_BAR; PG8_SCHED;
	v_mfma_f32_16x16x32_bf16 v[68:71], v[170:173], v[214:217], v[68:71]
	v_mfma_f32_16x16x32_bf16 v[64:67], v[182:185], v[214:217], v[64:67]
	s_setprio 0
	s_add_i32 s1, s1, s37
	v_lshl_add_u64 v[174:175], v[174:175], 0, s[14:15]
	s_mov_b32 m0, s1
	ds_read_b128 v[186:189], v153 offset:49152
	ds_read_b128 v[190:193], v153 offset:50176
	ds_read_b128 v[194:197], v153 offset:51200
	ds_read_b128 v[198:201], v153 offset:52224
	ds_read_b128 v[202:205], v153 offset:53248
	ds_read_b128 v[206:209], v153 offset:54272
	ds_read_b128 v[210:213], v153 offset:55296
	ds_read_b128 v[214:217], v153 offset:56320
	global_load_lds_dwordx4 v[174:175], off
	s_add_i32 m0, s1, 0x2000
	s_add_u32 s10, s66, 0x160080
	v_lshl_add_u64 v[174:175], v[218:219], 0, s[14:15]
	s_addc_u32 s11, s67, 0
	s_add_i32 s1, s12, s37
	global_load_lds_dwordx4 v[174:175], off
	v_lshl_add_u64 v[174:175], s[10:11], 0, v[130:131]
	s_mov_b32 m0, s1
	s_nop 0
	global_load_lds_dwordx4 v[174:175], off
	v_lshl_add_u64 v[174:175], s[10:11], 0, v[134:135]
	s_add_i32 m0, s1, 0x2000
	s_nop 0
	global_load_lds_dwordx4 v[174:175], off
	v_lshl_add_u64 v[174:175], v[220:221], 0, s[14:15]
	s_mov_b32 m0, s75
	s_nop 0
	global_load_lds_dwordx4 v[174:175], off
	v_lshl_add_u64 v[174:175], v[222:223], 0, s[14:15]
	s_mov_b32 m0, s76
	s_nop 0
	global_load_lds_dwordx4 v[174:175], off
	s_waitcnt vmcnt(8)
	s_waitcnt lgkmcnt(0)
	s_barrier
	s_setprio 1
	s_waitcnt lgkmcnt(0)
	v_mfma_f32_16x16x32_bf16 v[60:63], v[146:149], v[186:189], v[60:63]
	v_mfma_f32_16x16x32_bf16 v[56:59], v[158:161], v[186:189], v[56:59]
	v_mfma_f32_16x16x32_bf16 v[52:55], v[146:149], v[194:197], v[52:55]
	v_mfma_f32_16x16x32_bf16 v[40:43], v[158:161], v[194:197], v[40:43]
	v_mfma_f32_16x16x32_bf16 v[36:39], v[146:149], v[202:205], v[36:39]
	v_mfma_f32_16x16x32_bf16 v[24:27], v[158:161], v[202:205], v[24:27]
	v_mfma_f32_16x16x32_bf16 v[16:19], v[146:149], v[210:213], v[16:19]
	v_mfma_f32_16x16x32_bf16 v[8:11], v[158:161], v[210:213], v[8:11]
	v_mfma_f32_16x16x32_bf16 v[60:63], v[154:157], v[190:193], v[60:63]
	v_mfma_f32_16x16x32_bf16 v[56:59], v[162:165], v[190:193], v[56:59]
	v_mfma_f32_16x16x32_bf16 v[52:55], v[154:157], v[198:201], v[52:55]
	v_mfma_f32_16x16x32_bf16 v[40:43], v[162:165], v[198:201], v[40:43]
	v_mfma_f32_16x16x32_bf16 v[36:39], v[154:157], v[206:209], v[36:39]
	v_mfma_f32_16x16x32_bf16 v[24:27], v[162:165], v[206:209], v[24:27]
	v_mfma_f32_16x16x32_bf16 v[16:19], v[154:157], v[214:217], v[16:19]
	v_mfma_f32_16x16x32_bf16 v[8:11], v[162:165], v[214:217], v[8:11]
	s_setprio 0
	s_setprio 1
	v_mfma_f32_16x16x32_bf16 v[48:51], v[166:169], v[186:189], v[48:51]
	v_mfma_f32_16x16x32_bf16 v[44:47], v[178:181], v[186:189], v[44:47]
	v_mfma_f32_16x16x32_bf16 v[32:35], v[166:169], v[194:197], v[32:35]
	v_mfma_f32_16x16x32_bf16 v[28:31], v[178:181], v[194:197], v[28:31]
	v_mfma_f32_16x16x32_bf16 v[20:23], v[166:169], v[202:205], v[20:23]
	v_mfma_f32_16x16x32_bf16 v[12:15], v[178:181], v[202:205], v[12:15]
	v_mfma_f32_16x16x32_bf16 v[4:7], v[166:169], v[210:213], v[4:7]
	v_mfma_f32_16x16x32_bf16 v[0:3], v[178:181], v[210:213], v[0:3]
	v_mfma_f32_16x16x32_bf16 v[48:51], v[170:173], v[190:193], v[48:51]
	v_mfma_f32_16x16x32_bf16 v[44:47], v[182:185], v[190:193], v[44:47]
	v_mfma_f32_16x16x32_bf16 v[32:35], v[170:173], v[198:201], v[32:35]
	v_mfma_f32_16x16x32_bf16 v[28:31], v[182:185], v[198:201], v[28:31]
	v_mfma_f32_16x16x32_bf16 v[20:23], v[170:173], v[206:209], v[20:23]
	v_mfma_f32_16x16x32_bf16 v[12:15], v[182:185], v[206:209], v[12:15]
	s_setprio 2
	s_barrier
	v_mfma_f32_16x16x32_bf16 v[4:7], v[170:173], v[214:217], v[4:7]
	v_mfma_f32_16x16x32_bf16 v[0:3], v[182:185], v[214:217], v[0:3]
	s_setprio 0
	s_add_i32 s0, s0, 2
	s_add_u32 s84, s84, 0x100
	s_addc_u32 s85, s85, 0
	s_add_u32 s72, s72, 0x100
	s_addc_u32 s73, s73, 0
	s_cmpk_gt_u32 s0, 0x55
	s_cbranch_scc0 .LBB0_199
	s_and_b64 vcc, exec, s[48:49]
	s_cbranch_vccz .LBB0_202
	s_barrier

; #define PG8_STAGE(bufoff, gbase, voff) do { _Pragma("unroll") for (int _i = 0; _i < 2; ++_i) \
;         __builtin_amdgcn_global_load_lds((const unsigned*)((const char*)(gbase) + (voff)[_i]), (LAS unsigned*)(lds + (bufoff) + ldsw + _i * 8192), 16, 0, 0); } while (0)
; #define PG8_LDA(dst, b, h) do { _Pragma("unroll") for (int m = 0; m < 4; ++m) _Pragma("unroll") for (int k = 0; k < 2; ++k) dst[m][k] = *(const LAS bf16x8*)(lds + PG8_SA(b, h) + aoff + m * 2048 + k * 1024); } while (0)
; #define PG8_LDB(dst, b, h) do { _Pragma("unroll") for (int n = 0; n < 2; ++n) _Pragma("unroll") for (int k = 0; k < 2; ++k) dst[n][k] = *(const LAS bf16x8*)(lds + PG8_SB(b, h) + boff + n * 2048 + k * 1024); } while (0)
; #define PG8_MMA(ai, bj, At, Bt) do { __builtin_amdgcn_s_setprio(1); _Pragma("unroll") for (int m = 0; m < 4; ++m) _Pragma("unroll") for (int n = 0; n < 2; ++n) _Pragma("unroll") for (int k = 0; k < 2; ++k) \
;         acc[ai][bj][m][n] = __builtin_amdgcn_mfma_f32_16x16x32_bf16(Bt[n][k], At[m][k], acc[ai][bj][m][n], 0, 0, 0); __builtin_amdgcn_s_setprio(0); } while (0)
; #define PG8_WAIT_V(n) asm volatile("s_waitcnt vmcnt(" #n ")" ::: "memory")
; #define PG8_WAIT_L(n) asm volatile("s_waitcnt lgkmcnt(" #n ")" ::: "memory")
; #define PG8_BAR __builtin_amdgcn_s_barrier()
; #define PG8_SCHED __builtin_amdgcn_sched_barrier(0)
; template <class Epi, class Sched, bool ALIGN_EPI = true, bool SP2 = true>
; __device__ __forceinline__ void gemm_phase(LAS unsigned char* lds, const bf16_t* Ag, const bf16_t* Btg, const int K, const int lda, const int ldb, const Sched& S, const Epi& E) {
;     ...
;             const bool last = (t == nt - 2);
;             const char* a1 = cA + (size_t)(t + 1) * kstep;
;             const char* a2 = last ? nA : cA + (size_t)(t + 2) * kstep; const char* b2 = last ? nB : cB + (size_t)(t + 2) * kstep;
;             const char* a3 = a2 + kstep; const char* b3 = b2 + kstep;
;             if constexpr (SP2) {
;             PG8_LDB(B0, 0, 0); PG8_LDB(B1, 0, 1); PG8_SCHED; PG8_LDA(At, 0, 0); PG8_STAGE(PG8_SA(1, 1), a1 + hstepA, voffA);
;             PG8_WAIT_V(8); PG8_WAIT_L(0); PG8_BAR; PG8_MMA(0, 0, At, B0); PG8_MMA(0, 1, At, B1); PG8_BAR; PG8_SCHED;
;             PG8_LDA(At, 0, 1); PG8_STAGE(PG8_SB(0, 0), b2, voffB); PG8_STAGE(PG8_SB(0, 1), b2 + hstepB, voffB); PG8_STAGE(PG8_SA(0, 0), a2, voffA);
.LBB0_278:
	ds_read_b128 v[152:155], v137
	ds_read_b128 v[156:159], v137 offset:1024
	ds_read_b128 v[160:163], v137 offset:2048
	ds_read_b128 v[164:167], v137 offset:3072
	ds_read_b128 v[168:171], v150
	ds_read_b128 v[172:175], v150 offset:1024
	ds_read_b128 v[180:183], v150 offset:2048
	ds_read_b128 v[184:187], v150 offset:3072
	s_add_u32 s34, s30, 0xfff80080
	s_addc_u32 s35, s31, -1
	s_cmp_eq_u32 s59, 28
	s_cselect_b32 s39, s55, s35
	s_cselect_b32 s38, s56, s34
	s_cselect_b32 s35, s6, s58
	s_cselect_b32 s34, s7, s57
	v_lshl_add_u64 v[220:221], s[30:31], 0, v[140:141]
	s_add_i32 m0, s33, 0xc000
	ds_read_b128 v[188:191], v151
	ds_read_b128 v[192:195], v151 offset:1024
	ds_read_b128 v[196:199], v151 offset:2048
	ds_read_b128 v[200:203], v151 offset:3072
	ds_read_b128 v[204:207], v151 offset:4096
	ds_read_b128 v[208:211], v151 offset:5120
	ds_read_b128 v[212:215], v151 offset:6144
	ds_read_b128 v[216:219], v151 offset:7168
	global_load_lds_dwordx4 v[220:221], off
	v_lshl_add_u64 v[220:221], s[30:31], 0, v[142:143]
	s_add_i32 m0, s33, 0xe000
	s_nop 0
	global_load_lds_dwordx4 v[220:221], off
	s_waitcnt vmcnt(8)
	s_waitcnt lgkmcnt(0)
	s_barrier
	s_setprio 1
	s_waitcnt lgkmcnt(0)
	v_mfma_f32_16x16x32_bf16 v[124:127], v[152:155], v[188:191], v[124:127]
	v_mfma_f32_16x16x32_bf16 v[120:123], v[160:163], v[188:191], v[120:123]
	v_mfma_f32_16x16x32_bf16 v[116:119], v[152:155], v[196:199], v[116:119]
	v_mfma_f32_16x16x32_bf16 v[112:115], v[160:163], v[196:199], v[112:115]
	v_mfma_f32_16x16x32_bf16 v[100:103], v[152:155], v[204:207], v[100:103]
	v_mfma_f32_16x16x32_bf16 v[96:99], v[160:163], v[204:207], v[96:99]
	v_mfma_f32_16x16x32_bf16 v[84:87], v[152:155], v[212:215], v[84:87]
	v_mfma_f32_16x16x32_bf16 v[80:83], v[160:163], v[212:215], v[80:83]
	v_mfma_f32_16x16x32_bf16 v[124:127], v[156:159], v[192:195], v[124:127]
	v_mfma_f32_16x16x32_bf16 v[120:123], v[164:167], v[192:195], v[120:123]
	v_mfma_f32_16x16x32_bf16 v[116:119], v[156:159], v[200:203], v[116:119]
	v_mfma_f32_16x16x32_bf16 v[112:115], v[164:167], v[200:203], v[112:115]
	v_mfma_f32_16x16x32_bf16 v[100:103], v[156:159], v[208:211], v[100:103]
	v_mfma_f32_16x16x32_bf16 v[96:99], v[164:167], v[208:211], v[96:99]
	v_mfma_f32_16x16x32_bf16 v[84:87], v[156:159], v[216:219], v[84:87]
	v_mfma_f32_16x16x32_bf16 v[80:83], v[164:167], v[216:219], v[80:83]
	s_setprio 0
	s_setprio 1
	v_mfma_f32_16x16x32_bf16 v[108:111], v[168:171], v[188:191], v[108:111]
	v_mfma_f32_16x16x32_bf16 v[104:107], v[180:183], v[188:191], v[104:107]
	v_mfma_f32_16x16x32_bf16 v[92:95], v[168:171], v[196:199], v[92:95]
	v_mfma_f32_16x16x32_bf16 v[88:91], v[180:183], v[196:199], v[88:91]
	v_mfma_f32_16x16x32_bf16 v[76:79], v[168:171], v[204:207], v[76:79]
	v_mfma_f32_16x16x32_bf16 v[72:75], v[180:183], v[204:207], v[72:75]
	v_mfma_f32_16x16x32_bf16 v[68:71], v[168:171], v[212:215], v[68:71]
	v_mfma_f32_16x16x32_bf16 v[64:67], v[180:183], v[212:215], v[64:67]
	v_mfma_f32_16x16x32_bf16 v[108:111], v[172:175], v[192:195], v[108:111]
	v_mfma_f32_16x16x32_bf16 v[104:107], v[184:187], v[192:195], v[104:107]
	v_mfma_f32_16x16x32_bf16 v[92:95], v[172:175], v[200:203], v[92:95]
	v_mfma_f32_16x16x32_bf16 v[88:91], v[184:187], v[200:203], v[88:91]
	v_mfma_f32_16x16x32_bf16 v[76:79], v[172:175], v[208:211], v[76:79]
	v_mfma_f32_16x16x32_bf16 v[72:75], v[184:187], v[208:211], v[72:75]
	s_setprio 2
	s_barrier
	v_mfma_f32_16x16x32_bf16 v[68:71], v[172:175], v[216:219], v[68:71]
	v_mfma_f32_16x16x32_bf16 v[64:67], v[184:187], v[216:219], v[64:67]
	s_setprio 0
	s_add_i32 s60, s0, s9
	v_lshl_add_u64 v[220:221], s[34:35], 0, v[130:131]
	s_mov_b32 m0, s60
	ds_read_b128 v[188:191], v151 offset:16384
	ds_read_b128 v[192:195], v151 offset:17408
	ds_read_b128 v[196:199], v151 offset:18432
	ds_read_b128 v[200:203], v151 offset:19456
	ds_read_b128 v[204:207], v151 offset:20480
	ds_read_b128 v[208:211], v151 offset:21504
	ds_read_b128 v[212:215], v151 offset:22528
	ds_read_b128 v[216:219], v151 offset:23552
	global_load_lds_dwordx4 v[220:221], off
	s_add_i32 m0, s60, 0x2000
	s_add_u32 s60, s34, 0x80000
	v_lshl_add_u64 v[222:223], s[34:35], 0, v[134:135]
	s_addc_u32 s61, s35, 0
	s_add_i32 s62, s54, s9
	global_load_lds_dwordx4 v[222:223], off
	v_lshl_add_u64 v[224:225], s[60:61], 0, v[130:131]
	s_mov_b32 m0, s62
	v_lshl_add_u64 v[226:227], s[38:39], 0, v[132:133]
	global_load_lds_dwordx4 v[224:225], off
	v_lshl_add_u64 v[224:225], s[60:61], 0, v[134:135]
	s_add_i32 m0, s62, 0x2000
	s_nop 0
	global_load_lds_dwordx4 v[224:225], off
	v_lshl_add_u64 v[224:225], s[38:39], 0, v[128:129]
	s_mov_b32 m0, s33
	s_nop 0
	global_load_lds_dwordx4 v[224:225], off
	s_mov_b32 m0, s41
	s_nop 0
	global_load_lds_dwordx4 v[226:227], off
	s_waitcnt vmcnt(8)
	s_waitcnt lgkmcnt(0)
	s_barrier
; #define PG8_STAGE(bufoff, gbase, voff) do { _Pragma("unroll") for (int _i = 0; _i < 2; ++_i) \
;         __builtin_amdgcn_global_load_lds((const unsigned*)((const char*)(gbase) + (voff)[_i]), (LAS unsigned*)(lds + (bufoff) + ldsw + _i * 8192), 16, 0, 0); } while (0)
; #define PG8_LDA(dst, b, h) do { _Pragma("unroll") for (int m = 0; m < 4; ++m) _Pragma("unroll") for (int k = 0; k < 2; ++k) dst[m][k] = *(const LAS bf16x8*)(lds + PG8_SA(b, h) + aoff + m * 2048 + k * 1024); } while (0)
; #define PG8_LDB(dst, b, h) do { _Pragma("unroll") for (int n = 0; n < 2; ++n) _Pragma("unroll") for (int k = 0; k < 2; ++k) dst[n][k] = *(const LAS bf16x8*)(lds + PG8_SB(b, h) + boff + n * 2048 + k * 1024); } while (0)
; #define PG8_MMA(ai, bj, At, Bt) do { __builtin_amdgcn_s_setprio(1); _Pragma("unroll") for (int m = 0; m < 4; ++m) _Pragma("unroll") for (int n = 0; n < 2; ++n) _Pragma("unroll") for (int k = 0; k < 2; ++k) \
;         acc[ai][bj][m][n] = __builtin_amdgcn_mfma_f32_16x16x32_bf16(Bt[n][k], At[m][k], acc[ai][bj][m][n], 0, 0, 0); __builtin_amdgcn_s_setprio(0); } while (0)
; #define PG8_WAIT_V(n) asm volatile("s_waitcnt vmcnt(" #n ")" ::: "memory")
; #define PG8_WAIT_L(n) asm volatile("s_waitcnt lgkmcnt(" #n ")" ::: "memory")
; #define PG8_BAR __builtin_amdgcn_s_barrier()
; #define PG8_SCHED __builtin_amdgcn_sched_barrier(0)
; template <class Epi, class Sched, bool ALIGN_EPI = true, bool SP2 = true>
; __device__ __forceinline__ void gemm_phase(LAS unsigned char* lds, const bf16_t* Ag, const bf16_t* Btg, const int K, const int lda, const int ldb, const Sched& S, const Epi& E) {
;     ...
;             PG8_WAIT_V(8); PG8_WAIT_L(0); PG8_BAR; PG8_MMA(1, 0, At, B0); PG8_MMA(1, 1, At, B1); PG8_BAR; PG8_SCHED;
;             PG8_LDB(B0, 1, 0); PG8_LDB(B1, 1, 1); PG8_SCHED; PG8_LDA(At, 1, 0); PG8_STAGE(PG8_SA(0, 1), a2 + hstepA, voffA);
;             PG8_WAIT_V(8); PG8_WAIT_L(0); PG8_BAR; PG8_MMA(0, 0, At, B0); PG8_MMA(0, 1, At, B1); PG8_BAR; PG8_SCHED;
	s_setprio 1
	s_waitcnt lgkmcnt(0)
	v_mfma_f32_16x16x32_bf16 v[60:63], v[152:155], v[188:191], v[60:63]
	v_mfma_f32_16x16x32_bf16 v[56:59], v[160:163], v[188:191], v[56:59]
	v_mfma_f32_16x16x32_bf16 v[52:55], v[152:155], v[196:199], v[52:55]
	v_mfma_f32_16x16x32_bf16 v[48:51], v[160:163], v[196:199], v[48:51]
	v_mfma_f32_16x16x32_bf16 v[36:39], v[152:155], v[204:207], v[36:39]
	v_mfma_f32_16x16x32_bf16 v[32:35], v[160:163], v[204:207], v[32:35]
	v_mfma_f32_16x16x32_bf16 v[20:23], v[152:155], v[212:215], v[20:23]
	v_mfma_f32_16x16x32_bf16 v[16:19], v[160:163], v[212:215], v[16:19]
	v_mfma_f32_16x16x32_bf16 v[60:63], v[156:159], v[192:195], v[60:63]
	v_mfma_f32_16x16x32_bf16 v[56:59], v[164:167], v[192:195], v[56:59]
	v_mfma_f32_16x16x32_bf16 v[52:55], v[156:159], v[200:203], v[52:55]
	v_mfma_f32_16x16x32_bf16 v[48:51], v[164:167], v[200:203], v[48:51]
	v_mfma_f32_16x16x32_bf16 v[36:39], v[156:159], v[208:211], v[36:39]
	v_mfma_f32_16x16x32_bf16 v[32:35], v[164:167], v[208:211], v[32:35]
	v_mfma_f32_16x16x32_bf16 v[20:23], v[156:159], v[216:219], v[20:23]
	v_mfma_f32_16x16x32_bf16 v[16:19], v[164:167], v[216:219], v[16:19]
	s_setprio 0
	s_setprio 1
	v_mfma_f32_16x16x32_bf16 v[44:47], v[168:171], v[188:191], v[44:47]
	v_mfma_f32_16x16x32_bf16 v[40:43], v[180:183], v[188:191], v[40:43]
	v_mfma_f32_16x16x32_bf16 v[28:31], v[168:171], v[196:199], v[28:31]
	v_mfma_f32_16x16x32_bf16 v[24:27], v[180:183], v[196:199], v[24:27]
	v_mfma_f32_16x16x32_bf16 v[12:15], v[168:171], v[204:207], v[12:15]
	v_mfma_f32_16x16x32_bf16 v[8:11], v[180:183], v[204:207], v[8:11]
	v_mfma_f32_16x16x32_bf16 v[4:7], v[168:171], v[212:215], v[4:7]
	v_mfma_f32_16x16x32_bf16 v[0:3], v[180:183], v[212:215], v[0:3]
	v_mfma_f32_16x16x32_bf16 v[44:47], v[172:175], v[192:195], v[44:47]
	v_mfma_f32_16x16x32_bf16 v[40:43], v[184:187], v[192:195], v[40:43]
	v_mfma_f32_16x16x32_bf16 v[28:31], v[172:175], v[200:203], v[28:31]
	v_mfma_f32_16x16x32_bf16 v[24:27], v[184:187], v[200:203], v[24:27]
	v_mfma_f32_16x16x32_bf16 v[12:15], v[172:175], v[208:211], v[12:15]
	v_mfma_f32_16x16x32_bf16 v[8:11], v[184:187], v[208:211], v[8:11]
	s_setprio 2
	s_barrier
	v_mfma_f32_16x16x32_bf16 v[4:7], v[172:175], v[216:219], v[4:7]
	v_mfma_f32_16x16x32_bf16 v[0:3], v[184:187], v[216:219], v[0:3]
	s_setprio 0
	s_add_i32 s60, 0, 0x18000
	s_add_i32 s61, 0, 0x1c000
	v_add_u32_e32 v164, s60, v149
	v_add_u32_e32 v184, s61, v149
	ds_read_b128 v[152:155], v164
	ds_read_b128 v[156:159], v164 offset:1024
	ds_read_b128 v[160:163], v164 offset:2048
	ds_read_b128 v[164:167], v164 offset:3072
	ds_read_b128 v[168:171], v184
	ds_read_b128 v[172:175], v184 offset:1024
	ds_read_b128 v[180:183], v184 offset:2048
	ds_read_b128 v[184:187], v184 offset:3072
	s_add_u32 s38, s38, 0x80000
	s_addc_u32 s39, s39, 0
	s_mov_b32 m0, s46
	v_lshl_add_u64 v[228:229], s[38:39], 0, v[128:129]
	ds_read_b128 v[188:191], v151 offset:32768
	ds_read_b128 v[192:195], v151 offset:33792
	ds_read_b128 v[196:199], v151 offset:34816
	ds_read_b128 v[200:203], v151 offset:35840
	ds_read_b128 v[204:207], v151 offset:36864
	ds_read_b128 v[208:211], v151 offset:37888
	ds_read_b128 v[212:215], v151 offset:38912
	ds_read_b128 v[216:219], v151 offset:39936
	global_load_lds_dwordx4 v[228:229], off
	v_lshl_add_u64 v[228:229], s[38:39], 0, v[132:133]
	s_mov_b32 m0, s47
	s_nop 0
	global_load_lds_dwordx4 v[228:229], off
	s_waitcnt vmcnt(8)
	s_waitcnt lgkmcnt(0)
	s_barrier
	s_setprio 1
	s_waitcnt lgkmcnt(0)
	v_mfma_f32_16x16x32_bf16 v[124:127], v[152:155], v[188:191], v[124:127]
	v_mfma_f32_16x16x32_bf16 v[120:123], v[160:163], v[188:191], v[120:123]
	v_mfma_f32_16x16x32_bf16 v[116:119], v[152:155], v[196:199], v[116:119]
	v_mfma_f32_16x16x32_bf16 v[112:115], v[160:163], v[196:199], v[112:115]
	v_mfma_f32_16x16x32_bf16 v[100:103], v[152:155], v[204:207], v[100:103]
	v_mfma_f32_16x16x32_bf16 v[96:99], v[160:163], v[204:207], v[96:99]
	v_mfma_f32_16x16x32_bf16 v[84:87], v[152:155], v[212:215], v[84:87]
	v_mfma_f32_16x16x32_bf16 v[80:83], v[160:163], v[212:215], v[80:83]
	v_mfma_f32_16x16x32_bf16 v[124:127], v[156:159], v[192:195], v[124:127]
	v_mfma_f32_16x16x32_bf16 v[120:123], v[164:167], v[192:195], v[120:123]
	v_mfma_f32_16x16x32_bf16 v[116:119], v[156:159], v[200:203], v[116:119]
	v_mfma_f32_16x16x32_bf16 v[112:115], v[164:167], v[200:203], v[112:115]
	v_mfma_f32_16x16x32_bf16 v[100:103], v[156:159], v[208:211], v[100:103]
	v_mfma_f32_16x16x32_bf16 v[96:99], v[164:167], v[208:211], v[96:99]
	v_mfma_f32_16x16x32_bf16 v[84:87], v[156:159], v[216:219], v[84:87]
	v_mfma_f32_16x16x32_bf16 v[80:83], v[164:167], v[216:219], v[80:83]
	s_setprio 0
	s_setprio 1
	v_mfma_f32_16x16x32_bf16 v[108:111], v[168:171], v[188:191], v[108:111]
	v_mfma_f32_16x16x32_bf16 v[104:107], v[180:183], v[188:191], v[104:107]
	v_mfma_f32_16x16x32_bf16 v[92:95], v[168:171], v[196:199], v[92:95]
	v_mfma_f32_16x16x32_bf16 v[88:91], v[180:183], v[196:199], v[88:91]
	v_mfma_f32_16x16x32_bf16 v[76:79], v[168:171], v[204:207], v[76:79]
	v_mfma_f32_16x16x32_bf16 v[72:75], v[180:183], v[204:207], v[72:75]
	v_mfma_f32_16x16x32_bf16 v[68:71], v[168:171], v[212:215], v[68:71]
	v_mfma_f32_16x16x32_bf16 v[64:67], v[180:183], v[212:215], v[64:67]
	v_mfma_f32_16x16x32_bf16 v[108:111], v[172:175], v[192:195], v[108:111]
	v_mfma_f32_16x16x32_bf16 v[104:107], v[184:187], v[192:195], v[104:107]
	v_mfma_f32_16x16x32_bf16 v[92:95], v[172:175], v[200:203], v[92:95]
	v_mfma_f32_16x16x32_bf16 v[88:91], v[184:187], v[200:203], v[88:91]
	v_mfma_f32_16x16x32_bf16 v[76:79], v[172:175], v[208:211], v[76:79]
	v_mfma_f32_16x16x32_bf16 v[72:75], v[184:187], v[208:211], v[72:75]
	s_setprio 2
	s_barrier
; #define PG8_STAGE(bufoff, gbase, voff) do { _Pragma("unroll") for (int _i = 0; _i < 2; ++_i) \
;         __builtin_amdgcn_global_load_lds((const unsigned*)((const char*)(gbase) + (voff)[_i]), (LAS unsigned*)(lds + (bufoff) + ldsw + _i * 8192), 16, 0, 0); } while (0)
; #define PG8_LDA(dst, b, h) do { _Pragma("unroll") for (int m = 0; m < 4; ++m) _Pragma("unroll") for (int k = 0; k < 2; ++k) dst[m][k] = *(const LAS bf16x8*)(lds + PG8_SA(b, h) + aoff + m * 2048 + k * 1024); } while (0)
; #define PG8_MMA(ai, bj, At, Bt) do { __builtin_amdgcn_s_setprio(1); _Pragma("unroll") for (int m = 0; m < 4; ++m) _Pragma("unroll") for (int n = 0; n < 2; ++n) _Pragma("unroll") for (int k = 0; k < 2; ++k) \
;         acc[ai][bj][m][n] = __builtin_amdgcn_mfma_f32_16x16x32_bf16(Bt[n][k], At[m][k], acc[ai][bj][m][n], 0, 0, 0); __builtin_amdgcn_s_setprio(0); } while (0)
; #define PG8_WAIT_V(n) asm volatile("s_waitcnt vmcnt(" #n ")" ::: "memory")
; #define PG8_WAIT_L(n) asm volatile("s_waitcnt lgkmcnt(" #n ")" ::: "memory")
; #define PG8_BAR __builtin_amdgcn_s_barrier()
; #define PG8_SCHED __builtin_amdgcn_sched_barrier(0)
; template <class Epi, class Sched, bool ALIGN_EPI = true, bool SP2 = true>
; __device__ __forceinline__ void gemm_phase(LAS unsigned char* lds, const bf16_t* Ag, const bf16_t* Btg, const int K, const int lda, const int ldb, const Sched& S, const Epi& E) {
;     ...
;             PG8_LDA(At, 1, 1); PG8_STAGE(PG8_SB(1, 0), b3, voffB); PG8_STAGE(PG8_SB(1, 1), b3 + hstepB, voffB); PG8_STAGE(PG8_SA(1, 0), a3, voffA);
;             PG8_WAIT_V(8); PG8_WAIT_L(0); PG8_BAR; PG8_MMA(1, 0, At, B0); PG8_MMA(1, 1, At, B1); PG8_BAR; PG8_SCHED;
	v_mfma_f32_16x16x32_bf16 v[68:71], v[172:175], v[216:219], v[68:71]
	v_mfma_f32_16x16x32_bf16 v[64:67], v[184:187], v[216:219], v[64:67]
	s_setprio 0
	s_add_i32 s38, s60, s9
	v_lshl_add_u64 v[220:221], v[220:221], 0, s[12:13]
	s_mov_b32 m0, s38
	ds_read_b128 v[188:191], v151 offset:49152
	ds_read_b128 v[192:195], v151 offset:50176
	ds_read_b128 v[196:199], v151 offset:51200
	ds_read_b128 v[200:203], v151 offset:52224
	ds_read_b128 v[204:207], v151 offset:53248
	ds_read_b128 v[208:211], v151 offset:54272
	ds_read_b128 v[212:215], v151 offset:55296
	ds_read_b128 v[216:219], v151 offset:56320
	global_load_lds_dwordx4 v[220:221], off
	s_add_i32 m0, s38, 0x2000
	s_add_u32 s34, s34, 0x80080
	v_lshl_add_u64 v[220:221], v[222:223], 0, s[12:13]
	s_addc_u32 s35, s35, 0
	s_add_i32 s38, s61, s9
	global_load_lds_dwordx4 v[220:221], off
	v_lshl_add_u64 v[220:221], s[34:35], 0, v[130:131]
	s_mov_b32 m0, s38
	s_nop 0
	global_load_lds_dwordx4 v[220:221], off
	v_lshl_add_u64 v[220:221], s[34:35], 0, v[134:135]
	s_add_i32 m0, s38, 0x2000
	s_nop 0
	global_load_lds_dwordx4 v[220:221], off
	v_lshl_add_u64 v[220:221], v[224:225], 0, s[12:13]
	s_mov_b32 m0, s50
	s_nop 0
	global_load_lds_dwordx4 v[220:221], off
	v_lshl_add_u64 v[220:221], v[226:227], 0, s[12:13]
	s_mov_b32 m0, s51
	s_nop 0
	global_load_lds_dwordx4 v[220:221], off
	s_waitcnt vmcnt(8)
	s_waitcnt lgkmcnt(0)
	s_barrier
	s_setprio 1
	s_waitcnt lgkmcnt(0)
	v_mfma_f32_16x16x32_bf16 v[60:63], v[152:155], v[188:191], v[60:63]
	v_mfma_f32_16x16x32_bf16 v[56:59], v[160:163], v[188:191], v[56:59]
	v_mfma_f32_16x16x32_bf16 v[52:55], v[152:155], v[196:199], v[52:55]
	v_mfma_f32_16x16x32_bf16 v[48:51], v[160:163], v[196:199], v[48:51]
	v_mfma_f32_16x16x32_bf16 v[36:39], v[152:155], v[204:207], v[36:39]
	v_mfma_f32_16x16x32_bf16 v[32:35], v[160:163], v[204:207], v[32:35]
	v_mfma_f32_16x16x32_bf16 v[20:23], v[152:155], v[212:215], v[20:23]
	v_mfma_f32_16x16x32_bf16 v[16:19], v[160:163], v[212:215], v[16:19]
	v_mfma_f32_16x16x32_bf16 v[60:63], v[156:159], v[192:195], v[60:63]
	v_mfma_f32_16x16x32_bf16 v[56:59], v[164:167], v[192:195], v[56:59]
	v_mfma_f32_16x16x32_bf16 v[52:55], v[156:159], v[200:203], v[52:55]
	v_mfma_f32_16x16x32_bf16 v[48:51], v[164:167], v[200:203], v[48:51]
	v_mfma_f32_16x16x32_bf16 v[36:39], v[156:159], v[208:211], v[36:39]
	v_mfma_f32_16x16x32_bf16 v[32:35], v[164:167], v[208:211], v[32:35]
	v_mfma_f32_16x16x32_bf16 v[20:23], v[156:159], v[216:219], v[20:23]
	v_mfma_f32_16x16x32_bf16 v[16:19], v[164:167], v[216:219], v[16:19]
	s_setprio 0
	s_setprio 1
	v_mfma_f32_16x16x32_bf16 v[44:47], v[168:171], v[188:191], v[44:47]
	v_mfma_f32_16x16x32_bf16 v[40:43], v[180:183], v[188:191], v[40:43]
	v_mfma_f32_16x16x32_bf16 v[28:31], v[168:171], v[196:199], v[28:31]
	v_mfma_f32_16x16x32_bf16 v[24:27], v[180:183], v[196:199], v[24:27]
	v_mfma_f32_16x16x32_bf16 v[12:15], v[168:171], v[204:207], v[12:15]
	v_mfma_f32_16x16x32_bf16 v[8:11], v[180:183], v[204:207], v[8:11]
	v_mfma_f32_16x16x32_bf16 v[4:7], v[168:171], v[212:215], v[4:7]
	v_mfma_f32_16x16x32_bf16 v[0:3], v[180:183], v[212:215], v[0:3]
	v_mfma_f32_16x16x32_bf16 v[44:47], v[172:175], v[192:195], v[44:47]
	v_mfma_f32_16x16x32_bf16 v[40:43], v[184:187], v[192:195], v[40:43]
	v_mfma_f32_16x16x32_bf16 v[28:31], v[172:175], v[200:203], v[28:31]
	v_mfma_f32_16x16x32_bf16 v[24:27], v[184:187], v[200:203], v[24:27]
	v_mfma_f32_16x16x32_bf16 v[12:15], v[172:175], v[208:211], v[12:15]
	v_mfma_f32_16x16x32_bf16 v[8:11], v[184:187], v[208:211], v[8:11]
	s_setprio 2
	s_barrier
	v_mfma_f32_16x16x32_bf16 v[4:7], v[172:175], v[216:219], v[4:7]
	v_mfma_f32_16x16x32_bf16 v[0:3], v[184:187], v[216:219], v[0:3]
	s_setprio 0
	s_add_i32 s59, s59, 2
	s_add_u32 s30, s30, 0x100
	s_addc_u32 s31, s31, 0
	s_add_u32 s57, s57, 0x100
	s_addc_u32 s58, s58, 0
	s_cmp_gt_u32 s59, 29
	s_cbranch_scc0 .LBB0_278
	s_and_b64 vcc, exec, s[14:15]
	s_cbranch_vccz .LBB0_281
	s_barrier

; #define PG8_STAGE(bufoff, gbase, voff) do { _Pragma("unroll") for (int _i = 0; _i < 2; ++_i) \
;         __builtin_amdgcn_global_load_lds((const unsigned*)((const char*)(gbase) + (voff)[_i]), (LAS unsigned*)(lds + (bufoff) + ldsw + _i * 8192), 16, 0, 0); } while (0)
; #define PG8_LDA(dst, b, h) do { _Pragma("unroll") for (int m = 0; m < 4; ++m) _Pragma("unroll") for (int k = 0; k < 2; ++k) dst[m][k] = *(const LAS bf16x8*)(lds + PG8_SA(b, h) + aoff + m * 2048 + k * 1024); } while (0)
; #define PG8_LDB(dst, b, h) do { _Pragma("unroll") for (int n = 0; n < 2; ++n) _Pragma("unroll") for (int k = 0; k < 2; ++k) dst[n][k] = *(const LAS bf16x8*)(lds + PG8_SB(b, h) + boff + n * 2048 + k * 1024); } while (0)
; #define PG8_MMA(ai, bj, At, Bt) do { __builtin_amdgcn_s_setprio(1); _Pragma("unroll") for (int m = 0; m < 4; ++m) _Pragma("unroll") for (int n = 0; n < 2; ++n) _Pragma("unroll") for (int k = 0; k < 2; ++k) \
;         acc[ai][bj][m][n] = __builtin_amdgcn_mfma_f32_16x16x32_bf16(Bt[n][k], At[m][k], acc[ai][bj][m][n], 0, 0, 0); __builtin_amdgcn_s_setprio(0); } while (0)
; #define PG8_WAIT_V(n) asm volatile("s_waitcnt vmcnt(" #n ")" ::: "memory")
; #define PG8_WAIT_L(n) asm volatile("s_waitcnt lgkmcnt(" #n ")" ::: "memory")
; #define PG8_BAR __builtin_amdgcn_s_barrier()
; #define PG8_SCHED __builtin_amdgcn_sched_barrier(0)
; template <class Epi, class Sched, bool ALIGN_EPI = true, bool SP2 = true>
; __device__ __forceinline__ void gemm_phase(LAS unsigned char* lds, const bf16_t* Ag, const bf16_t* Btg, const int K, const int lda, const int ldb, const Sched& S, const Epi& E) {
;     ...
;             const bool last = (t == nt - 2);
;             const char* a1 = cA + (size_t)(t + 1) * kstep;
;             const char* a2 = last ? nA : cA + (size_t)(t + 2) * kstep; const char* b2 = last ? nB : cB + (size_t)(t + 2) * kstep;
;             const char* a3 = a2 + kstep; const char* b3 = b2 + kstep;
;             if constexpr (SP2) {
;             PG8_LDB(B0, 0, 0); PG8_LDB(B1, 0, 1); PG8_SCHED; PG8_LDA(At, 0, 0); PG8_STAGE(PG8_SA(1, 1), a1 + hstepA, voffA);
;             PG8_WAIT_V(8); PG8_WAIT_L(0); PG8_BAR; PG8_MMA(0, 0, At, B0); PG8_MMA(0, 1, At, B1); PG8_BAR; PG8_SCHED;
;             PG8_LDA(At, 0, 1); PG8_STAGE(PG8_SB(0, 0), b2, voffB); PG8_STAGE(PG8_SB(0, 1), b2 + hstepB, voffB); PG8_STAGE(PG8_SA(0, 0), a2, voffA);
.LBB0_302:
	ds_read_b128 v[146:149], v143
	ds_read_b128 v[150:153], v143 offset:1024
	ds_read_b128 v[154:157], v143 offset:2048
	ds_read_b128 v[158:161], v143 offset:3072
	ds_read_b128 v[162:165], v144
	ds_read_b128 v[166:169], v144 offset:1024
	ds_read_b128 v[170:173], v144 offset:2048
	ds_read_b128 v[180:183], v144 offset:3072
	s_add_u32 s30, s28, 0xfff80080
	s_addc_u32 s31, s29, -1
	s_cmp_eq_u32 s62, 28
	s_cselect_b32 s35, s56, s31
	s_cselect_b32 s34, s57, s30
	s_cselect_b32 s31, s58, s61
	s_cselect_b32 s30, s59, s60
	v_lshl_add_u64 v[174:175], s[28:29], 0, v[138:139]
	s_add_i32 m0, s41, 0xc000
	ds_read_b128 v[184:187], v145
	ds_read_b128 v[188:191], v145 offset:1024
	ds_read_b128 v[192:195], v145 offset:2048
	ds_read_b128 v[196:199], v145 offset:3072
	ds_read_b128 v[200:203], v145 offset:4096
	ds_read_b128 v[204:207], v145 offset:5120
	ds_read_b128 v[208:211], v145 offset:6144
	ds_read_b128 v[212:215], v145 offset:7168
	global_load_lds_dwordx4 v[174:175], off
	v_lshl_add_u64 v[174:175], s[28:29], 0, v[140:141]
	s_add_i32 m0, s41, 0xe000
	s_nop 0
	global_load_lds_dwordx4 v[174:175], off
	s_waitcnt vmcnt(8)
	s_waitcnt lgkmcnt(0)
	s_barrier
	s_setprio 1
	s_waitcnt lgkmcnt(0)
	v_mfma_f32_16x16x32_bf16 v[124:127], v[146:149], v[184:187], v[124:127]
	v_mfma_f32_16x16x32_bf16 v[120:123], v[154:157], v[184:187], v[120:123]
	v_mfma_f32_16x16x32_bf16 v[116:119], v[146:149], v[192:195], v[116:119]
	v_mfma_f32_16x16x32_bf16 v[112:115], v[154:157], v[192:195], v[112:115]
	v_mfma_f32_16x16x32_bf16 v[100:103], v[146:149], v[200:203], v[100:103]
	v_mfma_f32_16x16x32_bf16 v[96:99], v[154:157], v[200:203], v[96:99]
	v_mfma_f32_16x16x32_bf16 v[84:87], v[146:149], v[208:211], v[84:87]
	v_mfma_f32_16x16x32_bf16 v[80:83], v[154:157], v[208:211], v[80:83]
	v_mfma_f32_16x16x32_bf16 v[124:127], v[150:153], v[188:191], v[124:127]
	v_mfma_f32_16x16x32_bf16 v[120:123], v[158:161], v[188:191], v[120:123]
	v_mfma_f32_16x16x32_bf16 v[116:119], v[150:153], v[196:199], v[116:119]
	v_mfma_f32_16x16x32_bf16 v[112:115], v[158:161], v[196:199], v[112:115]
	v_mfma_f32_16x16x32_bf16 v[100:103], v[150:153], v[204:207], v[100:103]
	v_mfma_f32_16x16x32_bf16 v[96:99], v[158:161], v[204:207], v[96:99]
	v_mfma_f32_16x16x32_bf16 v[84:87], v[150:153], v[212:215], v[84:87]
	v_mfma_f32_16x16x32_bf16 v[80:83], v[158:161], v[212:215], v[80:83]
	s_setprio 0
	s_setprio 1
	v_mfma_f32_16x16x32_bf16 v[108:111], v[162:165], v[184:187], v[108:111]
	v_mfma_f32_16x16x32_bf16 v[104:107], v[170:173], v[184:187], v[104:107]
	v_mfma_f32_16x16x32_bf16 v[92:95], v[162:165], v[192:195], v[92:95]
	v_mfma_f32_16x16x32_bf16 v[88:91], v[170:173], v[192:195], v[88:91]
	v_mfma_f32_16x16x32_bf16 v[76:79], v[162:165], v[200:203], v[76:79]
	v_mfma_f32_16x16x32_bf16 v[72:75], v[170:173], v[200:203], v[72:75]
	v_mfma_f32_16x16x32_bf16 v[68:71], v[162:165], v[208:211], v[68:71]
	v_mfma_f32_16x16x32_bf16 v[64:67], v[170:173], v[208:211], v[64:67]
	v_mfma_f32_16x16x32_bf16 v[108:111], v[166:169], v[188:191], v[108:111]
	v_mfma_f32_16x16x32_bf16 v[104:107], v[180:183], v[188:191], v[104:107]
	v_mfma_f32_16x16x32_bf16 v[92:95], v[166:169], v[196:199], v[92:95]
	v_mfma_f32_16x16x32_bf16 v[88:91], v[180:183], v[196:199], v[88:91]
	v_mfma_f32_16x16x32_bf16 v[76:79], v[166:169], v[204:207], v[76:79]
	v_mfma_f32_16x16x32_bf16 v[72:75], v[180:183], v[204:207], v[72:75]
	s_setprio 2
	s_barrier
	v_mfma_f32_16x16x32_bf16 v[68:71], v[166:169], v[212:215], v[68:71]
	v_mfma_f32_16x16x32_bf16 v[64:67], v[180:183], v[212:215], v[64:67]
	s_setprio 0
	s_add_i32 s63, s0, s39
	v_lshl_add_u64 v[174:175], s[30:31], 0, v[130:131]
	s_mov_b32 m0, s63
	ds_read_b128 v[184:187], v145 offset:16384
	ds_read_b128 v[188:191], v145 offset:17408
	ds_read_b128 v[192:195], v145 offset:18432
	ds_read_b128 v[196:199], v145 offset:19456
	ds_read_b128 v[200:203], v145 offset:20480
	ds_read_b128 v[204:207], v145 offset:21504
	ds_read_b128 v[208:211], v145 offset:22528
	ds_read_b128 v[212:215], v145 offset:23552
	global_load_lds_dwordx4 v[174:175], off
	s_add_i32 m0, s63, 0x2000
	s_add_u32 s64, s30, 0x80000
	v_lshl_add_u64 v[216:217], s[30:31], 0, v[134:135]
	s_addc_u32 s65, s31, 0
	s_add_i32 s63, s55, s39
	global_load_lds_dwordx4 v[216:217], off
	v_lshl_add_u64 v[218:219], s[64:65], 0, v[130:131]
	s_mov_b32 m0, s63
	v_lshl_add_u64 v[220:221], s[34:35], 0, v[132:133]
	global_load_lds_dwordx4 v[218:219], off
	v_lshl_add_u64 v[218:219], s[64:65], 0, v[134:135]
	s_add_i32 m0, s63, 0x2000
	s_nop 0
	global_load_lds_dwordx4 v[218:219], off
	v_lshl_add_u64 v[218:219], s[34:35], 0, v[128:129]
	s_mov_b32 m0, s41
	s_nop 0
	global_load_lds_dwordx4 v[218:219], off
	s_mov_b32 m0, s46
	s_nop 0
	global_load_lds_dwordx4 v[220:221], off
	s_waitcnt vmcnt(8)
	s_waitcnt lgkmcnt(0)
	s_barrier
; #define PG8_STAGE(bufoff, gbase, voff) do { _Pragma("unroll") for (int _i = 0; _i < 2; ++_i) \
;         __builtin_amdgcn_global_load_lds((const unsigned*)((const char*)(gbase) + (voff)[_i]), (LAS unsigned*)(lds + (bufoff) + ldsw + _i * 8192), 16, 0, 0); } while (0)
; #define PG8_LDA(dst, b, h) do { _Pragma("unroll") for (int m = 0; m < 4; ++m) _Pragma("unroll") for (int k = 0; k < 2; ++k) dst[m][k] = *(const LAS bf16x8*)(lds + PG8_SA(b, h) + aoff + m * 2048 + k * 1024); } while (0)
; #define PG8_LDB(dst, b, h) do { _Pragma("unroll") for (int n = 0; n < 2; ++n) _Pragma("unroll") for (int k = 0; k < 2; ++k) dst[n][k] = *(const LAS bf16x8*)(lds + PG8_SB(b, h) + boff + n * 2048 + k * 1024); } while (0)
; #define PG8_MMA(ai, bj, At, Bt) do { __builtin_amdgcn_s_setprio(1); _Pragma("unroll") for (int m = 0; m < 4; ++m) _Pragma("unroll") for (int n = 0; n < 2; ++n) _Pragma("unroll") for (int k = 0; k < 2; ++k) \
;         acc[ai][bj][m][n] = __builtin_amdgcn_mfma_f32_16x16x32_bf16(Bt[n][k], At[m][k], acc[ai][bj][m][n], 0, 0, 0); __builtin_amdgcn_s_setprio(0); } while (0)
; #define PG8_WAIT_V(n) asm volatile("s_waitcnt vmcnt(" #n ")" ::: "memory")
; #define PG8_WAIT_L(n) asm volatile("s_waitcnt lgkmcnt(" #n ")" ::: "memory")
; #define PG8_BAR __builtin_amdgcn_s_barrier()
; #define PG8_SCHED __builtin_amdgcn_sched_barrier(0)
; template <class Epi, class Sched, bool ALIGN_EPI = true, bool SP2 = true>
; __device__ __forceinline__ void gemm_phase(LAS unsigned char* lds, const bf16_t* Ag, const bf16_t* Btg, const int K, const int lda, const int ldb, const Sched& S, const Epi& E) {
;     ...
;             PG8_WAIT_V(8); PG8_WAIT_L(0); PG8_BAR; PG8_MMA(1, 0, At, B0); PG8_MMA(1, 1, At, B1); PG8_BAR; PG8_SCHED;
;             PG8_LDB(B0, 1, 0); PG8_LDB(B1, 1, 1); PG8_SCHED; PG8_LDA(At, 1, 0); PG8_STAGE(PG8_SA(0, 1), a2 + hstepA, voffA);
;             PG8_WAIT_V(8); PG8_WAIT_L(0); PG8_BAR; PG8_MMA(0, 0, At, B0); PG8_MMA(0, 1, At, B1); PG8_BAR; PG8_SCHED;
	s_setprio 1
	s_waitcnt lgkmcnt(0)
	v_mfma_f32_16x16x32_bf16 v[60:63], v[146:149], v[184:187], v[60:63]
	v_mfma_f32_16x16x32_bf16 v[56:59], v[154:157], v[184:187], v[56:59]
	v_mfma_f32_16x16x32_bf16 v[52:55], v[146:149], v[192:195], v[52:55]
	v_mfma_f32_16x16x32_bf16 v[48:51], v[154:157], v[192:195], v[48:51]
	v_mfma_f32_16x16x32_bf16 v[36:39], v[146:149], v[200:203], v[36:39]
	v_mfma_f32_16x16x32_bf16 v[32:35], v[154:157], v[200:203], v[32:35]
	v_mfma_f32_16x16x32_bf16 v[20:23], v[146:149], v[208:211], v[20:23]
	v_mfma_f32_16x16x32_bf16 v[16:19], v[154:157], v[208:211], v[16:19]
	v_mfma_f32_16x16x32_bf16 v[60:63], v[150:153], v[188:191], v[60:63]
	v_mfma_f32_16x16x32_bf16 v[56:59], v[158:161], v[188:191], v[56:59]
	v_mfma_f32_16x16x32_bf16 v[52:55], v[150:153], v[196:199], v[52:55]
	v_mfma_f32_16x16x32_bf16 v[48:51], v[158:161], v[196:199], v[48:51]
	v_mfma_f32_16x16x32_bf16 v[36:39], v[150:153], v[204:207], v[36:39]
	v_mfma_f32_16x16x32_bf16 v[32:35], v[158:161], v[204:207], v[32:35]
	v_mfma_f32_16x16x32_bf16 v[20:23], v[150:153], v[212:215], v[20:23]
	v_mfma_f32_16x16x32_bf16 v[16:19], v[158:161], v[212:215], v[16:19]
	s_setprio 0
	s_setprio 1
	v_mfma_f32_16x16x32_bf16 v[44:47], v[162:165], v[184:187], v[44:47]
	v_mfma_f32_16x16x32_bf16 v[40:43], v[170:173], v[184:187], v[40:43]
	v_mfma_f32_16x16x32_bf16 v[28:31], v[162:165], v[192:195], v[28:31]
	v_mfma_f32_16x16x32_bf16 v[24:27], v[170:173], v[192:195], v[24:27]
	v_mfma_f32_16x16x32_bf16 v[12:15], v[162:165], v[200:203], v[12:15]
	v_mfma_f32_16x16x32_bf16 v[8:11], v[170:173], v[200:203], v[8:11]
	v_mfma_f32_16x16x32_bf16 v[4:7], v[162:165], v[208:211], v[4:7]
	v_mfma_f32_16x16x32_bf16 v[0:3], v[170:173], v[208:211], v[0:3]
	v_mfma_f32_16x16x32_bf16 v[44:47], v[166:169], v[188:191], v[44:47]
	v_mfma_f32_16x16x32_bf16 v[40:43], v[180:183], v[188:191], v[40:43]
	v_mfma_f32_16x16x32_bf16 v[28:31], v[166:169], v[196:199], v[28:31]
	v_mfma_f32_16x16x32_bf16 v[24:27], v[180:183], v[196:199], v[24:27]
	v_mfma_f32_16x16x32_bf16 v[12:15], v[166:169], v[204:207], v[12:15]
	v_mfma_f32_16x16x32_bf16 v[8:11], v[180:183], v[204:207], v[8:11]
	s_setprio 2
	s_barrier
	v_mfma_f32_16x16x32_bf16 v[4:7], v[166:169], v[212:215], v[4:7]
	v_mfma_f32_16x16x32_bf16 v[0:3], v[180:183], v[212:215], v[0:3]
	s_setprio 0
	s_add_i32 s63, 0, 0x18000
	s_add_i32 s64, 0, 0x1c000
	v_add_u32_e32 v158, s63, v142
	v_add_u32_e32 v180, s64, v142
	ds_read_b128 v[146:149], v158
	ds_read_b128 v[150:153], v158 offset:1024
	ds_read_b128 v[154:157], v158 offset:2048
	ds_read_b128 v[158:161], v158 offset:3072
	ds_read_b128 v[162:165], v180
	ds_read_b128 v[166:169], v180 offset:1024
	ds_read_b128 v[170:173], v180 offset:2048
	ds_read_b128 v[180:183], v180 offset:3072
	s_add_u32 s34, s34, 0x80000
	s_addc_u32 s35, s35, 0
	s_mov_b32 m0, s47
	v_lshl_add_u64 v[222:223], s[34:35], 0, v[128:129]
	ds_read_b128 v[184:187], v145 offset:32768
	ds_read_b128 v[188:191], v145 offset:33792
	ds_read_b128 v[192:195], v145 offset:34816
	ds_read_b128 v[196:199], v145 offset:35840
	ds_read_b128 v[200:203], v145 offset:36864
	ds_read_b128 v[204:207], v145 offset:37888
	ds_read_b128 v[208:211], v145 offset:38912
	ds_read_b128 v[212:215], v145 offset:39936
	global_load_lds_dwordx4 v[222:223], off
	v_lshl_add_u64 v[222:223], s[34:35], 0, v[132:133]
	s_mov_b32 m0, s50
	s_nop 0
	global_load_lds_dwordx4 v[222:223], off
	s_waitcnt vmcnt(8)
	s_waitcnt lgkmcnt(0)
	s_barrier
	s_setprio 1
	s_waitcnt lgkmcnt(0)
	v_mfma_f32_16x16x32_bf16 v[124:127], v[146:149], v[184:187], v[124:127]
	v_mfma_f32_16x16x32_bf16 v[120:123], v[154:157], v[184:187], v[120:123]
	v_mfma_f32_16x16x32_bf16 v[116:119], v[146:149], v[192:195], v[116:119]
	v_mfma_f32_16x16x32_bf16 v[112:115], v[154:157], v[192:195], v[112:115]
	v_mfma_f32_16x16x32_bf16 v[100:103], v[146:149], v[200:203], v[100:103]
	v_mfma_f32_16x16x32_bf16 v[96:99], v[154:157], v[200:203], v[96:99]
	v_mfma_f32_16x16x32_bf16 v[84:87], v[146:149], v[208:211], v[84:87]
	v_mfma_f32_16x16x32_bf16 v[80:83], v[154:157], v[208:211], v[80:83]
	v_mfma_f32_16x16x32_bf16 v[124:127], v[150:153], v[188:191], v[124:127]
	v_mfma_f32_16x16x32_bf16 v[120:123], v[158:161], v[188:191], v[120:123]
	v_mfma_f32_16x16x32_bf16 v[116:119], v[150:153], v[196:199], v[116:119]
	v_mfma_f32_16x16x32_bf16 v[112:115], v[158:161], v[196:199], v[112:115]
	v_mfma_f32_16x16x32_bf16 v[100:103], v[150:153], v[204:207], v[100:103]
	v_mfma_f32_16x16x32_bf16 v[96:99], v[158:161], v[204:207], v[96:99]
	v_mfma_f32_16x16x32_bf16 v[84:87], v[150:153], v[212:215], v[84:87]
	v_mfma_f32_16x16x32_bf16 v[80:83], v[158:161], v[212:215], v[80:83]
	s_setprio 0
	s_setprio 1
	v_mfma_f32_16x16x32_bf16 v[108:111], v[162:165], v[184:187], v[108:111]
	v_mfma_f32_16x16x32_bf16 v[104:107], v[170:173], v[184:187], v[104:107]
	v_mfma_f32_16x16x32_bf16 v[92:95], v[162:165], v[192:195], v[92:95]
	v_mfma_f32_16x16x32_bf16 v[88:91], v[170:173], v[192:195], v[88:91]
	v_mfma_f32_16x16x32_bf16 v[76:79], v[162:165], v[200:203], v[76:79]
	v_mfma_f32_16x16x32_bf16 v[72:75], v[170:173], v[200:203], v[72:75]
	v_mfma_f32_16x16x32_bf16 v[68:71], v[162:165], v[208:211], v[68:71]
	v_mfma_f32_16x16x32_bf16 v[64:67], v[170:173], v[208:211], v[64:67]
	v_mfma_f32_16x16x32_bf16 v[108:111], v[166:169], v[188:191], v[108:111]
	v_mfma_f32_16x16x32_bf16 v[104:107], v[180:183], v[188:191], v[104:107]
	v_mfma_f32_16x16x32_bf16 v[92:95], v[166:169], v[196:199], v[92:95]
	v_mfma_f32_16x16x32_bf16 v[88:91], v[180:183], v[196:199], v[88:91]
	v_mfma_f32_16x16x32_bf16 v[76:79], v[166:169], v[204:207], v[76:79]
	v_mfma_f32_16x16x32_bf16 v[72:75], v[180:183], v[204:207], v[72:75]
	s_setprio 2
	s_barrier
; #define PG8_STAGE(bufoff, gbase, voff) do { _Pragma("unroll") for (int _i = 0; _i < 2; ++_i) \
;         __builtin_amdgcn_global_load_lds((const unsigned*)((const char*)(gbase) + (voff)[_i]), (LAS unsigned*)(lds + (bufoff) + ldsw + _i * 8192), 16, 0, 0); } while (0)
; #define PG8_LDA(dst, b, h) do { _Pragma("unroll") for (int m = 0; m < 4; ++m) _Pragma("unroll") for (int k = 0; k < 2; ++k) dst[m][k] = *(const LAS bf16x8*)(lds + PG8_SA(b, h) + aoff + m * 2048 + k * 1024); } while (0)
; #define PG8_MMA(ai, bj, At, Bt) do { __builtin_amdgcn_s_setprio(1); _Pragma("unroll") for (int m = 0; m < 4; ++m) _Pragma("unroll") for (int n = 0; n < 2; ++n) _Pragma("unroll") for (int k = 0; k < 2; ++k) \
;         acc[ai][bj][m][n] = __builtin_amdgcn_mfma_f32_16x16x32_bf16(Bt[n][k], At[m][k], acc[ai][bj][m][n], 0, 0, 0); __builtin_amdgcn_s_setprio(0); } while (0)
; #define PG8_WAIT_V(n) asm volatile("s_waitcnt vmcnt(" #n ")" ::: "memory")
; #define PG8_WAIT_L(n) asm volatile("s_waitcnt lgkmcnt(" #n ")" ::: "memory")
; #define PG8_BAR __builtin_amdgcn_s_barrier()
; #define PG8_SCHED __builtin_amdgcn_sched_barrier(0)
; template <class Epi, class Sched, bool ALIGN_EPI = true, bool SP2 = true>
; __device__ __forceinline__ void gemm_phase(LAS unsigned char* lds, const bf16_t* Ag, const bf16_t* Btg, const int K, const int lda, const int ldb, const Sched& S, const Epi& E) {
;     ...
;             PG8_LDA(At, 1, 1); PG8_STAGE(PG8_SB(1, 0), b3, voffB); PG8_STAGE(PG8_SB(1, 1), b3 + hstepB, voffB); PG8_STAGE(PG8_SA(1, 0), a3, voffA);
;             PG8_WAIT_V(8); PG8_WAIT_L(0); PG8_BAR; PG8_MMA(1, 0, At, B0); PG8_MMA(1, 1, At, B1); PG8_BAR; PG8_SCHED;
	v_mfma_f32_16x16x32_bf16 v[68:71], v[166:169], v[212:215], v[68:71]
	v_mfma_f32_16x16x32_bf16 v[64:67], v[180:183], v[212:215], v[64:67]
	s_setprio 0
	s_add_i32 s34, s63, s39
	v_lshl_add_u64 v[174:175], v[174:175], 0, s[10:11]
	s_mov_b32 m0, s34
	ds_read_b128 v[184:187], v145 offset:49152
	ds_read_b128 v[188:191], v145 offset:50176
	ds_read_b128 v[192:195], v145 offset:51200
	ds_read_b128 v[196:199], v145 offset:52224
	ds_read_b128 v[200:203], v145 offset:53248
	ds_read_b128 v[204:207], v145 offset:54272
	ds_read_b128 v[208:211], v145 offset:55296
	ds_read_b128 v[212:215], v145 offset:56320
	global_load_lds_dwordx4 v[174:175], off
	s_add_i32 m0, s34, 0x2000
	s_add_u32 s30, s30, 0x80080
	v_lshl_add_u64 v[174:175], v[216:217], 0, s[10:11]
	s_addc_u32 s31, s31, 0
	s_add_i32 s34, s64, s39
	global_load_lds_dwordx4 v[174:175], off
	v_lshl_add_u64 v[174:175], s[30:31], 0, v[130:131]
	s_mov_b32 m0, s34
	s_nop 0
	global_load_lds_dwordx4 v[174:175], off
	v_lshl_add_u64 v[174:175], s[30:31], 0, v[134:135]
	s_add_i32 m0, s34, 0x2000
	s_nop 0
	global_load_lds_dwordx4 v[174:175], off
	v_lshl_add_u64 v[174:175], v[218:219], 0, s[10:11]
	s_mov_b32 m0, s51
	s_nop 0
	global_load_lds_dwordx4 v[174:175], off
	v_lshl_add_u64 v[174:175], v[220:221], 0, s[10:11]
	s_mov_b32 m0, s52
	s_nop 0
	global_load_lds_dwordx4 v[174:175], off
	s_waitcnt vmcnt(8)
	s_waitcnt lgkmcnt(0)
	s_barrier
	s_setprio 1
	s_waitcnt lgkmcnt(0)
	v_mfma_f32_16x16x32_bf16 v[60:63], v[146:149], v[184:187], v[60:63]
	v_mfma_f32_16x16x32_bf16 v[56:59], v[154:157], v[184:187], v[56:59]
	v_mfma_f32_16x16x32_bf16 v[52:55], v[146:149], v[192:195], v[52:55]
	v_mfma_f32_16x16x32_bf16 v[48:51], v[154:157], v[192:195], v[48:51]
	v_mfma_f32_16x16x32_bf16 v[36:39], v[146:149], v[200:203], v[36:39]
	v_mfma_f32_16x16x32_bf16 v[32:35], v[154:157], v[200:203], v[32:35]
	v_mfma_f32_16x16x32_bf16 v[20:23], v[146:149], v[208:211], v[20:23]
	v_mfma_f32_16x16x32_bf16 v[16:19], v[154:157], v[208:211], v[16:19]
	v_mfma_f32_16x16x32_bf16 v[60:63], v[150:153], v[188:191], v[60:63]
	v_mfma_f32_16x16x32_bf16 v[56:59], v[158:161], v[188:191], v[56:59]
	v_mfma_f32_16x16x32_bf16 v[52:55], v[150:153], v[196:199], v[52:55]
	v_mfma_f32_16x16x32_bf16 v[48:51], v[158:161], v[196:199], v[48:51]
	v_mfma_f32_16x16x32_bf16 v[36:39], v[150:153], v[204:207], v[36:39]
	v_mfma_f32_16x16x32_bf16 v[32:35], v[158:161], v[204:207], v[32:35]
	v_mfma_f32_16x16x32_bf16 v[20:23], v[150:153], v[212:215], v[20:23]
	v_mfma_f32_16x16x32_bf16 v[16:19], v[158:161], v[212:215], v[16:19]
	s_setprio 0
	s_setprio 1
	v_mfma_f32_16x16x32_bf16 v[44:47], v[162:165], v[184:187], v[44:47]
	v_mfma_f32_16x16x32_bf16 v[40:43], v[170:173], v[184:187], v[40:43]
	v_mfma_f32_16x16x32_bf16 v[28:31], v[162:165], v[192:195], v[28:31]
	v_mfma_f32_16x16x32_bf16 v[24:27], v[170:173], v[192:195], v[24:27]
	v_mfma_f32_16x16x32_bf16 v[12:15], v[162:165], v[200:203], v[12:15]
	v_mfma_f32_16x16x32_bf16 v[8:11], v[170:173], v[200:203], v[8:11]
	v_mfma_f32_16x16x32_bf16 v[4:7], v[162:165], v[208:211], v[4:7]
	v_mfma_f32_16x16x32_bf16 v[0:3], v[170:173], v[208:211], v[0:3]
	v_mfma_f32_16x16x32_bf16 v[44:47], v[166:169], v[188:191], v[44:47]
	v_mfma_f32_16x16x32_bf16 v[40:43], v[180:183], v[188:191], v[40:43]
	v_mfma_f32_16x16x32_bf16 v[28:31], v[166:169], v[196:199], v[28:31]
	v_mfma_f32_16x16x32_bf16 v[24:27], v[180:183], v[196:199], v[24:27]
	v_mfma_f32_16x16x32_bf16 v[12:15], v[166:169], v[204:207], v[12:15]
	v_mfma_f32_16x16x32_bf16 v[8:11], v[180:183], v[204:207], v[8:11]
	s_setprio 2
	s_barrier
	v_mfma_f32_16x16x32_bf16 v[4:7], v[166:169], v[212:215], v[4:7]
	v_mfma_f32_16x16x32_bf16 v[0:3], v[180:183], v[212:215], v[0:3]
	s_setprio 0
	s_add_i32 s62, s62, 2
	s_add_u32 s28, s28, 0x100
	s_addc_u32 s29, s29, 0
	s_add_u32 s60, s60, 0x100
	s_addc_u32 s61, s61, 0
	s_cmp_gt_u32 s62, 29
	s_cbranch_scc0 .LBB0_302
	s_and_b64 vcc, exec, s[12:13]
	s_cbranch_vccz .LBB0_305
	s_barrier

; #define PG8_STAGE(bufoff, gbase, voff) do { _Pragma("unroll") for (int _i = 0; _i < 2; ++_i) \
;         __builtin_amdgcn_global_load_lds((const unsigned*)((const char*)(gbase) + (voff)[_i]), (LAS unsigned*)(lds + (bufoff) + ldsw + _i * 8192), 16, 0, 0); } while (0)
; #define PG8_LDA(dst, b, h) do { _Pragma("unroll") for (int m = 0; m < 4; ++m) _Pragma("unroll") for (int k = 0; k < 2; ++k) dst[m][k] = *(const LAS bf16x8*)(lds + PG8_SA(b, h) + aoff + m * 2048 + k * 1024); } while (0)
; #define PG8_LDB(dst, b, h) do { _Pragma("unroll") for (int n = 0; n < 2; ++n) _Pragma("unroll") for (int k = 0; k < 2; ++k) dst[n][k] = *(const LAS bf16x8*)(lds + PG8_SB(b, h) + boff + n * 2048 + k * 1024); } while (0)
; #define PG8_MMA(ai, bj, At, Bt) do { __builtin_amdgcn_s_setprio(1); _Pragma("unroll") for (int m = 0; m < 4; ++m) _Pragma("unroll") for (int n = 0; n < 2; ++n) _Pragma("unroll") for (int k = 0; k < 2; ++k) \
;         acc[ai][bj][m][n] = __builtin_amdgcn_mfma_f32_16x16x32_bf16(Bt[n][k], At[m][k], acc[ai][bj][m][n], 0, 0, 0); __builtin_amdgcn_s_setprio(0); } while (0)
; #define PG8_WAIT_V(n) asm volatile("s_waitcnt vmcnt(" #n ")" ::: "memory")
; #define PG8_WAIT_L(n) asm volatile("s_waitcnt lgkmcnt(" #n ")" ::: "memory")
; #define PG8_BAR __builtin_amdgcn_s_barrier()
; #define PG8_SCHED __builtin_amdgcn_sched_barrier(0)
; template <class Epi, class Sched, bool ALIGN_EPI = true, bool SP2 = true>
; __device__ __forceinline__ void gemm_phase(LAS unsigned char* lds, const bf16_t* Ag, const bf16_t* Btg, const int K, const int lda, const int ldb, const Sched& S, const Epi& E) {
;     ...
;             const bool last = (t == nt - 2);
;             const char* a1 = cA + (size_t)(t + 1) * kstep;
;             const char* a2 = last ? nA : cA + (size_t)(t + 2) * kstep; const char* b2 = last ? nB : cB + (size_t)(t + 2) * kstep;
;             const char* a3 = a2 + kstep; const char* b3 = b2 + kstep;
;             if constexpr (SP2) {
;             PG8_LDB(B0, 0, 0); PG8_LDB(B1, 0, 1); PG8_SCHED; PG8_LDA(At, 0, 0); PG8_STAGE(PG8_SA(1, 1), a1 + hstepA, voffA);
;             PG8_WAIT_V(8); PG8_WAIT_L(0); PG8_BAR; PG8_MMA(0, 0, At, B0); PG8_MMA(0, 1, At, B1); PG8_BAR; PG8_SCHED;
;             PG8_LDA(At, 0, 1); PG8_STAGE(PG8_SB(0, 0), b2, voffB); PG8_STAGE(PG8_SB(0, 1), b2 + hstepB, voffB); PG8_STAGE(PG8_SA(0, 0), a2, voffA);
.LBB0_387:
	ds_read_b128 v[80:83], v182
	ds_read_b128 v[84:87], v182 offset:1024
	ds_read_b128 v[136:139], v182 offset:2048
	ds_read_b128 v[140:143], v182 offset:3072
	ds_read_b128 v[164:167], v183
	ds_read_b128 v[168:171], v183 offset:1024
	ds_read_b128 v[172:175], v183 offset:2048
	ds_read_b128 v[186:189], v183 offset:3072
	s_add_u32 s6, s4, 0xfff80080
	s_addc_u32 s7, s5, -1
	s_cmp_eq_u32 s38, 28
	s_cselect_b32 s35, s1, s7
	s_cselect_b32 s34, s9, s6
	s_cselect_b32 s7, s15, s33
	s_cselect_b32 s6, s21, s23
	v_lshl_add_u64 v[222:223], s[4:5], 0, v[156:157]
	s_add_i32 m0, s54, 0xc000
	ds_read_b128 v[190:193], v184
	ds_read_b128 v[194:197], v184 offset:1024
	ds_read_b128 v[198:201], v184 offset:2048
	ds_read_b128 v[202:205], v184 offset:3072
	ds_read_b128 v[206:209], v184 offset:4096
	ds_read_b128 v[210:213], v184 offset:5120
	ds_read_b128 v[214:217], v184 offset:6144
	ds_read_b128 v[218:221], v184 offset:7168
	global_load_lds_dwordx4 v[222:223], off
	v_lshl_add_u64 v[222:223], s[4:5], 0, v[158:159]
	s_add_i32 m0, s54, 0xe000
	s_nop 0
	global_load_lds_dwordx4 v[222:223], off
	s_waitcnt vmcnt(8)
	s_waitcnt lgkmcnt(0)
	s_barrier
	s_setprio 1
	s_waitcnt lgkmcnt(0)
	v_mfma_f32_16x16x32_bf16 v[132:135], v[80:83], v[190:193], v[132:135]
	v_mfma_f32_16x16x32_bf16 v[128:131], v[136:139], v[190:193], v[128:131]
	v_mfma_f32_16x16x32_bf16 v[124:127], v[80:83], v[198:201], v[124:127]
	v_mfma_f32_16x16x32_bf16 v[120:123], v[136:139], v[198:201], v[120:123]
	v_mfma_f32_16x16x32_bf16 v[116:119], v[80:83], v[206:209], v[116:119]
	v_mfma_f32_16x16x32_bf16 v[112:115], v[136:139], v[206:209], v[112:115]
	v_mfma_f32_16x16x32_bf16 v[108:111], v[80:83], v[214:217], v[108:111]
	v_mfma_f32_16x16x32_bf16 v[104:107], v[136:139], v[214:217], v[104:107]
	v_mfma_f32_16x16x32_bf16 v[132:135], v[84:87], v[194:197], v[132:135]
	v_mfma_f32_16x16x32_bf16 v[128:131], v[140:143], v[194:197], v[128:131]
	v_mfma_f32_16x16x32_bf16 v[124:127], v[84:87], v[202:205], v[124:127]
	v_mfma_f32_16x16x32_bf16 v[120:123], v[140:143], v[202:205], v[120:123]
	v_mfma_f32_16x16x32_bf16 v[116:119], v[84:87], v[210:213], v[116:119]
	v_mfma_f32_16x16x32_bf16 v[112:115], v[140:143], v[210:213], v[112:115]
	v_mfma_f32_16x16x32_bf16 v[108:111], v[84:87], v[218:221], v[108:111]
	v_mfma_f32_16x16x32_bf16 v[104:107], v[140:143], v[218:221], v[104:107]
	s_setprio 0
	s_setprio 1
	v_mfma_f32_16x16x32_bf16 v[60:63], v[164:167], v[190:193], v[60:63]
	v_mfma_f32_16x16x32_bf16 v[56:59], v[172:175], v[190:193], v[56:59]
	v_mfma_f32_16x16x32_bf16 v[52:55], v[164:167], v[198:201], v[52:55]
	v_mfma_f32_16x16x32_bf16 v[48:51], v[172:175], v[198:201], v[48:51]
	v_mfma_f32_16x16x32_bf16 v[44:47], v[164:167], v[206:209], v[44:47]
	v_mfma_f32_16x16x32_bf16 v[40:43], v[172:175], v[206:209], v[40:43]
	v_mfma_f32_16x16x32_bf16 v[36:39], v[164:167], v[214:217], v[36:39]
	v_mfma_f32_16x16x32_bf16 v[32:35], v[172:175], v[214:217], v[32:35]
	v_mfma_f32_16x16x32_bf16 v[60:63], v[168:171], v[194:197], v[60:63]
	v_mfma_f32_16x16x32_bf16 v[56:59], v[186:189], v[194:197], v[56:59]
	v_mfma_f32_16x16x32_bf16 v[52:55], v[168:171], v[202:205], v[52:55]
	v_mfma_f32_16x16x32_bf16 v[48:51], v[186:189], v[202:205], v[48:51]
	v_mfma_f32_16x16x32_bf16 v[44:47], v[168:171], v[210:213], v[44:47]
	v_mfma_f32_16x16x32_bf16 v[40:43], v[186:189], v[210:213], v[40:43]
	s_setprio 2
	s_barrier
	v_mfma_f32_16x16x32_bf16 v[36:39], v[168:171], v[218:221], v[36:39]
	v_mfma_f32_16x16x32_bf16 v[32:35], v[186:189], v[218:221], v[32:35]
	s_setprio 0
	s_add_i32 s39, s84, s37
	v_lshl_add_u64 v[222:223], s[6:7], 0, v[146:147]
	s_mov_b32 m0, s39
	ds_read_b128 v[190:193], v184 offset:16384
	ds_read_b128 v[194:197], v184 offset:17408
	ds_read_b128 v[198:201], v184 offset:18432
	ds_read_b128 v[202:205], v184 offset:19456
	ds_read_b128 v[206:209], v184 offset:20480
	ds_read_b128 v[210:213], v184 offset:21504
	ds_read_b128 v[214:217], v184 offset:22528
	ds_read_b128 v[218:221], v184 offset:23552
	global_load_lds_dwordx4 v[222:223], off
	s_add_i32 m0, s39, 0x2000
	s_add_u32 s46, s6, 0x80000
	v_lshl_add_u64 v[224:225], s[6:7], 0, v[150:151]
	s_addc_u32 s47, s7, 0
	s_add_i32 s39, s85, s37
	global_load_lds_dwordx4 v[224:225], off
	v_lshl_add_u64 v[226:227], s[46:47], 0, v[146:147]
	s_mov_b32 m0, s39
	v_lshl_add_u64 v[228:229], s[34:35], 0, v[148:149]
	global_load_lds_dwordx4 v[226:227], off
	v_lshl_add_u64 v[226:227], s[46:47], 0, v[150:151]
	s_add_i32 m0, s39, 0x2000
	s_nop 0
	global_load_lds_dwordx4 v[226:227], off
	v_lshl_add_u64 v[226:227], s[34:35], 0, v[144:145]
	s_mov_b32 m0, s54
	s_nop 0
	global_load_lds_dwordx4 v[226:227], off
	s_mov_b32 m0, s55
	s_nop 0
	global_load_lds_dwordx4 v[228:229], off
	s_waitcnt vmcnt(8)
	s_waitcnt lgkmcnt(0)
	s_barrier
; #define PG8_STAGE(bufoff, gbase, voff) do { _Pragma("unroll") for (int _i = 0; _i < 2; ++_i) \
;         __builtin_amdgcn_global_load_lds((const unsigned*)((const char*)(gbase) + (voff)[_i]), (LAS unsigned*)(lds + (bufoff) + ldsw + _i * 8192), 16, 0, 0); } while (0)
; #define PG8_LDA(dst, b, h) do { _Pragma("unroll") for (int m = 0; m < 4; ++m) _Pragma("unroll") for (int k = 0; k < 2; ++k) dst[m][k] = *(const LAS bf16x8*)(lds + PG8_SA(b, h) + aoff + m * 2048 + k * 1024); } while (0)
; #define PG8_LDB(dst, b, h) do { _Pragma("unroll") for (int n = 0; n < 2; ++n) _Pragma("unroll") for (int k = 0; k < 2; ++k) dst[n][k] = *(const LAS bf16x8*)(lds + PG8_SB(b, h) + boff + n * 2048 + k * 1024); } while (0)
; #define PG8_MMA(ai, bj, At, Bt) do { __builtin_amdgcn_s_setprio(1); _Pragma("unroll") for (int m = 0; m < 4; ++m) _Pragma("unroll") for (int n = 0; n < 2; ++n) _Pragma("unroll") for (int k = 0; k < 2; ++k) \
;         acc[ai][bj][m][n] = __builtin_amdgcn_mfma_f32_16x16x32_bf16(Bt[n][k], At[m][k], acc[ai][bj][m][n], 0, 0, 0); __builtin_amdgcn_s_setprio(0); } while (0)
; #define PG8_WAIT_V(n) asm volatile("s_waitcnt vmcnt(" #n ")" ::: "memory")
; #define PG8_WAIT_L(n) asm volatile("s_waitcnt lgkmcnt(" #n ")" ::: "memory")
; #define PG8_BAR __builtin_amdgcn_s_barrier()
; #define PG8_SCHED __builtin_amdgcn_sched_barrier(0)
; template <class Epi, class Sched, bool ALIGN_EPI = true, bool SP2 = true>
; __device__ __forceinline__ void gemm_phase(LAS unsigned char* lds, const bf16_t* Ag, const bf16_t* Btg, const int K, const int lda, const int ldb, const Sched& S, const Epi& E) {
;     ...
;             PG8_WAIT_V(8); PG8_WAIT_L(0); PG8_BAR; PG8_MMA(1, 0, At, B0); PG8_MMA(1, 1, At, B1); PG8_BAR; PG8_SCHED;
;             PG8_LDB(B0, 1, 0); PG8_LDB(B1, 1, 1); PG8_SCHED; PG8_LDA(At, 1, 0); PG8_STAGE(PG8_SA(0, 1), a2 + hstepA, voffA);
;             PG8_WAIT_V(8); PG8_WAIT_L(0); PG8_BAR; PG8_MMA(0, 0, At, B0); PG8_MMA(0, 1, At, B1); PG8_BAR; PG8_SCHED;
	s_setprio 1
	s_waitcnt lgkmcnt(0)
	v_mfma_f32_16x16x32_bf16 v[100:103], v[80:83], v[190:193], v[100:103]
	v_mfma_f32_16x16x32_bf16 v[96:99], v[136:139], v[190:193], v[96:99]
	v_mfma_f32_16x16x32_bf16 v[92:95], v[80:83], v[198:201], v[92:95]
	v_mfma_f32_16x16x32_bf16 v[88:91], v[136:139], v[198:201], v[88:91]
	v_mfma_f32_16x16x32_bf16 v[76:79], v[80:83], v[206:209], v[76:79]
	v_mfma_f32_16x16x32_bf16 v[72:75], v[136:139], v[206:209], v[72:75]
	v_mfma_f32_16x16x32_bf16 v[68:71], v[80:83], v[214:217], v[68:71]
	v_mfma_f32_16x16x32_bf16 v[64:67], v[136:139], v[214:217], v[64:67]
	v_mfma_f32_16x16x32_bf16 v[100:103], v[84:87], v[194:197], v[100:103]
	v_mfma_f32_16x16x32_bf16 v[96:99], v[140:143], v[194:197], v[96:99]
	v_mfma_f32_16x16x32_bf16 v[92:95], v[84:87], v[202:205], v[92:95]
	v_mfma_f32_16x16x32_bf16 v[88:91], v[140:143], v[202:205], v[88:91]
	v_mfma_f32_16x16x32_bf16 v[76:79], v[84:87], v[210:213], v[76:79]
	v_mfma_f32_16x16x32_bf16 v[72:75], v[140:143], v[210:213], v[72:75]
	v_mfma_f32_16x16x32_bf16 v[68:71], v[84:87], v[218:221], v[68:71]
	v_mfma_f32_16x16x32_bf16 v[64:67], v[140:143], v[218:221], v[64:67]
	s_setprio 0
	s_setprio 1
	v_mfma_f32_16x16x32_bf16 v[28:31], v[164:167], v[190:193], v[28:31]
	v_mfma_f32_16x16x32_bf16 v[24:27], v[172:175], v[190:193], v[24:27]
	v_mfma_f32_16x16x32_bf16 v[20:23], v[164:167], v[198:201], v[20:23]
	v_mfma_f32_16x16x32_bf16 v[16:19], v[172:175], v[198:201], v[16:19]
	v_mfma_f32_16x16x32_bf16 v[12:15], v[164:167], v[206:209], v[12:15]
	v_mfma_f32_16x16x32_bf16 v[8:11], v[172:175], v[206:209], v[8:11]
	v_mfma_f32_16x16x32_bf16 v[4:7], v[164:167], v[214:217], v[4:7]
	v_mfma_f32_16x16x32_bf16 v[0:3], v[172:175], v[214:217], v[0:3]
	v_mfma_f32_16x16x32_bf16 v[28:31], v[168:171], v[194:197], v[28:31]
	v_mfma_f32_16x16x32_bf16 v[24:27], v[186:189], v[194:197], v[24:27]
	v_mfma_f32_16x16x32_bf16 v[20:23], v[168:171], v[202:205], v[20:23]
	v_mfma_f32_16x16x32_bf16 v[16:19], v[186:189], v[202:205], v[16:19]
	v_mfma_f32_16x16x32_bf16 v[12:15], v[168:171], v[210:213], v[12:15]
	v_mfma_f32_16x16x32_bf16 v[8:11], v[186:189], v[210:213], v[8:11]
	s_setprio 2
	s_barrier
	v_mfma_f32_16x16x32_bf16 v[4:7], v[168:171], v[218:221], v[4:7]
	v_mfma_f32_16x16x32_bf16 v[0:3], v[186:189], v[218:221], v[0:3]
	s_setprio 0
	s_add_i32 s39, 0, 0x18000
	s_add_i32 s40, 0, 0x1c000
	v_add_u32_e32 v140, s39, v180
	v_add_u32_e32 v152, s40, v180
	ds_read_b128 v[80:83], v140
	ds_read_b128 v[84:87], v140 offset:1024
	ds_read_b128 v[136:139], v140 offset:2048
	ds_read_b128 v[140:143], v140 offset:3072
	ds_read_b128 v[164:167], v152
	ds_read_b128 v[168:171], v152 offset:1024
	ds_read_b128 v[172:175], v152 offset:2048
	ds_read_b128 v[186:189], v152 offset:3072
	s_add_u32 s34, s34, 0x80000
	s_addc_u32 s35, s35, 0
	s_mov_b32 m0, s58
	v_lshl_add_u64 v[230:231], s[34:35], 0, v[144:145]
	ds_read_b128 v[190:193], v184 offset:32768
	ds_read_b128 v[194:197], v184 offset:33792
	ds_read_b128 v[198:201], v184 offset:34816
	ds_read_b128 v[202:205], v184 offset:35840
	ds_read_b128 v[206:209], v184 offset:36864
	ds_read_b128 v[210:213], v184 offset:37888
	ds_read_b128 v[214:217], v184 offset:38912
	ds_read_b128 v[218:221], v184 offset:39936
	global_load_lds_dwordx4 v[230:231], off
	v_lshl_add_u64 v[230:231], s[34:35], 0, v[148:149]
	s_mov_b32 m0, s59
	s_nop 0
	global_load_lds_dwordx4 v[230:231], off
	s_waitcnt vmcnt(8)
	s_waitcnt lgkmcnt(0)
	s_barrier
	s_setprio 1
	s_waitcnt lgkmcnt(0)
	v_mfma_f32_16x16x32_bf16 v[132:135], v[80:83], v[190:193], v[132:135]
	v_mfma_f32_16x16x32_bf16 v[128:131], v[136:139], v[190:193], v[128:131]
	v_mfma_f32_16x16x32_bf16 v[124:127], v[80:83], v[198:201], v[124:127]
	v_mfma_f32_16x16x32_bf16 v[120:123], v[136:139], v[198:201], v[120:123]
	v_mfma_f32_16x16x32_bf16 v[116:119], v[80:83], v[206:209], v[116:119]
	v_mfma_f32_16x16x32_bf16 v[112:115], v[136:139], v[206:209], v[112:115]
	v_mfma_f32_16x16x32_bf16 v[108:111], v[80:83], v[214:217], v[108:111]
	v_mfma_f32_16x16x32_bf16 v[104:107], v[136:139], v[214:217], v[104:107]
	v_mfma_f32_16x16x32_bf16 v[132:135], v[84:87], v[194:197], v[132:135]
	v_mfma_f32_16x16x32_bf16 v[128:131], v[140:143], v[194:197], v[128:131]
	v_mfma_f32_16x16x32_bf16 v[124:127], v[84:87], v[202:205], v[124:127]
	v_mfma_f32_16x16x32_bf16 v[120:123], v[140:143], v[202:205], v[120:123]
	v_mfma_f32_16x16x32_bf16 v[116:119], v[84:87], v[210:213], v[116:119]
	v_mfma_f32_16x16x32_bf16 v[112:115], v[140:143], v[210:213], v[112:115]
	v_mfma_f32_16x16x32_bf16 v[108:111], v[84:87], v[218:221], v[108:111]
	v_mfma_f32_16x16x32_bf16 v[104:107], v[140:143], v[218:221], v[104:107]
	s_setprio 0
	s_setprio 1
	v_mfma_f32_16x16x32_bf16 v[60:63], v[164:167], v[190:193], v[60:63]
	v_mfma_f32_16x16x32_bf16 v[56:59], v[172:175], v[190:193], v[56:59]
	v_mfma_f32_16x16x32_bf16 v[52:55], v[164:167], v[198:201], v[52:55]
	v_mfma_f32_16x16x32_bf16 v[48:51], v[172:175], v[198:201], v[48:51]
	v_mfma_f32_16x16x32_bf16 v[44:47], v[164:167], v[206:209], v[44:47]
	v_mfma_f32_16x16x32_bf16 v[40:43], v[172:175], v[206:209], v[40:43]
	v_mfma_f32_16x16x32_bf16 v[36:39], v[164:167], v[214:217], v[36:39]
	v_mfma_f32_16x16x32_bf16 v[32:35], v[172:175], v[214:217], v[32:35]
	v_mfma_f32_16x16x32_bf16 v[60:63], v[168:171], v[194:197], v[60:63]
	v_mfma_f32_16x16x32_bf16 v[56:59], v[186:189], v[194:197], v[56:59]
	v_mfma_f32_16x16x32_bf16 v[52:55], v[168:171], v[202:205], v[52:55]
	v_mfma_f32_16x16x32_bf16 v[48:51], v[186:189], v[202:205], v[48:51]
	v_mfma_f32_16x16x32_bf16 v[44:47], v[168:171], v[210:213], v[44:47]
	v_mfma_f32_16x16x32_bf16 v[40:43], v[186:189], v[210:213], v[40:43]
	s_setprio 2
	s_barrier
; #define PG8_STAGE(bufoff, gbase, voff) do { _Pragma("unroll") for (int _i = 0; _i < 2; ++_i) \
;         __builtin_amdgcn_global_load_lds((const unsigned*)((const char*)(gbase) + (voff)[_i]), (LAS unsigned*)(lds + (bufoff) + ldsw + _i * 8192), 16, 0, 0); } while (0)
; #define PG8_LDA(dst, b, h) do { _Pragma("unroll") for (int m = 0; m < 4; ++m) _Pragma("unroll") for (int k = 0; k < 2; ++k) dst[m][k] = *(const LAS bf16x8*)(lds + PG8_SA(b, h) + aoff + m * 2048 + k * 1024); } while (0)
; #define PG8_MMA(ai, bj, At, Bt) do { __builtin_amdgcn_s_setprio(1); _Pragma("unroll") for (int m = 0; m < 4; ++m) _Pragma("unroll") for (int n = 0; n < 2; ++n) _Pragma("unroll") for (int k = 0; k < 2; ++k) \
;         acc[ai][bj][m][n] = __builtin_amdgcn_mfma_f32_16x16x32_bf16(Bt[n][k], At[m][k], acc[ai][bj][m][n], 0, 0, 0); __builtin_amdgcn_s_setprio(0); } while (0)
; #define PG8_WAIT_V(n) asm volatile("s_waitcnt vmcnt(" #n ")" ::: "memory")
; #define PG8_WAIT_L(n) asm volatile("s_waitcnt lgkmcnt(" #n ")" ::: "memory")
; #define PG8_BAR __builtin_amdgcn_s_barrier()
; #define PG8_SCHED __builtin_amdgcn_sched_barrier(0)
; template <class Epi, class Sched, bool ALIGN_EPI = true, bool SP2 = true>
; __device__ __forceinline__ void gemm_phase(LAS unsigned char* lds, const bf16_t* Ag, const bf16_t* Btg, const int K, const int lda, const int ldb, const Sched& S, const Epi& E) {
;     ...
;             PG8_LDA(At, 1, 1); PG8_STAGE(PG8_SB(1, 0), b3, voffB); PG8_STAGE(PG8_SB(1, 1), b3 + hstepB, voffB); PG8_STAGE(PG8_SA(1, 0), a3, voffA);
;             PG8_WAIT_V(8); PG8_WAIT_L(0); PG8_BAR; PG8_MMA(1, 0, At, B0); PG8_MMA(1, 1, At, B1); PG8_BAR; PG8_SCHED;
	v_mfma_f32_16x16x32_bf16 v[36:39], v[168:171], v[218:221], v[36:39]
	v_mfma_f32_16x16x32_bf16 v[32:35], v[186:189], v[218:221], v[32:35]
	s_setprio 0
	s_add_i32 s34, s39, s37
	v_lshl_add_u64 v[222:223], v[222:223], 0, s[16:17]
	s_mov_b32 m0, s34
	ds_read_b128 v[190:193], v184 offset:49152
	ds_read_b128 v[194:197], v184 offset:50176
	ds_read_b128 v[198:201], v184 offset:51200
	ds_read_b128 v[202:205], v184 offset:52224
	ds_read_b128 v[206:209], v184 offset:53248
	ds_read_b128 v[210:213], v184 offset:54272
	ds_read_b128 v[214:217], v184 offset:55296
	ds_read_b128 v[218:221], v184 offset:56320
	global_load_lds_dwordx4 v[222:223], off
	s_add_i32 m0, s34, 0x2000
	s_add_u32 s6, s6, 0x80080
	v_lshl_add_u64 v[222:223], v[224:225], 0, s[16:17]
	s_addc_u32 s7, s7, 0
	s_add_i32 s34, s40, s37
	global_load_lds_dwordx4 v[222:223], off
	v_lshl_add_u64 v[222:223], s[6:7], 0, v[146:147]
	s_mov_b32 m0, s34
	s_nop 0
	global_load_lds_dwordx4 v[222:223], off
	v_lshl_add_u64 v[222:223], s[6:7], 0, v[150:151]
	s_add_i32 m0, s34, 0x2000
	s_nop 0
	global_load_lds_dwordx4 v[222:223], off
	v_lshl_add_u64 v[222:223], v[226:227], 0, s[16:17]
	s_mov_b32 m0, s61
	s_nop 0
	global_load_lds_dwordx4 v[222:223], off
	v_lshl_add_u64 v[222:223], v[228:229], 0, s[16:17]
	s_mov_b32 m0, s70
	s_nop 0
	global_load_lds_dwordx4 v[222:223], off
	s_waitcnt vmcnt(8)
	s_waitcnt lgkmcnt(0)
	s_barrier
	s_setprio 1
	s_waitcnt lgkmcnt(0)
	v_mfma_f32_16x16x32_bf16 v[100:103], v[80:83], v[190:193], v[100:103]
	v_mfma_f32_16x16x32_bf16 v[96:99], v[136:139], v[190:193], v[96:99]
	v_mfma_f32_16x16x32_bf16 v[92:95], v[80:83], v[198:201], v[92:95]
	v_mfma_f32_16x16x32_bf16 v[88:91], v[136:139], v[198:201], v[88:91]
	v_mfma_f32_16x16x32_bf16 v[76:79], v[80:83], v[206:209], v[76:79]
	v_mfma_f32_16x16x32_bf16 v[72:75], v[136:139], v[206:209], v[72:75]
	v_mfma_f32_16x16x32_bf16 v[68:71], v[80:83], v[214:217], v[68:71]
	v_mfma_f32_16x16x32_bf16 v[64:67], v[136:139], v[214:217], v[64:67]
	v_mfma_f32_16x16x32_bf16 v[100:103], v[84:87], v[194:197], v[100:103]
	v_mfma_f32_16x16x32_bf16 v[96:99], v[140:143], v[194:197], v[96:99]
	v_mfma_f32_16x16x32_bf16 v[92:95], v[84:87], v[202:205], v[92:95]
	v_mfma_f32_16x16x32_bf16 v[88:91], v[140:143], v[202:205], v[88:91]
	v_mfma_f32_16x16x32_bf16 v[76:79], v[84:87], v[210:213], v[76:79]
	v_mfma_f32_16x16x32_bf16 v[72:75], v[140:143], v[210:213], v[72:75]
	v_mfma_f32_16x16x32_bf16 v[68:71], v[84:87], v[218:221], v[68:71]
	v_mfma_f32_16x16x32_bf16 v[64:67], v[140:143], v[218:221], v[64:67]
	s_setprio 0
	s_setprio 1
	v_mfma_f32_16x16x32_bf16 v[28:31], v[164:167], v[190:193], v[28:31]
	v_mfma_f32_16x16x32_bf16 v[24:27], v[172:175], v[190:193], v[24:27]
	v_mfma_f32_16x16x32_bf16 v[20:23], v[164:167], v[198:201], v[20:23]
	v_mfma_f32_16x16x32_bf16 v[16:19], v[172:175], v[198:201], v[16:19]
	v_mfma_f32_16x16x32_bf16 v[12:15], v[164:167], v[206:209], v[12:15]
	v_mfma_f32_16x16x32_bf16 v[8:11], v[172:175], v[206:209], v[8:11]
	v_mfma_f32_16x16x32_bf16 v[4:7], v[164:167], v[214:217], v[4:7]
	v_mfma_f32_16x16x32_bf16 v[0:3], v[172:175], v[214:217], v[0:3]
	v_mfma_f32_16x16x32_bf16 v[28:31], v[168:171], v[194:197], v[28:31]
	v_mfma_f32_16x16x32_bf16 v[24:27], v[186:189], v[194:197], v[24:27]
	v_mfma_f32_16x16x32_bf16 v[20:23], v[168:171], v[202:205], v[20:23]
	v_mfma_f32_16x16x32_bf16 v[16:19], v[186:189], v[202:205], v[16:19]
	v_mfma_f32_16x16x32_bf16 v[12:15], v[168:171], v[210:213], v[12:15]
	v_mfma_f32_16x16x32_bf16 v[8:11], v[186:189], v[210:213], v[8:11]
	s_setprio 2
	s_barrier
	v_mfma_f32_16x16x32_bf16 v[4:7], v[168:171], v[218:221], v[4:7]
	v_mfma_f32_16x16x32_bf16 v[0:3], v[186:189], v[218:221], v[0:3]
	s_setprio 0
	s_add_i32 s38, s38, 2
	s_add_u32 s4, s4, 0x100
	s_addc_u32 s5, s5, 0
	s_add_u32 s23, s23, 0x100
	s_addc_u32 s33, s33, 0
	s_cmp_gt_u32 s38, 29
	s_cbranch_scc0 .LBB0_387
	s_and_b64 vcc, exec, s[18:19]
	s_cbranch_vccz .LBB0_390
	s_barrier

; #define PG8_STAGE(bufoff, gbase, voff) do { _Pragma("unroll") for (int _i = 0; _i < 2; ++_i) \
;         __builtin_amdgcn_global_load_lds((const unsigned*)((const char*)(gbase) + (voff)[_i]), (LAS unsigned*)(lds + (bufoff) + ldsw + _i * 8192), 16, 0, 0); } while (0)
; #define PG8_LDA(dst, b, h) do { _Pragma("unroll") for (int m = 0; m < 4; ++m) _Pragma("unroll") for (int k = 0; k < 2; ++k) dst[m][k] = *(const LAS bf16x8*)(lds + PG8_SA(b, h) + aoff + m * 2048 + k * 1024); } while (0)
; #define PG8_LDB(dst, b, h) do { _Pragma("unroll") for (int n = 0; n < 2; ++n) _Pragma("unroll") for (int k = 0; k < 2; ++k) dst[n][k] = *(const LAS bf16x8*)(lds + PG8_SB(b, h) + boff + n * 2048 + k * 1024); } while (0)
; #define PG8_MMA(ai, bj, At, Bt) do { __builtin_amdgcn_s_setprio(1); _Pragma("unroll") for (int m = 0; m < 4; ++m) _Pragma("unroll") for (int n = 0; n < 2; ++n) _Pragma("unroll") for (int k = 0; k < 2; ++k) \
;         acc[ai][bj][m][n] = __builtin_amdgcn_mfma_f32_16x16x32_bf16(Bt[n][k], At[m][k], acc[ai][bj][m][n], 0, 0, 0); __builtin_amdgcn_s_setprio(0); } while (0)
; #define PG8_WAIT_V(n) asm volatile("s_waitcnt vmcnt(" #n ")" ::: "memory")
; #define PG8_WAIT_L(n) asm volatile("s_waitcnt lgkmcnt(" #n ")" ::: "memory")
; #define PG8_BAR __builtin_amdgcn_s_barrier()
; #define PG8_SCHED __builtin_amdgcn_sched_barrier(0)
; template <class Epi, class Sched, bool ALIGN_EPI = true, bool SP2 = true>
; __device__ __forceinline__ void gemm_phase(LAS unsigned char* lds, const bf16_t* Ag, const bf16_t* Btg, const int K, const int lda, const int ldb, const Sched& S, const Epi& E) {
;     ...
;             const bool last = (t == nt - 2);
;             const char* a1 = cA + (size_t)(t + 1) * kstep;
;             const char* a2 = last ? nA : cA + (size_t)(t + 2) * kstep; const char* b2 = last ? nB : cB + (size_t)(t + 2) * kstep;
;             const char* a3 = a2 + kstep; const char* b3 = b2 + kstep;
;             if constexpr (SP2) {
;             PG8_LDB(B0, 0, 0); PG8_LDB(B1, 0, 1); PG8_SCHED; PG8_LDA(At, 0, 0); PG8_STAGE(PG8_SA(1, 1), a1 + hstepA, voffA);
;             PG8_WAIT_V(8); PG8_WAIT_L(0); PG8_BAR; PG8_MMA(0, 0, At, B0); PG8_MMA(0, 1, At, B1); PG8_BAR; PG8_SCHED;
;             PG8_LDA(At, 0, 1); PG8_STAGE(PG8_SB(0, 0), b2, voffB); PG8_STAGE(PG8_SB(0, 1), b2 + hstepB, voffB); PG8_STAGE(PG8_SA(0, 0), a2, voffA);
.LBB0_787:
	ds_read_b128 v[108:111], v170
	ds_read_b128 v[112:115], v170 offset:1024
	ds_read_b128 v[154:157], v170 offset:2048
	ds_read_b128 v[158:161], v170 offset:3072
	ds_read_b128 v[162:165], v171
	ds_read_b128 v[180:183], v171 offset:1024
	ds_read_b128 v[184:187], v171 offset:2048
	ds_read_b128 v[188:191], v171 offset:3072
	s_add_u32 s26, s24, 0xfff80080
	s_addc_u32 s27, s25, -1
	s_cmp_eq_u32 s53, 28
	s_cselect_b32 s29, s11, s27
	s_cselect_b32 s28, s13, s26
	s_cselect_b32 s27, s33, s52
	s_cselect_b32 s26, s50, s51
	v_lshl_add_u64 v[174:175], s[24:25], 0, v[146:147]
	s_add_i32 m0, s37, 0xc000
	ds_read_b128 v[192:195], v172
	ds_read_b128 v[196:199], v172 offset:1024
	ds_read_b128 v[200:203], v172 offset:2048
	ds_read_b128 v[204:207], v172 offset:3072
	ds_read_b128 v[208:211], v172 offset:4096
	ds_read_b128 v[212:215], v172 offset:5120
	ds_read_b128 v[216:219], v172 offset:6144
	ds_read_b128 v[220:223], v172 offset:7168
	global_load_lds_dwordx4 v[174:175], off
	v_lshl_add_u64 v[174:175], s[24:25], 0, v[148:149]
	s_add_i32 m0, s37, 0xe000
	s_nop 0
	global_load_lds_dwordx4 v[174:175], off
	s_waitcnt vmcnt(8)
	s_waitcnt lgkmcnt(0)
	s_barrier
	s_setprio 1
	s_waitcnt lgkmcnt(0)
	v_mfma_f32_16x16x32_bf16 v[132:135], v[108:111], v[192:195], v[132:135]
	v_mfma_f32_16x16x32_bf16 v[128:131], v[154:157], v[192:195], v[128:131]
	v_mfma_f32_16x16x32_bf16 v[124:127], v[108:111], v[200:203], v[124:127]
	v_mfma_f32_16x16x32_bf16 v[120:123], v[154:157], v[200:203], v[120:123]
	v_mfma_f32_16x16x32_bf16 v[116:119], v[108:111], v[208:211], v[116:119]
	v_mfma_f32_16x16x32_bf16 v[104:107], v[154:157], v[208:211], v[104:107]
	v_mfma_f32_16x16x32_bf16 v[100:103], v[108:111], v[216:219], v[100:103]
	v_mfma_f32_16x16x32_bf16 v[96:99], v[154:157], v[216:219], v[96:99]
	v_mfma_f32_16x16x32_bf16 v[132:135], v[112:115], v[196:199], v[132:135]
	v_mfma_f32_16x16x32_bf16 v[128:131], v[158:161], v[196:199], v[128:131]
	v_mfma_f32_16x16x32_bf16 v[124:127], v[112:115], v[204:207], v[124:127]
	v_mfma_f32_16x16x32_bf16 v[120:123], v[158:161], v[204:207], v[120:123]
	v_mfma_f32_16x16x32_bf16 v[116:119], v[112:115], v[212:215], v[116:119]
	v_mfma_f32_16x16x32_bf16 v[104:107], v[158:161], v[212:215], v[104:107]
	v_mfma_f32_16x16x32_bf16 v[100:103], v[112:115], v[220:223], v[100:103]
	v_mfma_f32_16x16x32_bf16 v[96:99], v[158:161], v[220:223], v[96:99]
	s_setprio 0
	s_setprio 1
	v_mfma_f32_16x16x32_bf16 v[60:63], v[162:165], v[192:195], v[60:63]
	v_mfma_f32_16x16x32_bf16 v[56:59], v[184:187], v[192:195], v[56:59]
	v_mfma_f32_16x16x32_bf16 v[52:55], v[162:165], v[200:203], v[52:55]
	v_mfma_f32_16x16x32_bf16 v[48:51], v[184:187], v[200:203], v[48:51]
	v_mfma_f32_16x16x32_bf16 v[44:47], v[162:165], v[208:211], v[44:47]
	v_mfma_f32_16x16x32_bf16 v[40:43], v[184:187], v[208:211], v[40:43]
	v_mfma_f32_16x16x32_bf16 v[36:39], v[162:165], v[216:219], v[36:39]
	v_mfma_f32_16x16x32_bf16 v[32:35], v[184:187], v[216:219], v[32:35]
	v_mfma_f32_16x16x32_bf16 v[60:63], v[180:183], v[196:199], v[60:63]
	v_mfma_f32_16x16x32_bf16 v[56:59], v[188:191], v[196:199], v[56:59]
	v_mfma_f32_16x16x32_bf16 v[52:55], v[180:183], v[204:207], v[52:55]
	v_mfma_f32_16x16x32_bf16 v[48:51], v[188:191], v[204:207], v[48:51]
	v_mfma_f32_16x16x32_bf16 v[44:47], v[180:183], v[212:215], v[44:47]
	v_mfma_f32_16x16x32_bf16 v[40:43], v[188:191], v[212:215], v[40:43]
	s_setprio 2
	s_barrier
	v_mfma_f32_16x16x32_bf16 v[36:39], v[180:183], v[220:223], v[36:39]
	v_mfma_f32_16x16x32_bf16 v[32:35], v[188:191], v[220:223], v[32:35]
	s_setprio 0
	s_add_i32 s54, s46, s35
	v_lshl_add_u64 v[174:175], s[26:27], 0, v[138:139]
	s_mov_b32 m0, s54
	ds_read_b128 v[192:195], v172 offset:16384
	ds_read_b128 v[196:199], v172 offset:17408
	ds_read_b128 v[200:203], v172 offset:18432
	ds_read_b128 v[204:207], v172 offset:19456
	ds_read_b128 v[208:211], v172 offset:20480
	ds_read_b128 v[212:215], v172 offset:21504
	ds_read_b128 v[216:219], v172 offset:22528
	ds_read_b128 v[220:223], v172 offset:23552
	global_load_lds_dwordx4 v[174:175], off
	s_add_i32 m0, s54, 0x2000
	s_add_u32 s54, s26, 0x80000
	v_lshl_add_u64 v[224:225], s[26:27], 0, v[142:143]
	s_addc_u32 s55, s27, 0
	s_add_i32 s58, s47, s35
	global_load_lds_dwordx4 v[224:225], off
	v_lshl_add_u64 v[226:227], s[54:55], 0, v[138:139]
	s_mov_b32 m0, s58
	v_lshl_add_u64 v[228:229], s[28:29], 0, v[140:141]
	global_load_lds_dwordx4 v[226:227], off
	v_lshl_add_u64 v[226:227], s[54:55], 0, v[142:143]
	s_add_i32 m0, s58, 0x2000
	s_nop 0
	global_load_lds_dwordx4 v[226:227], off
	v_lshl_add_u64 v[226:227], s[28:29], 0, v[136:137]
	s_mov_b32 m0, s37
	s_nop 0
	global_load_lds_dwordx4 v[226:227], off
	s_mov_b32 m0, s38
	s_nop 0
	global_load_lds_dwordx4 v[228:229], off
	s_waitcnt vmcnt(8)
	s_waitcnt lgkmcnt(0)
	s_barrier
; #define PG8_STAGE(bufoff, gbase, voff) do { _Pragma("unroll") for (int _i = 0; _i < 2; ++_i) \
;         __builtin_amdgcn_global_load_lds((const unsigned*)((const char*)(gbase) + (voff)[_i]), (LAS unsigned*)(lds + (bufoff) + ldsw + _i * 8192), 16, 0, 0); } while (0)
; #define PG8_LDA(dst, b, h) do { _Pragma("unroll") for (int m = 0; m < 4; ++m) _Pragma("unroll") for (int k = 0; k < 2; ++k) dst[m][k] = *(const LAS bf16x8*)(lds + PG8_SA(b, h) + aoff + m * 2048 + k * 1024); } while (0)
; #define PG8_LDB(dst, b, h) do { _Pragma("unroll") for (int n = 0; n < 2; ++n) _Pragma("unroll") for (int k = 0; k < 2; ++k) dst[n][k] = *(const LAS bf16x8*)(lds + PG8_SB(b, h) + boff + n * 2048 + k * 1024); } while (0)
; #define PG8_MMA(ai, bj, At, Bt) do { __builtin_amdgcn_s_setprio(1); _Pragma("unroll") for (int m = 0; m < 4; ++m) _Pragma("unroll") for (int n = 0; n < 2; ++n) _Pragma("unroll") for (int k = 0; k < 2; ++k) \
;         acc[ai][bj][m][n] = __builtin_amdgcn_mfma_f32_16x16x32_bf16(Bt[n][k], At[m][k], acc[ai][bj][m][n], 0, 0, 0); __builtin_amdgcn_s_setprio(0); } while (0)
; #define PG8_WAIT_V(n) asm volatile("s_waitcnt vmcnt(" #n ")" ::: "memory")
; #define PG8_WAIT_L(n) asm volatile("s_waitcnt lgkmcnt(" #n ")" ::: "memory")
; #define PG8_BAR __builtin_amdgcn_s_barrier()
; #define PG8_SCHED __builtin_amdgcn_sched_barrier(0)
; template <class Epi, class Sched, bool ALIGN_EPI = true, bool SP2 = true>
; __device__ __forceinline__ void gemm_phase(LAS unsigned char* lds, const bf16_t* Ag, const bf16_t* Btg, const int K, const int lda, const int ldb, const Sched& S, const Epi& E) {
;     ...
;             PG8_WAIT_V(8); PG8_WAIT_L(0); PG8_BAR; PG8_MMA(1, 0, At, B0); PG8_MMA(1, 1, At, B1); PG8_BAR; PG8_SCHED;
;             PG8_LDB(B0, 1, 0); PG8_LDB(B1, 1, 1); PG8_SCHED; PG8_LDA(At, 1, 0); PG8_STAGE(PG8_SA(0, 1), a2 + hstepA, voffA);
;             PG8_WAIT_V(8); PG8_WAIT_L(0); PG8_BAR; PG8_MMA(0, 0, At, B0); PG8_MMA(0, 1, At, B1); PG8_BAR; PG8_SCHED;
	s_setprio 1
	s_waitcnt lgkmcnt(0)
	v_mfma_f32_16x16x32_bf16 v[92:95], v[108:111], v[192:195], v[92:95]
	v_mfma_f32_16x16x32_bf16 v[88:91], v[154:157], v[192:195], v[88:91]
	v_mfma_f32_16x16x32_bf16 v[84:87], v[108:111], v[200:203], v[84:87]
	v_mfma_f32_16x16x32_bf16 v[80:83], v[154:157], v[200:203], v[80:83]
	v_mfma_f32_16x16x32_bf16 v[76:79], v[108:111], v[208:211], v[76:79]
	v_mfma_f32_16x16x32_bf16 v[72:75], v[154:157], v[208:211], v[72:75]
	v_mfma_f32_16x16x32_bf16 v[68:71], v[108:111], v[216:219], v[68:71]
	v_mfma_f32_16x16x32_bf16 v[64:67], v[154:157], v[216:219], v[64:67]
	v_mfma_f32_16x16x32_bf16 v[92:95], v[112:115], v[196:199], v[92:95]
	v_mfma_f32_16x16x32_bf16 v[88:91], v[158:161], v[196:199], v[88:91]
	v_mfma_f32_16x16x32_bf16 v[84:87], v[112:115], v[204:207], v[84:87]
	v_mfma_f32_16x16x32_bf16 v[80:83], v[158:161], v[204:207], v[80:83]
	v_mfma_f32_16x16x32_bf16 v[76:79], v[112:115], v[212:215], v[76:79]
	v_mfma_f32_16x16x32_bf16 v[72:75], v[158:161], v[212:215], v[72:75]
	v_mfma_f32_16x16x32_bf16 v[68:71], v[112:115], v[220:223], v[68:71]
	v_mfma_f32_16x16x32_bf16 v[64:67], v[158:161], v[220:223], v[64:67]
	s_setprio 0
	s_setprio 1
	v_mfma_f32_16x16x32_bf16 v[28:31], v[162:165], v[192:195], v[28:31]
	v_mfma_f32_16x16x32_bf16 v[24:27], v[184:187], v[192:195], v[24:27]
	v_mfma_f32_16x16x32_bf16 v[20:23], v[162:165], v[200:203], v[20:23]
	v_mfma_f32_16x16x32_bf16 v[16:19], v[184:187], v[200:203], v[16:19]
	v_mfma_f32_16x16x32_bf16 v[12:15], v[162:165], v[208:211], v[12:15]
	v_mfma_f32_16x16x32_bf16 v[8:11], v[184:187], v[208:211], v[8:11]
	v_mfma_f32_16x16x32_bf16 v[4:7], v[162:165], v[216:219], v[4:7]
	v_mfma_f32_16x16x32_bf16 v[0:3], v[184:187], v[216:219], v[0:3]
	v_mfma_f32_16x16x32_bf16 v[28:31], v[180:183], v[196:199], v[28:31]
	v_mfma_f32_16x16x32_bf16 v[24:27], v[188:191], v[196:199], v[24:27]
	v_mfma_f32_16x16x32_bf16 v[20:23], v[180:183], v[204:207], v[20:23]
	v_mfma_f32_16x16x32_bf16 v[16:19], v[188:191], v[204:207], v[16:19]
	v_mfma_f32_16x16x32_bf16 v[12:15], v[180:183], v[212:215], v[12:15]
	v_mfma_f32_16x16x32_bf16 v[8:11], v[188:191], v[212:215], v[8:11]
	s_setprio 2
	s_barrier
	v_mfma_f32_16x16x32_bf16 v[4:7], v[180:183], v[220:223], v[4:7]
	v_mfma_f32_16x16x32_bf16 v[0:3], v[188:191], v[220:223], v[0:3]
	s_setprio 0
	s_add_i32 s54, 0, 0x18000
	s_add_i32 s55, 0, 0x1c000
	v_add_u32_e32 v158, s54, v168
	v_add_u32_e32 v173, s55, v168
	ds_read_b128 v[108:111], v158
	ds_read_b128 v[112:115], v158 offset:1024
	ds_read_b128 v[154:157], v158 offset:2048
	ds_read_b128 v[158:161], v158 offset:3072
	ds_read_b128 v[162:165], v173
	ds_read_b128 v[180:183], v173 offset:1024
	ds_read_b128 v[184:187], v173 offset:2048
	ds_read_b128 v[188:191], v173 offset:3072
	s_add_u32 s28, s28, 0x80000
	s_addc_u32 s29, s29, 0
	s_mov_b32 m0, s39
	v_lshl_add_u64 v[230:231], s[28:29], 0, v[136:137]
	ds_read_b128 v[192:195], v172 offset:32768
	ds_read_b128 v[196:199], v172 offset:33792
	ds_read_b128 v[200:203], v172 offset:34816
	ds_read_b128 v[204:207], v172 offset:35840
	ds_read_b128 v[208:211], v172 offset:36864
	ds_read_b128 v[212:215], v172 offset:37888
	ds_read_b128 v[216:219], v172 offset:38912
	ds_read_b128 v[220:223], v172 offset:39936
	global_load_lds_dwordx4 v[230:231], off
	v_lshl_add_u64 v[230:231], s[28:29], 0, v[140:141]
	s_mov_b32 m0, s40
	s_nop 0
	global_load_lds_dwordx4 v[230:231], off
	s_waitcnt vmcnt(8)
	s_waitcnt lgkmcnt(0)
	s_barrier
	s_setprio 1
	s_waitcnt lgkmcnt(0)
	v_mfma_f32_16x16x32_bf16 v[132:135], v[108:111], v[192:195], v[132:135]
	v_mfma_f32_16x16x32_bf16 v[128:131], v[154:157], v[192:195], v[128:131]
	v_mfma_f32_16x16x32_bf16 v[124:127], v[108:111], v[200:203], v[124:127]
	v_mfma_f32_16x16x32_bf16 v[120:123], v[154:157], v[200:203], v[120:123]
	v_mfma_f32_16x16x32_bf16 v[116:119], v[108:111], v[208:211], v[116:119]
	v_mfma_f32_16x16x32_bf16 v[104:107], v[154:157], v[208:211], v[104:107]
	v_mfma_f32_16x16x32_bf16 v[100:103], v[108:111], v[216:219], v[100:103]
	v_mfma_f32_16x16x32_bf16 v[96:99], v[154:157], v[216:219], v[96:99]
	v_mfma_f32_16x16x32_bf16 v[132:135], v[112:115], v[196:199], v[132:135]
	v_mfma_f32_16x16x32_bf16 v[128:131], v[158:161], v[196:199], v[128:131]
	v_mfma_f32_16x16x32_bf16 v[124:127], v[112:115], v[204:207], v[124:127]
	v_mfma_f32_16x16x32_bf16 v[120:123], v[158:161], v[204:207], v[120:123]
	v_mfma_f32_16x16x32_bf16 v[116:119], v[112:115], v[212:215], v[116:119]
	v_mfma_f32_16x16x32_bf16 v[104:107], v[158:161], v[212:215], v[104:107]
	v_mfma_f32_16x16x32_bf16 v[100:103], v[112:115], v[220:223], v[100:103]
	v_mfma_f32_16x16x32_bf16 v[96:99], v[158:161], v[220:223], v[96:99]
	s_setprio 0
	s_setprio 1
	v_mfma_f32_16x16x32_bf16 v[60:63], v[162:165], v[192:195], v[60:63]
	v_mfma_f32_16x16x32_bf16 v[56:59], v[184:187], v[192:195], v[56:59]
	v_mfma_f32_16x16x32_bf16 v[52:55], v[162:165], v[200:203], v[52:55]
	v_mfma_f32_16x16x32_bf16 v[48:51], v[184:187], v[200:203], v[48:51]
	v_mfma_f32_16x16x32_bf16 v[44:47], v[162:165], v[208:211], v[44:47]
	v_mfma_f32_16x16x32_bf16 v[40:43], v[184:187], v[208:211], v[40:43]
	v_mfma_f32_16x16x32_bf16 v[36:39], v[162:165], v[216:219], v[36:39]
	v_mfma_f32_16x16x32_bf16 v[32:35], v[184:187], v[216:219], v[32:35]
	v_mfma_f32_16x16x32_bf16 v[60:63], v[180:183], v[196:199], v[60:63]
	v_mfma_f32_16x16x32_bf16 v[56:59], v[188:191], v[196:199], v[56:59]
	v_mfma_f32_16x16x32_bf16 v[52:55], v[180:183], v[204:207], v[52:55]
	v_mfma_f32_16x16x32_bf16 v[48:51], v[188:191], v[204:207], v[48:51]
	v_mfma_f32_16x16x32_bf16 v[44:47], v[180:183], v[212:215], v[44:47]
	v_mfma_f32_16x16x32_bf16 v[40:43], v[188:191], v[212:215], v[40:43]
	s_setprio 2
	s_barrier
; #define PG8_STAGE(bufoff, gbase, voff) do { _Pragma("unroll") for (int _i = 0; _i < 2; ++_i) \
;         __builtin_amdgcn_global_load_lds((const unsigned*)((const char*)(gbase) + (voff)[_i]), (LAS unsigned*)(lds + (bufoff) + ldsw + _i * 8192), 16, 0, 0); } while (0)
; #define PG8_LDA(dst, b, h) do { _Pragma("unroll") for (int m = 0; m < 4; ++m) _Pragma("unroll") for (int k = 0; k < 2; ++k) dst[m][k] = *(const LAS bf16x8*)(lds + PG8_SA(b, h) + aoff + m * 2048 + k * 1024); } while (0)
; #define PG8_MMA(ai, bj, At, Bt) do { __builtin_amdgcn_s_setprio(1); _Pragma("unroll") for (int m = 0; m < 4; ++m) _Pragma("unroll") for (int n = 0; n < 2; ++n) _Pragma("unroll") for (int k = 0; k < 2; ++k) \
;         acc[ai][bj][m][n] = __builtin_amdgcn_mfma_f32_16x16x32_bf16(Bt[n][k], At[m][k], acc[ai][bj][m][n], 0, 0, 0); __builtin_amdgcn_s_setprio(0); } while (0)
; #define PG8_WAIT_V(n) asm volatile("s_waitcnt vmcnt(" #n ")" ::: "memory")
; #define PG8_WAIT_L(n) asm volatile("s_waitcnt lgkmcnt(" #n ")" ::: "memory")
; #define PG8_BAR __builtin_amdgcn_s_barrier()
; #define PG8_SCHED __builtin_amdgcn_sched_barrier(0)
; template <class Epi, class Sched, bool ALIGN_EPI = true, bool SP2 = true>
; __device__ __forceinline__ void gemm_phase(LAS unsigned char* lds, const bf16_t* Ag, const bf16_t* Btg, const int K, const int lda, const int ldb, const Sched& S, const Epi& E) {
;     ...
;             PG8_LDA(At, 1, 1); PG8_STAGE(PG8_SB(1, 0), b3, voffB); PG8_STAGE(PG8_SB(1, 1), b3 + hstepB, voffB); PG8_STAGE(PG8_SA(1, 0), a3, voffA);
;             PG8_WAIT_V(8); PG8_WAIT_L(0); PG8_BAR; PG8_MMA(1, 0, At, B0); PG8_MMA(1, 1, At, B1); PG8_BAR; PG8_SCHED;
	v_mfma_f32_16x16x32_bf16 v[36:39], v[180:183], v[220:223], v[36:39]
	v_mfma_f32_16x16x32_bf16 v[32:35], v[188:191], v[220:223], v[32:35]
	s_setprio 0
	s_add_i32 s28, s54, s35
	v_lshl_add_u64 v[174:175], v[174:175], 0, s[6:7]
	s_mov_b32 m0, s28
	ds_read_b128 v[192:195], v172 offset:49152
	ds_read_b128 v[196:199], v172 offset:50176
	ds_read_b128 v[200:203], v172 offset:51200
	ds_read_b128 v[204:207], v172 offset:52224
	ds_read_b128 v[208:211], v172 offset:53248
	ds_read_b128 v[212:215], v172 offset:54272
	ds_read_b128 v[216:219], v172 offset:55296
	ds_read_b128 v[220:223], v172 offset:56320
	global_load_lds_dwordx4 v[174:175], off
	s_add_i32 m0, s28, 0x2000
	s_add_u32 s26, s26, 0x80080
	v_lshl_add_u64 v[174:175], v[224:225], 0, s[6:7]
	s_addc_u32 s27, s27, 0
	s_add_i32 s28, s55, s35
	global_load_lds_dwordx4 v[174:175], off
	v_lshl_add_u64 v[174:175], s[26:27], 0, v[138:139]
	s_mov_b32 m0, s28
	s_nop 0
	global_load_lds_dwordx4 v[174:175], off
	v_lshl_add_u64 v[174:175], s[26:27], 0, v[142:143]
	s_add_i32 m0, s28, 0x2000
	s_nop 0
	global_load_lds_dwordx4 v[174:175], off
	v_lshl_add_u64 v[174:175], v[226:227], 0, s[6:7]
	s_mov_b32 m0, s42
	s_nop 0
	global_load_lds_dwordx4 v[174:175], off
	v_lshl_add_u64 v[174:175], v[228:229], 0, s[6:7]
	s_mov_b32 m0, s43
	s_nop 0
	global_load_lds_dwordx4 v[174:175], off
	s_waitcnt vmcnt(8)
	s_waitcnt lgkmcnt(0)
	s_barrier
	s_setprio 1
	s_waitcnt lgkmcnt(0)
	v_mfma_f32_16x16x32_bf16 v[92:95], v[108:111], v[192:195], v[92:95]
	v_mfma_f32_16x16x32_bf16 v[88:91], v[154:157], v[192:195], v[88:91]
	v_mfma_f32_16x16x32_bf16 v[84:87], v[108:111], v[200:203], v[84:87]
	v_mfma_f32_16x16x32_bf16 v[80:83], v[154:157], v[200:203], v[80:83]
	v_mfma_f32_16x16x32_bf16 v[76:79], v[108:111], v[208:211], v[76:79]
	v_mfma_f32_16x16x32_bf16 v[72:75], v[154:157], v[208:211], v[72:75]
	v_mfma_f32_16x16x32_bf16 v[68:71], v[108:111], v[216:219], v[68:71]
	v_mfma_f32_16x16x32_bf16 v[64:67], v[154:157], v[216:219], v[64:67]
	v_mfma_f32_16x16x32_bf16 v[92:95], v[112:115], v[196:199], v[92:95]
	v_mfma_f32_16x16x32_bf16 v[88:91], v[158:161], v[196:199], v[88:91]
	v_mfma_f32_16x16x32_bf16 v[84:87], v[112:115], v[204:207], v[84:87]
	v_mfma_f32_16x16x32_bf16 v[80:83], v[158:161], v[204:207], v[80:83]
	v_mfma_f32_16x16x32_bf16 v[76:79], v[112:115], v[212:215], v[76:79]
	v_mfma_f32_16x16x32_bf16 v[72:75], v[158:161], v[212:215], v[72:75]
	v_mfma_f32_16x16x32_bf16 v[68:71], v[112:115], v[220:223], v[68:71]
	v_mfma_f32_16x16x32_bf16 v[64:67], v[158:161], v[220:223], v[64:67]
	s_setprio 0
	s_setprio 1
	v_mfma_f32_16x16x32_bf16 v[28:31], v[162:165], v[192:195], v[28:31]
	v_mfma_f32_16x16x32_bf16 v[24:27], v[184:187], v[192:195], v[24:27]
	v_mfma_f32_16x16x32_bf16 v[20:23], v[162:165], v[200:203], v[20:23]
	v_mfma_f32_16x16x32_bf16 v[16:19], v[184:187], v[200:203], v[16:19]
	v_mfma_f32_16x16x32_bf16 v[12:15], v[162:165], v[208:211], v[12:15]
	v_mfma_f32_16x16x32_bf16 v[8:11], v[184:187], v[208:211], v[8:11]
	v_mfma_f32_16x16x32_bf16 v[4:7], v[162:165], v[216:219], v[4:7]
	v_mfma_f32_16x16x32_bf16 v[0:3], v[184:187], v[216:219], v[0:3]
	v_mfma_f32_16x16x32_bf16 v[28:31], v[180:183], v[196:199], v[28:31]
	v_mfma_f32_16x16x32_bf16 v[24:27], v[188:191], v[196:199], v[24:27]
	v_mfma_f32_16x16x32_bf16 v[20:23], v[180:183], v[204:207], v[20:23]
	v_mfma_f32_16x16x32_bf16 v[16:19], v[188:191], v[204:207], v[16:19]
	v_mfma_f32_16x16x32_bf16 v[12:15], v[180:183], v[212:215], v[12:15]
	v_mfma_f32_16x16x32_bf16 v[8:11], v[188:191], v[212:215], v[8:11]
	s_setprio 2
	s_barrier
	v_mfma_f32_16x16x32_bf16 v[4:7], v[180:183], v[220:223], v[4:7]
	v_mfma_f32_16x16x32_bf16 v[0:3], v[188:191], v[220:223], v[0:3]
	s_setprio 0
	s_add_i32 s53, s53, 2
	s_add_u32 s24, s24, 0x100
	s_addc_u32 s25, s25, 0
	s_add_u32 s51, s51, 0x100
	s_addc_u32 s52, s52, 0
	s_cmp_gt_u32 s53, 29
	s_cbranch_scc0 .LBB0_787
	s_and_b64 vcc, exec, s[8:9]
	s_cbranch_vccz .LBB0_790
	s_barrier

; #define PG8_STAGE(bufoff, gbase, voff) do { _Pragma("unroll") for (int _i = 0; _i < 2; ++_i) \
;         __builtin_amdgcn_global_load_lds((const unsigned*)((const char*)(gbase) + (voff)[_i]), (LAS unsigned*)(lds + (bufoff) + ldsw + _i * 8192), 16, 0, 0); } while (0)
; #define PG8_LDA(dst, b, h) do { _Pragma("unroll") for (int m = 0; m < 4; ++m) _Pragma("unroll") for (int k = 0; k < 2; ++k) dst[m][k] = *(const LAS bf16x8*)(lds + PG8_SA(b, h) + aoff + m * 2048 + k * 1024); } while (0)
; #define PG8_LDB(dst, b, h) do { _Pragma("unroll") for (int n = 0; n < 2; ++n) _Pragma("unroll") for (int k = 0; k < 2; ++k) dst[n][k] = *(const LAS bf16x8*)(lds + PG8_SB(b, h) + boff + n * 2048 + k * 1024); } while (0)
; #define PG8_MMA(ai, bj, At, Bt) do { __builtin_amdgcn_s_setprio(1); _Pragma("unroll") for (int m = 0; m < 4; ++m) _Pragma("unroll") for (int n = 0; n < 2; ++n) _Pragma("unroll") for (int k = 0; k < 2; ++k) \
;         acc[ai][bj][m][n] = __builtin_amdgcn_mfma_f32_16x16x32_bf16(Bt[n][k], At[m][k], acc[ai][bj][m][n], 0, 0, 0); __builtin_amdgcn_s_setprio(0); } while (0)
; #define PG8_WAIT_V(n) asm volatile("s_waitcnt vmcnt(" #n ")" ::: "memory")
; #define PG8_WAIT_L(n) asm volatile("s_waitcnt lgkmcnt(" #n ")" ::: "memory")
; #define PG8_BAR __builtin_amdgcn_s_barrier()
; #define PG8_SCHED __builtin_amdgcn_sched_barrier(0)
; template <class Epi, class Sched, bool ALIGN_EPI = true, bool SP2 = true>
; __device__ __forceinline__ void gemm_phase(LAS unsigned char* lds, const bf16_t* Ag, const bf16_t* Btg, const int K, const int lda, const int ldb, const Sched& S, const Epi& E) {
;     ...
;             const bool last = (t == nt - 2);
;             const char* a1 = cA + (size_t)(t + 1) * kstep;
;             const char* a2 = last ? nA : cA + (size_t)(t + 2) * kstep; const char* b2 = last ? nB : cB + (size_t)(t + 2) * kstep;
;             const char* a3 = a2 + kstep; const char* b3 = b2 + kstep;
;             if constexpr (SP2) {
;             PG8_LDB(B0, 0, 0); PG8_LDB(B1, 0, 1); PG8_SCHED; PG8_LDA(At, 0, 0); PG8_STAGE(PG8_SA(1, 1), a1 + hstepA, voffA);
;             PG8_WAIT_V(8); PG8_WAIT_L(0); PG8_BAR; PG8_MMA(0, 0, At, B0); PG8_MMA(0, 1, At, B1); PG8_BAR; PG8_SCHED;
;             PG8_LDA(At, 0, 1); PG8_STAGE(PG8_SB(0, 0), b2, voffB); PG8_STAGE(PG8_SB(0, 1), b2 + hstepB, voffB); PG8_STAGE(PG8_SA(0, 0), a2, voffA);
.LBB0_866:
	ds_read_b128 v[146:149], v159
	ds_read_b128 v[162:165], v159 offset:1024
	ds_read_b128 v[168:171], v159 offset:2048
	ds_read_b128 v[172:175], v159 offset:3072
	ds_read_b128 v[180:183], v160
	ds_read_b128 v[184:187], v160 offset:1024
	ds_read_b128 v[188:191], v160 offset:2048
	ds_read_b128 v[192:195], v160 offset:3072
	s_add_u32 s28, s26, 0xfff80080
	s_addc_u32 s29, s27, -1
	s_cmp_eq_u32 s53, 12
	s_cselect_b32 s31, s13, s29
	s_cselect_b32 s30, s15, s28
	s_cselect_b32 s29, s47, s52
	s_cselect_b32 s28, s50, s51
	v_lshl_add_u64 v[228:229], s[26:27], 0, v[138:139]
	s_add_i32 m0, s35, 0xc000
	ds_read_b128 v[196:199], v161
	ds_read_b128 v[200:203], v161 offset:1024
	ds_read_b128 v[204:207], v161 offset:2048
	ds_read_b128 v[208:211], v161 offset:3072
	ds_read_b128 v[212:215], v161 offset:4096
	ds_read_b128 v[216:219], v161 offset:5120
	ds_read_b128 v[220:223], v161 offset:6144
	ds_read_b128 v[224:227], v161 offset:7168
	global_load_lds_dwordx4 v[228:229], off
	v_lshl_add_u64 v[228:229], s[26:27], 0, v[140:141]
	s_add_i32 m0, s35, 0xe000
	s_nop 0
	global_load_lds_dwordx4 v[228:229], off
	s_waitcnt vmcnt(8)
	s_waitcnt lgkmcnt(0)
	s_barrier
	s_setprio 1
	s_waitcnt lgkmcnt(0)
	v_mfma_f32_16x16x32_bf16 v[124:127], v[146:149], v[196:199], v[124:127]
	v_mfma_f32_16x16x32_bf16 v[120:123], v[168:171], v[196:199], v[120:123]
	v_mfma_f32_16x16x32_bf16 v[108:111], v[146:149], v[204:207], v[108:111]
	v_mfma_f32_16x16x32_bf16 v[104:107], v[168:171], v[204:207], v[104:107]
	v_mfma_f32_16x16x32_bf16 v[92:95], v[146:149], v[212:215], v[92:95]
	v_mfma_f32_16x16x32_bf16 v[88:91], v[168:171], v[212:215], v[88:91]
	v_mfma_f32_16x16x32_bf16 v[76:79], v[146:149], v[220:223], v[76:79]
	v_mfma_f32_16x16x32_bf16 v[72:75], v[168:171], v[220:223], v[72:75]
	v_mfma_f32_16x16x32_bf16 v[124:127], v[162:165], v[200:203], v[124:127]
	v_mfma_f32_16x16x32_bf16 v[120:123], v[172:175], v[200:203], v[120:123]
	v_mfma_f32_16x16x32_bf16 v[108:111], v[162:165], v[208:211], v[108:111]
	v_mfma_f32_16x16x32_bf16 v[104:107], v[172:175], v[208:211], v[104:107]
	v_mfma_f32_16x16x32_bf16 v[92:95], v[162:165], v[216:219], v[92:95]
	v_mfma_f32_16x16x32_bf16 v[88:91], v[172:175], v[216:219], v[88:91]
	v_mfma_f32_16x16x32_bf16 v[76:79], v[162:165], v[224:227], v[76:79]
	v_mfma_f32_16x16x32_bf16 v[72:75], v[172:175], v[224:227], v[72:75]
	s_setprio 0
	s_setprio 1
	v_mfma_f32_16x16x32_bf16 v[116:119], v[180:183], v[196:199], v[116:119]
	v_mfma_f32_16x16x32_bf16 v[112:115], v[188:191], v[196:199], v[112:115]
	v_mfma_f32_16x16x32_bf16 v[100:103], v[180:183], v[204:207], v[100:103]
	v_mfma_f32_16x16x32_bf16 v[96:99], v[188:191], v[204:207], v[96:99]
	v_mfma_f32_16x16x32_bf16 v[84:87], v[180:183], v[212:215], v[84:87]
	v_mfma_f32_16x16x32_bf16 v[80:83], v[188:191], v[212:215], v[80:83]
	v_mfma_f32_16x16x32_bf16 v[68:71], v[180:183], v[220:223], v[68:71]
	v_mfma_f32_16x16x32_bf16 v[64:67], v[188:191], v[220:223], v[64:67]
	v_mfma_f32_16x16x32_bf16 v[116:119], v[184:187], v[200:203], v[116:119]
	v_mfma_f32_16x16x32_bf16 v[112:115], v[192:195], v[200:203], v[112:115]
	v_mfma_f32_16x16x32_bf16 v[100:103], v[184:187], v[208:211], v[100:103]
	v_mfma_f32_16x16x32_bf16 v[96:99], v[192:195], v[208:211], v[96:99]
	v_mfma_f32_16x16x32_bf16 v[84:87], v[184:187], v[216:219], v[84:87]
	v_mfma_f32_16x16x32_bf16 v[80:83], v[192:195], v[216:219], v[80:83]
	s_setprio 2
	s_barrier
	v_mfma_f32_16x16x32_bf16 v[68:71], v[184:187], v[224:227], v[68:71]
	v_mfma_f32_16x16x32_bf16 v[64:67], v[192:195], v[224:227], v[64:67]
	s_setprio 0
	s_add_i32 s54, s45, s34
	v_lshl_add_u64 v[228:229], s[28:29], 0, v[130:131]
	s_mov_b32 m0, s54
	ds_read_b128 v[196:199], v161 offset:16384
	ds_read_b128 v[200:203], v161 offset:17408
	ds_read_b128 v[204:207], v161 offset:18432
	ds_read_b128 v[208:211], v161 offset:19456
	ds_read_b128 v[212:215], v161 offset:20480
	ds_read_b128 v[216:219], v161 offset:21504
	ds_read_b128 v[220:223], v161 offset:22528
	ds_read_b128 v[224:227], v161 offset:23552
	global_load_lds_dwordx4 v[228:229], off
	s_add_i32 m0, s54, 0x2000
	s_add_u32 s54, s28, 0x80000
	v_lshl_add_u64 v[230:231], s[28:29], 0, v[134:135]
	s_addc_u32 s55, s29, 0
	s_add_i32 s58, s46, s34
	global_load_lds_dwordx4 v[230:231], off
	v_lshl_add_u64 v[232:233], s[54:55], 0, v[130:131]
	s_mov_b32 m0, s58
	v_lshl_add_u64 v[234:235], s[30:31], 0, v[132:133]
	global_load_lds_dwordx4 v[232:233], off
	v_lshl_add_u64 v[232:233], s[54:55], 0, v[134:135]
	s_add_i32 m0, s58, 0x2000
	s_nop 0
	global_load_lds_dwordx4 v[232:233], off
	v_lshl_add_u64 v[232:233], s[30:31], 0, v[128:129]
	s_mov_b32 m0, s35
	s_nop 0
	global_load_lds_dwordx4 v[232:233], off
	s_mov_b32 m0, s37
	s_nop 0
	global_load_lds_dwordx4 v[234:235], off
	s_waitcnt vmcnt(8)
	s_waitcnt lgkmcnt(0)
	s_barrier
; #define PG8_STAGE(bufoff, gbase, voff) do { _Pragma("unroll") for (int _i = 0; _i < 2; ++_i) \
;         __builtin_amdgcn_global_load_lds((const unsigned*)((const char*)(gbase) + (voff)[_i]), (LAS unsigned*)(lds + (bufoff) + ldsw + _i * 8192), 16, 0, 0); } while (0)
; #define PG8_LDA(dst, b, h) do { _Pragma("unroll") for (int m = 0; m < 4; ++m) _Pragma("unroll") for (int k = 0; k < 2; ++k) dst[m][k] = *(const LAS bf16x8*)(lds + PG8_SA(b, h) + aoff + m * 2048 + k * 1024); } while (0)
; #define PG8_LDB(dst, b, h) do { _Pragma("unroll") for (int n = 0; n < 2; ++n) _Pragma("unroll") for (int k = 0; k < 2; ++k) dst[n][k] = *(const LAS bf16x8*)(lds + PG8_SB(b, h) + boff + n * 2048 + k * 1024); } while (0)
; #define PG8_MMA(ai, bj, At, Bt) do { __builtin_amdgcn_s_setprio(1); _Pragma("unroll") for (int m = 0; m < 4; ++m) _Pragma("unroll") for (int n = 0; n < 2; ++n) _Pragma("unroll") for (int k = 0; k < 2; ++k) \
;         acc[ai][bj][m][n] = __builtin_amdgcn_mfma_f32_16x16x32_bf16(Bt[n][k], At[m][k], acc[ai][bj][m][n], 0, 0, 0); __builtin_amdgcn_s_setprio(0); } while (0)
; #define PG8_WAIT_V(n) asm volatile("s_waitcnt vmcnt(" #n ")" ::: "memory")
; #define PG8_WAIT_L(n) asm volatile("s_waitcnt lgkmcnt(" #n ")" ::: "memory")
; #define PG8_BAR __builtin_amdgcn_s_barrier()
; #define PG8_SCHED __builtin_amdgcn_sched_barrier(0)
; template <class Epi, class Sched, bool ALIGN_EPI = true, bool SP2 = true>
; __device__ __forceinline__ void gemm_phase(LAS unsigned char* lds, const bf16_t* Ag, const bf16_t* Btg, const int K, const int lda, const int ldb, const Sched& S, const Epi& E) {
;     ...
;             PG8_WAIT_V(8); PG8_WAIT_L(0); PG8_BAR; PG8_MMA(1, 0, At, B0); PG8_MMA(1, 1, At, B1); PG8_BAR; PG8_SCHED;
;             PG8_LDB(B0, 1, 0); PG8_LDB(B1, 1, 1); PG8_SCHED; PG8_LDA(At, 1, 0); PG8_STAGE(PG8_SA(0, 1), a2 + hstepA, voffA);
;             PG8_WAIT_V(8); PG8_WAIT_L(0); PG8_BAR; PG8_MMA(0, 0, At, B0); PG8_MMA(0, 1, At, B1); PG8_BAR; PG8_SCHED;
	s_setprio 1
	s_waitcnt lgkmcnt(0)
	v_mfma_f32_16x16x32_bf16 v[60:63], v[146:149], v[196:199], v[60:63]
	v_mfma_f32_16x16x32_bf16 v[56:59], v[168:171], v[196:199], v[56:59]
	v_mfma_f32_16x16x32_bf16 v[44:47], v[146:149], v[204:207], v[44:47]
	v_mfma_f32_16x16x32_bf16 v[40:43], v[168:171], v[204:207], v[40:43]
	v_mfma_f32_16x16x32_bf16 v[28:31], v[146:149], v[212:215], v[28:31]
	v_mfma_f32_16x16x32_bf16 v[24:27], v[168:171], v[212:215], v[24:27]
	v_mfma_f32_16x16x32_bf16 v[12:15], v[146:149], v[220:223], v[12:15]
	v_mfma_f32_16x16x32_bf16 v[8:11], v[168:171], v[220:223], v[8:11]
	v_mfma_f32_16x16x32_bf16 v[60:63], v[162:165], v[200:203], v[60:63]
	v_mfma_f32_16x16x32_bf16 v[56:59], v[172:175], v[200:203], v[56:59]
	v_mfma_f32_16x16x32_bf16 v[44:47], v[162:165], v[208:211], v[44:47]
	v_mfma_f32_16x16x32_bf16 v[40:43], v[172:175], v[208:211], v[40:43]
	v_mfma_f32_16x16x32_bf16 v[28:31], v[162:165], v[216:219], v[28:31]
	v_mfma_f32_16x16x32_bf16 v[24:27], v[172:175], v[216:219], v[24:27]
	v_mfma_f32_16x16x32_bf16 v[12:15], v[162:165], v[224:227], v[12:15]
	v_mfma_f32_16x16x32_bf16 v[8:11], v[172:175], v[224:227], v[8:11]
	s_setprio 0
	s_setprio 1
	v_mfma_f32_16x16x32_bf16 v[52:55], v[180:183], v[196:199], v[52:55]
	v_mfma_f32_16x16x32_bf16 v[48:51], v[188:191], v[196:199], v[48:51]
	v_mfma_f32_16x16x32_bf16 v[36:39], v[180:183], v[204:207], v[36:39]
	v_mfma_f32_16x16x32_bf16 v[32:35], v[188:191], v[204:207], v[32:35]
	v_mfma_f32_16x16x32_bf16 v[20:23], v[180:183], v[212:215], v[20:23]
	v_mfma_f32_16x16x32_bf16 v[16:19], v[188:191], v[212:215], v[16:19]
	v_mfma_f32_16x16x32_bf16 v[4:7], v[180:183], v[220:223], v[4:7]
	v_mfma_f32_16x16x32_bf16 v[0:3], v[188:191], v[220:223], v[0:3]
	v_mfma_f32_16x16x32_bf16 v[52:55], v[184:187], v[200:203], v[52:55]
	v_mfma_f32_16x16x32_bf16 v[48:51], v[192:195], v[200:203], v[48:51]
	v_mfma_f32_16x16x32_bf16 v[36:39], v[184:187], v[208:211], v[36:39]
	v_mfma_f32_16x16x32_bf16 v[32:35], v[192:195], v[208:211], v[32:35]
	v_mfma_f32_16x16x32_bf16 v[20:23], v[184:187], v[216:219], v[20:23]
	v_mfma_f32_16x16x32_bf16 v[16:19], v[192:195], v[216:219], v[16:19]
	s_setprio 2
	s_barrier
	v_mfma_f32_16x16x32_bf16 v[4:7], v[184:187], v[224:227], v[4:7]
	v_mfma_f32_16x16x32_bf16 v[0:3], v[192:195], v[224:227], v[0:3]
	s_setprio 0
	s_add_i32 s54, 0, 0x18000
	s_add_i32 s55, 0, 0x1c000
	v_add_u32_e32 v172, s54, v157
	v_add_u32_e32 v192, s55, v157
	ds_read_b128 v[146:149], v172
	ds_read_b128 v[162:165], v172 offset:1024
	ds_read_b128 v[168:171], v172 offset:2048
	ds_read_b128 v[172:175], v172 offset:3072
	ds_read_b128 v[180:183], v192
	ds_read_b128 v[184:187], v192 offset:1024
	ds_read_b128 v[188:191], v192 offset:2048
	ds_read_b128 v[192:195], v192 offset:3072
	s_add_u32 s30, s30, 0x80000
	s_addc_u32 s31, s31, 0
	s_mov_b32 m0, s38
	v_lshl_add_u64 v[236:237], s[30:31], 0, v[128:129]
	ds_read_b128 v[196:199], v161 offset:32768
	ds_read_b128 v[200:203], v161 offset:33792
	ds_read_b128 v[204:207], v161 offset:34816
	ds_read_b128 v[208:211], v161 offset:35840
	ds_read_b128 v[212:215], v161 offset:36864
	ds_read_b128 v[216:219], v161 offset:37888
	ds_read_b128 v[220:223], v161 offset:38912
	ds_read_b128 v[224:227], v161 offset:39936
	global_load_lds_dwordx4 v[236:237], off
	v_lshl_add_u64 v[236:237], s[30:31], 0, v[132:133]
	s_mov_b32 m0, s39
	s_nop 0
	global_load_lds_dwordx4 v[236:237], off
	s_waitcnt vmcnt(8)
	s_waitcnt lgkmcnt(0)
	s_barrier
	s_setprio 1
	s_waitcnt lgkmcnt(0)
	v_mfma_f32_16x16x32_bf16 v[124:127], v[146:149], v[196:199], v[124:127]
	v_mfma_f32_16x16x32_bf16 v[120:123], v[168:171], v[196:199], v[120:123]
	v_mfma_f32_16x16x32_bf16 v[108:111], v[146:149], v[204:207], v[108:111]
	v_mfma_f32_16x16x32_bf16 v[104:107], v[168:171], v[204:207], v[104:107]
	v_mfma_f32_16x16x32_bf16 v[92:95], v[146:149], v[212:215], v[92:95]
	v_mfma_f32_16x16x32_bf16 v[88:91], v[168:171], v[212:215], v[88:91]
	v_mfma_f32_16x16x32_bf16 v[76:79], v[146:149], v[220:223], v[76:79]
	v_mfma_f32_16x16x32_bf16 v[72:75], v[168:171], v[220:223], v[72:75]
	v_mfma_f32_16x16x32_bf16 v[124:127], v[162:165], v[200:203], v[124:127]
	v_mfma_f32_16x16x32_bf16 v[120:123], v[172:175], v[200:203], v[120:123]
	v_mfma_f32_16x16x32_bf16 v[108:111], v[162:165], v[208:211], v[108:111]
	v_mfma_f32_16x16x32_bf16 v[104:107], v[172:175], v[208:211], v[104:107]
	v_mfma_f32_16x16x32_bf16 v[92:95], v[162:165], v[216:219], v[92:95]
	v_mfma_f32_16x16x32_bf16 v[88:91], v[172:175], v[216:219], v[88:91]
	v_mfma_f32_16x16x32_bf16 v[76:79], v[162:165], v[224:227], v[76:79]
	v_mfma_f32_16x16x32_bf16 v[72:75], v[172:175], v[224:227], v[72:75]
	s_setprio 0
	s_setprio 1
	v_mfma_f32_16x16x32_bf16 v[116:119], v[180:183], v[196:199], v[116:119]
	v_mfma_f32_16x16x32_bf16 v[112:115], v[188:191], v[196:199], v[112:115]
	v_mfma_f32_16x16x32_bf16 v[100:103], v[180:183], v[204:207], v[100:103]
	v_mfma_f32_16x16x32_bf16 v[96:99], v[188:191], v[204:207], v[96:99]
	v_mfma_f32_16x16x32_bf16 v[84:87], v[180:183], v[212:215], v[84:87]
	v_mfma_f32_16x16x32_bf16 v[80:83], v[188:191], v[212:215], v[80:83]
	v_mfma_f32_16x16x32_bf16 v[68:71], v[180:183], v[220:223], v[68:71]
	v_mfma_f32_16x16x32_bf16 v[64:67], v[188:191], v[220:223], v[64:67]
	v_mfma_f32_16x16x32_bf16 v[116:119], v[184:187], v[200:203], v[116:119]
	v_mfma_f32_16x16x32_bf16 v[112:115], v[192:195], v[200:203], v[112:115]
	v_mfma_f32_16x16x32_bf16 v[100:103], v[184:187], v[208:211], v[100:103]
	v_mfma_f32_16x16x32_bf16 v[96:99], v[192:195], v[208:211], v[96:99]
	v_mfma_f32_16x16x32_bf16 v[84:87], v[184:187], v[216:219], v[84:87]
	v_mfma_f32_16x16x32_bf16 v[80:83], v[192:195], v[216:219], v[80:83]
	s_setprio 2
	s_barrier
; #define PG8_STAGE(bufoff, gbase, voff) do { _Pragma("unroll") for (int _i = 0; _i < 2; ++_i) \
;         __builtin_amdgcn_global_load_lds((const unsigned*)((const char*)(gbase) + (voff)[_i]), (LAS unsigned*)(lds + (bufoff) + ldsw + _i * 8192), 16, 0, 0); } while (0)
; #define PG8_LDA(dst, b, h) do { _Pragma("unroll") for (int m = 0; m < 4; ++m) _Pragma("unroll") for (int k = 0; k < 2; ++k) dst[m][k] = *(const LAS bf16x8*)(lds + PG8_SA(b, h) + aoff + m * 2048 + k * 1024); } while (0)
; #define PG8_MMA(ai, bj, At, Bt) do { __builtin_amdgcn_s_setprio(1); _Pragma("unroll") for (int m = 0; m < 4; ++m) _Pragma("unroll") for (int n = 0; n < 2; ++n) _Pragma("unroll") for (int k = 0; k < 2; ++k) \
;         acc[ai][bj][m][n] = __builtin_amdgcn_mfma_f32_16x16x32_bf16(Bt[n][k], At[m][k], acc[ai][bj][m][n], 0, 0, 0); __builtin_amdgcn_s_setprio(0); } while (0)
; #define PG8_WAIT_V(n) asm volatile("s_waitcnt vmcnt(" #n ")" ::: "memory")
; #define PG8_WAIT_L(n) asm volatile("s_waitcnt lgkmcnt(" #n ")" ::: "memory")
; #define PG8_BAR __builtin_amdgcn_s_barrier()
; #define PG8_SCHED __builtin_amdgcn_sched_barrier(0)
; template <class Epi, class Sched, bool ALIGN_EPI = true, bool SP2 = true>
; __device__ __forceinline__ void gemm_phase(LAS unsigned char* lds, const bf16_t* Ag, const bf16_t* Btg, const int K, const int lda, const int ldb, const Sched& S, const Epi& E) {
;     ...
;             PG8_LDA(At, 1, 1); PG8_STAGE(PG8_SB(1, 0), b3, voffB); PG8_STAGE(PG8_SB(1, 1), b3 + hstepB, voffB); PG8_STAGE(PG8_SA(1, 0), a3, voffA);
;             PG8_WAIT_V(8); PG8_WAIT_L(0); PG8_BAR; PG8_MMA(1, 0, At, B0); PG8_MMA(1, 1, At, B1); PG8_BAR; PG8_SCHED;
	v_mfma_f32_16x16x32_bf16 v[68:71], v[184:187], v[224:227], v[68:71]
	v_mfma_f32_16x16x32_bf16 v[64:67], v[192:195], v[224:227], v[64:67]
	s_setprio 0
	s_add_i32 s30, s54, s34
	v_lshl_add_u64 v[228:229], v[228:229], 0, s[8:9]
	s_mov_b32 m0, s30
	ds_read_b128 v[196:199], v161 offset:49152
	ds_read_b128 v[200:203], v161 offset:50176
	ds_read_b128 v[204:207], v161 offset:51200
	ds_read_b128 v[208:211], v161 offset:52224
	ds_read_b128 v[212:215], v161 offset:53248
	ds_read_b128 v[216:219], v161 offset:54272
	ds_read_b128 v[220:223], v161 offset:55296
	ds_read_b128 v[224:227], v161 offset:56320
	global_load_lds_dwordx4 v[228:229], off
	s_add_i32 m0, s30, 0x2000
	s_add_u32 s28, s28, 0x80080
	v_lshl_add_u64 v[228:229], v[230:231], 0, s[8:9]
	s_addc_u32 s29, s29, 0
	s_add_i32 s30, s55, s34
	global_load_lds_dwordx4 v[228:229], off
	v_lshl_add_u64 v[228:229], s[28:29], 0, v[130:131]
	s_mov_b32 m0, s30
	s_nop 0
	global_load_lds_dwordx4 v[228:229], off
	v_lshl_add_u64 v[228:229], s[28:29], 0, v[134:135]
	s_add_i32 m0, s30, 0x2000
	s_nop 0
	global_load_lds_dwordx4 v[228:229], off
	v_lshl_add_u64 v[228:229], v[232:233], 0, s[8:9]
	s_mov_b32 m0, s41
	s_nop 0
	global_load_lds_dwordx4 v[228:229], off
	v_lshl_add_u64 v[228:229], v[234:235], 0, s[8:9]
	s_mov_b32 m0, s42
	s_nop 0
	global_load_lds_dwordx4 v[228:229], off
	s_waitcnt vmcnt(8)
	s_waitcnt lgkmcnt(0)
	s_barrier
	s_setprio 1
	s_waitcnt lgkmcnt(0)
	v_mfma_f32_16x16x32_bf16 v[60:63], v[146:149], v[196:199], v[60:63]
	v_mfma_f32_16x16x32_bf16 v[56:59], v[168:171], v[196:199], v[56:59]
	v_mfma_f32_16x16x32_bf16 v[44:47], v[146:149], v[204:207], v[44:47]
	v_mfma_f32_16x16x32_bf16 v[40:43], v[168:171], v[204:207], v[40:43]
	v_mfma_f32_16x16x32_bf16 v[28:31], v[146:149], v[212:215], v[28:31]
	v_mfma_f32_16x16x32_bf16 v[24:27], v[168:171], v[212:215], v[24:27]
	v_mfma_f32_16x16x32_bf16 v[12:15], v[146:149], v[220:223], v[12:15]
	v_mfma_f32_16x16x32_bf16 v[8:11], v[168:171], v[220:223], v[8:11]
	v_mfma_f32_16x16x32_bf16 v[60:63], v[162:165], v[200:203], v[60:63]
	v_mfma_f32_16x16x32_bf16 v[56:59], v[172:175], v[200:203], v[56:59]
	v_mfma_f32_16x16x32_bf16 v[44:47], v[162:165], v[208:211], v[44:47]
	v_mfma_f32_16x16x32_bf16 v[40:43], v[172:175], v[208:211], v[40:43]
	v_mfma_f32_16x16x32_bf16 v[28:31], v[162:165], v[216:219], v[28:31]
	v_mfma_f32_16x16x32_bf16 v[24:27], v[172:175], v[216:219], v[24:27]
	v_mfma_f32_16x16x32_bf16 v[12:15], v[162:165], v[224:227], v[12:15]
	v_mfma_f32_16x16x32_bf16 v[8:11], v[172:175], v[224:227], v[8:11]
	s_setprio 0
	s_setprio 1
	v_mfma_f32_16x16x32_bf16 v[52:55], v[180:183], v[196:199], v[52:55]
	v_mfma_f32_16x16x32_bf16 v[48:51], v[188:191], v[196:199], v[48:51]
	v_mfma_f32_16x16x32_bf16 v[36:39], v[180:183], v[204:207], v[36:39]
	v_mfma_f32_16x16x32_bf16 v[32:35], v[188:191], v[204:207], v[32:35]
	v_mfma_f32_16x16x32_bf16 v[20:23], v[180:183], v[212:215], v[20:23]
	v_mfma_f32_16x16x32_bf16 v[16:19], v[188:191], v[212:215], v[16:19]
	v_mfma_f32_16x16x32_bf16 v[4:7], v[180:183], v[220:223], v[4:7]
	v_mfma_f32_16x16x32_bf16 v[0:3], v[188:191], v[220:223], v[0:3]
	v_mfma_f32_16x16x32_bf16 v[52:55], v[184:187], v[200:203], v[52:55]
	v_mfma_f32_16x16x32_bf16 v[48:51], v[192:195], v[200:203], v[48:51]
	v_mfma_f32_16x16x32_bf16 v[36:39], v[184:187], v[208:211], v[36:39]
	v_mfma_f32_16x16x32_bf16 v[32:35], v[192:195], v[208:211], v[32:35]
	v_mfma_f32_16x16x32_bf16 v[20:23], v[184:187], v[216:219], v[20:23]
	v_mfma_f32_16x16x32_bf16 v[16:19], v[192:195], v[216:219], v[16:19]
	s_setprio 2
	s_barrier
	v_mfma_f32_16x16x32_bf16 v[4:7], v[184:187], v[224:227], v[4:7]
	v_mfma_f32_16x16x32_bf16 v[0:3], v[192:195], v[224:227], v[0:3]
	s_setprio 0
	s_add_i32 s53, s53, 2
	s_add_u32 s26, s26, 0x100
	s_addc_u32 s27, s27, 0
	s_add_u32 s51, s51, 0x100
	s_addc_u32 s52, s52, 0
	s_cmp_gt_u32 s53, 13
	s_cbranch_scc0 .LBB0_866
	s_and_b64 vcc, exec, s[10:11]
	s_cbranch_vccz .LBB0_869
	s_barrier

; #define PG8_STAGE(bufoff, gbase, voff) do { _Pragma("unroll") for (int _i = 0; _i < 2; ++_i) \
;         __builtin_amdgcn_global_load_lds((const unsigned*)((const char*)(gbase) + (voff)[_i]), (LAS unsigned*)(lds + (bufoff) + ldsw + _i * 8192), 16, 0, 0); } while (0)
; #define PG8_LDA(dst, b, h) do { _Pragma("unroll") for (int m = 0; m < 4; ++m) _Pragma("unroll") for (int k = 0; k < 2; ++k) dst[m][k] = *(const LAS bf16x8*)(lds + PG8_SA(b, h) + aoff + m * 2048 + k * 1024); } while (0)
; #define PG8_LDB(dst, b, h) do { _Pragma("unroll") for (int n = 0; n < 2; ++n) _Pragma("unroll") for (int k = 0; k < 2; ++k) dst[n][k] = *(const LAS bf16x8*)(lds + PG8_SB(b, h) + boff + n * 2048 + k * 1024); } while (0)
; #define PG8_MMA(ai, bj, At, Bt) do { __builtin_amdgcn_s_setprio(1); _Pragma("unroll") for (int m = 0; m < 4; ++m) _Pragma("unroll") for (int n = 0; n < 2; ++n) _Pragma("unroll") for (int k = 0; k < 2; ++k) \
;         acc[ai][bj][m][n] = __builtin_amdgcn_mfma_f32_16x16x32_bf16(Bt[n][k], At[m][k], acc[ai][bj][m][n], 0, 0, 0); __builtin_amdgcn_s_setprio(0); } while (0)
; #define PG8_WAIT_V(n) asm volatile("s_waitcnt vmcnt(" #n ")" ::: "memory")
; #define PG8_WAIT_L(n) asm volatile("s_waitcnt lgkmcnt(" #n ")" ::: "memory")
; #define PG8_BAR __builtin_amdgcn_s_barrier()
; #define PG8_SCHED __builtin_amdgcn_sched_barrier(0)
; template <class Epi, class Sched, bool ALIGN_EPI = true, bool SP2 = true>
; __device__ __forceinline__ void gemm_phase(LAS unsigned char* lds, const bf16_t* Ag, const bf16_t* Btg, const int K, const int lda, const int ldb, const Sched& S, const Epi& E) {
;     ...
;             const bool last = (t == nt - 2);
;             const char* a1 = cA + (size_t)(t + 1) * kstep;
;             const char* a2 = last ? nA : cA + (size_t)(t + 2) * kstep; const char* b2 = last ? nB : cB + (size_t)(t + 2) * kstep;
;             const char* a3 = a2 + kstep; const char* b3 = b2 + kstep;
;             if constexpr (SP2) {
;             PG8_LDB(B0, 0, 0); PG8_LDB(B1, 0, 1); PG8_SCHED; PG8_LDA(At, 0, 0); PG8_STAGE(PG8_SA(1, 1), a1 + hstepA, voffA);
;             PG8_WAIT_V(8); PG8_WAIT_L(0); PG8_BAR; PG8_MMA(0, 0, At, B0); PG8_MMA(0, 1, At, B1); PG8_BAR; PG8_SCHED;
;             PG8_LDA(At, 0, 1); PG8_STAGE(PG8_SB(0, 0), b2, voffB); PG8_STAGE(PG8_SB(0, 1), b2 + hstepB, voffB); PG8_STAGE(PG8_SA(0, 0), a2, voffA);
.LBB0_890:
	ds_read_b128 v[146:149], v156
	ds_read_b128 v[150:153], v156 offset:1024
	ds_read_b128 v[160:163], v156 offset:2048
	ds_read_b128 v[168:171], v156 offset:3072
	ds_read_b128 v[172:175], v157
	ds_read_b128 v[180:183], v157 offset:1024
	ds_read_b128 v[184:187], v157 offset:2048
	ds_read_b128 v[188:191], v157 offset:3072
	s_add_u32 s28, s26, 0xfff80080
	s_addc_u32 s29, s27, -1
	s_cmp_eq_u32 s59, 12
	s_cselect_b32 s31, s13, s29
	s_cselect_b32 s30, s15, s28
	s_cselect_b32 s29, s33, s58
	s_cselect_b32 s28, s54, s55
	v_lshl_add_u64 v[164:165], s[26:27], 0, v[138:139]
	s_add_i32 m0, s41, 0xc000
	ds_read_b128 v[192:195], v158
	ds_read_b128 v[196:199], v158 offset:1024
	ds_read_b128 v[200:203], v158 offset:2048
	ds_read_b128 v[204:207], v158 offset:3072
	ds_read_b128 v[208:211], v158 offset:4096
	ds_read_b128 v[212:215], v158 offset:5120
	ds_read_b128 v[216:219], v158 offset:6144
	ds_read_b128 v[220:223], v158 offset:7168
	global_load_lds_dwordx4 v[164:165], off
	v_lshl_add_u64 v[164:165], s[26:27], 0, v[140:141]
	s_add_i32 m0, s41, 0xe000
	s_nop 0
	global_load_lds_dwordx4 v[164:165], off
	s_waitcnt vmcnt(8)
	s_waitcnt lgkmcnt(0)
	s_barrier
	s_setprio 1
	s_waitcnt lgkmcnt(0)
	v_mfma_f32_16x16x32_bf16 v[124:127], v[146:149], v[192:195], v[124:127]
	v_mfma_f32_16x16x32_bf16 v[120:123], v[160:163], v[192:195], v[120:123]
	v_mfma_f32_16x16x32_bf16 v[108:111], v[146:149], v[200:203], v[108:111]
	v_mfma_f32_16x16x32_bf16 v[104:107], v[160:163], v[200:203], v[104:107]
	v_mfma_f32_16x16x32_bf16 v[92:95], v[146:149], v[208:211], v[92:95]
	v_mfma_f32_16x16x32_bf16 v[88:91], v[160:163], v[208:211], v[88:91]
	v_mfma_f32_16x16x32_bf16 v[76:79], v[146:149], v[216:219], v[76:79]
	v_mfma_f32_16x16x32_bf16 v[72:75], v[160:163], v[216:219], v[72:75]
	v_mfma_f32_16x16x32_bf16 v[124:127], v[150:153], v[196:199], v[124:127]
	v_mfma_f32_16x16x32_bf16 v[120:123], v[168:171], v[196:199], v[120:123]
	v_mfma_f32_16x16x32_bf16 v[108:111], v[150:153], v[204:207], v[108:111]
	v_mfma_f32_16x16x32_bf16 v[104:107], v[168:171], v[204:207], v[104:107]
	v_mfma_f32_16x16x32_bf16 v[92:95], v[150:153], v[212:215], v[92:95]
	v_mfma_f32_16x16x32_bf16 v[88:91], v[168:171], v[212:215], v[88:91]
	v_mfma_f32_16x16x32_bf16 v[76:79], v[150:153], v[220:223], v[76:79]
	v_mfma_f32_16x16x32_bf16 v[72:75], v[168:171], v[220:223], v[72:75]
	s_setprio 0
	s_setprio 1
	v_mfma_f32_16x16x32_bf16 v[116:119], v[172:175], v[192:195], v[116:119]
	v_mfma_f32_16x16x32_bf16 v[112:115], v[184:187], v[192:195], v[112:115]
	v_mfma_f32_16x16x32_bf16 v[100:103], v[172:175], v[200:203], v[100:103]
	v_mfma_f32_16x16x32_bf16 v[96:99], v[184:187], v[200:203], v[96:99]
	v_mfma_f32_16x16x32_bf16 v[84:87], v[172:175], v[208:211], v[84:87]
	v_mfma_f32_16x16x32_bf16 v[80:83], v[184:187], v[208:211], v[80:83]
	v_mfma_f32_16x16x32_bf16 v[68:71], v[172:175], v[216:219], v[68:71]
	v_mfma_f32_16x16x32_bf16 v[64:67], v[184:187], v[216:219], v[64:67]
	v_mfma_f32_16x16x32_bf16 v[116:119], v[180:183], v[196:199], v[116:119]
	v_mfma_f32_16x16x32_bf16 v[112:115], v[188:191], v[196:199], v[112:115]
	v_mfma_f32_16x16x32_bf16 v[100:103], v[180:183], v[204:207], v[100:103]
	v_mfma_f32_16x16x32_bf16 v[96:99], v[188:191], v[204:207], v[96:99]
	v_mfma_f32_16x16x32_bf16 v[84:87], v[180:183], v[212:215], v[84:87]
	v_mfma_f32_16x16x32_bf16 v[80:83], v[188:191], v[212:215], v[80:83]
	s_setprio 2
	s_barrier
	v_mfma_f32_16x16x32_bf16 v[68:71], v[180:183], v[220:223], v[68:71]
	v_mfma_f32_16x16x32_bf16 v[64:67], v[188:191], v[220:223], v[64:67]
	s_setprio 0
	s_add_i32 s60, s52, s40
	v_lshl_add_u64 v[164:165], s[28:29], 0, v[130:131]
	s_mov_b32 m0, s60
	ds_read_b128 v[192:195], v158 offset:16384
	ds_read_b128 v[196:199], v158 offset:17408
	ds_read_b128 v[200:203], v158 offset:18432
	ds_read_b128 v[204:207], v158 offset:19456
	ds_read_b128 v[208:211], v158 offset:20480
	ds_read_b128 v[212:215], v158 offset:21504
	ds_read_b128 v[216:219], v158 offset:22528
	ds_read_b128 v[220:223], v158 offset:23552
	global_load_lds_dwordx4 v[164:165], off
	s_add_i32 m0, s60, 0x2000
	s_add_u32 s60, s28, 0x80000
	v_lshl_add_u64 v[224:225], s[28:29], 0, v[134:135]
	s_addc_u32 s61, s29, 0
	s_add_i32 s64, s53, s40
	global_load_lds_dwordx4 v[224:225], off
	v_lshl_add_u64 v[226:227], s[60:61], 0, v[130:131]
	s_mov_b32 m0, s64
	v_lshl_add_u64 v[228:229], s[30:31], 0, v[132:133]
	global_load_lds_dwordx4 v[226:227], off
	v_lshl_add_u64 v[226:227], s[60:61], 0, v[134:135]
	s_add_i32 m0, s64, 0x2000
	s_nop 0
	global_load_lds_dwordx4 v[226:227], off
	v_lshl_add_u64 v[226:227], s[30:31], 0, v[128:129]
	s_mov_b32 m0, s41
	s_nop 0
	global_load_lds_dwordx4 v[226:227], off
	s_mov_b32 m0, s42
	s_nop 0
	global_load_lds_dwordx4 v[228:229], off
	s_waitcnt vmcnt(8)
	s_waitcnt lgkmcnt(0)
	s_barrier
; #define PG8_STAGE(bufoff, gbase, voff) do { _Pragma("unroll") for (int _i = 0; _i < 2; ++_i) \
;         __builtin_amdgcn_global_load_lds((const unsigned*)((const char*)(gbase) + (voff)[_i]), (LAS unsigned*)(lds + (bufoff) + ldsw + _i * 8192), 16, 0, 0); } while (0)
; #define PG8_LDA(dst, b, h) do { _Pragma("unroll") for (int m = 0; m < 4; ++m) _Pragma("unroll") for (int k = 0; k < 2; ++k) dst[m][k] = *(const LAS bf16x8*)(lds + PG8_SA(b, h) + aoff + m * 2048 + k * 1024); } while (0)
; #define PG8_LDB(dst, b, h) do { _Pragma("unroll") for (int n = 0; n < 2; ++n) _Pragma("unroll") for (int k = 0; k < 2; ++k) dst[n][k] = *(const LAS bf16x8*)(lds + PG8_SB(b, h) + boff + n * 2048 + k * 1024); } while (0)
; #define PG8_MMA(ai, bj, At, Bt) do { __builtin_amdgcn_s_setprio(1); _Pragma("unroll") for (int m = 0; m < 4; ++m) _Pragma("unroll") for (int n = 0; n < 2; ++n) _Pragma("unroll") for (int k = 0; k < 2; ++k) \
;         acc[ai][bj][m][n] = __builtin_amdgcn_mfma_f32_16x16x32_bf16(Bt[n][k], At[m][k], acc[ai][bj][m][n], 0, 0, 0); __builtin_amdgcn_s_setprio(0); } while (0)
; #define PG8_WAIT_V(n) asm volatile("s_waitcnt vmcnt(" #n ")" ::: "memory")
; #define PG8_WAIT_L(n) asm volatile("s_waitcnt lgkmcnt(" #n ")" ::: "memory")
; #define PG8_BAR __builtin_amdgcn_s_barrier()
; #define PG8_SCHED __builtin_amdgcn_sched_barrier(0)
; template <class Epi, class Sched, bool ALIGN_EPI = true, bool SP2 = true>
; __device__ __forceinline__ void gemm_phase(LAS unsigned char* lds, const bf16_t* Ag, const bf16_t* Btg, const int K, const int lda, const int ldb, const Sched& S, const Epi& E) {
;     ...
;             PG8_WAIT_V(8); PG8_WAIT_L(0); PG8_BAR; PG8_MMA(1, 0, At, B0); PG8_MMA(1, 1, At, B1); PG8_BAR; PG8_SCHED;
;             PG8_LDB(B0, 1, 0); PG8_LDB(B1, 1, 1); PG8_SCHED; PG8_LDA(At, 1, 0); PG8_STAGE(PG8_SA(0, 1), a2 + hstepA, voffA);
;             PG8_WAIT_V(8); PG8_WAIT_L(0); PG8_BAR; PG8_MMA(0, 0, At, B0); PG8_MMA(0, 1, At, B1); PG8_BAR; PG8_SCHED;
	s_setprio 1
	s_waitcnt lgkmcnt(0)
	v_mfma_f32_16x16x32_bf16 v[60:63], v[146:149], v[192:195], v[60:63]
	v_mfma_f32_16x16x32_bf16 v[56:59], v[160:163], v[192:195], v[56:59]
	v_mfma_f32_16x16x32_bf16 v[44:47], v[146:149], v[200:203], v[44:47]
	v_mfma_f32_16x16x32_bf16 v[40:43], v[160:163], v[200:203], v[40:43]
	v_mfma_f32_16x16x32_bf16 v[28:31], v[146:149], v[208:211], v[28:31]
	v_mfma_f32_16x16x32_bf16 v[24:27], v[160:163], v[208:211], v[24:27]
	v_mfma_f32_16x16x32_bf16 v[12:15], v[146:149], v[216:219], v[12:15]
	v_mfma_f32_16x16x32_bf16 v[8:11], v[160:163], v[216:219], v[8:11]
	v_mfma_f32_16x16x32_bf16 v[60:63], v[150:153], v[196:199], v[60:63]
	v_mfma_f32_16x16x32_bf16 v[56:59], v[168:171], v[196:199], v[56:59]
	v_mfma_f32_16x16x32_bf16 v[44:47], v[150:153], v[204:207], v[44:47]
	v_mfma_f32_16x16x32_bf16 v[40:43], v[168:171], v[204:207], v[40:43]
	v_mfma_f32_16x16x32_bf16 v[28:31], v[150:153], v[212:215], v[28:31]
	v_mfma_f32_16x16x32_bf16 v[24:27], v[168:171], v[212:215], v[24:27]
	v_mfma_f32_16x16x32_bf16 v[12:15], v[150:153], v[220:223], v[12:15]
	v_mfma_f32_16x16x32_bf16 v[8:11], v[168:171], v[220:223], v[8:11]
	s_setprio 0
	s_setprio 1
	v_mfma_f32_16x16x32_bf16 v[52:55], v[172:175], v[192:195], v[52:55]
	v_mfma_f32_16x16x32_bf16 v[48:51], v[184:187], v[192:195], v[48:51]
	v_mfma_f32_16x16x32_bf16 v[36:39], v[172:175], v[200:203], v[36:39]
	v_mfma_f32_16x16x32_bf16 v[32:35], v[184:187], v[200:203], v[32:35]
	v_mfma_f32_16x16x32_bf16 v[20:23], v[172:175], v[208:211], v[20:23]
	v_mfma_f32_16x16x32_bf16 v[16:19], v[184:187], v[208:211], v[16:19]
	v_mfma_f32_16x16x32_bf16 v[4:7], v[172:175], v[216:219], v[4:7]
	v_mfma_f32_16x16x32_bf16 v[0:3], v[184:187], v[216:219], v[0:3]
	v_mfma_f32_16x16x32_bf16 v[52:55], v[180:183], v[196:199], v[52:55]
	v_mfma_f32_16x16x32_bf16 v[48:51], v[188:191], v[196:199], v[48:51]
	v_mfma_f32_16x16x32_bf16 v[36:39], v[180:183], v[204:207], v[36:39]
	v_mfma_f32_16x16x32_bf16 v[32:35], v[188:191], v[204:207], v[32:35]
	v_mfma_f32_16x16x32_bf16 v[20:23], v[180:183], v[212:215], v[20:23]
	v_mfma_f32_16x16x32_bf16 v[16:19], v[188:191], v[212:215], v[16:19]
	s_setprio 2
	s_barrier
	v_mfma_f32_16x16x32_bf16 v[4:7], v[180:183], v[220:223], v[4:7]
	v_mfma_f32_16x16x32_bf16 v[0:3], v[188:191], v[220:223], v[0:3]
	s_setprio 0
	s_add_i32 s60, 0, 0x18000
	v_add_u32_e32 v159, s60, v154
	s_add_i32 s61, 0, 0x1c000
	ds_read_b128 v[146:149], v159
	ds_read_b128 v[150:153], v159 offset:1024
	ds_read_b128 v[160:163], v159 offset:2048
	ds_read_b128 v[168:171], v159 offset:3072
	v_add_u32_e32 v159, s61, v154
	ds_read_b128 v[172:175], v159
	ds_read_b128 v[180:183], v159 offset:1024
	ds_read_b128 v[184:187], v159 offset:2048
	ds_read_b128 v[188:191], v159 offset:3072
	s_add_u32 s30, s30, 0x80000
	s_addc_u32 s31, s31, 0
	s_mov_b32 m0, s43
	v_lshl_add_u64 v[230:231], s[30:31], 0, v[128:129]
	ds_read_b128 v[192:195], v158 offset:32768
	ds_read_b128 v[196:199], v158 offset:33792
	ds_read_b128 v[200:203], v158 offset:34816
	ds_read_b128 v[204:207], v158 offset:35840
	ds_read_b128 v[208:211], v158 offset:36864
	ds_read_b128 v[212:215], v158 offset:37888
	ds_read_b128 v[216:219], v158 offset:38912
	ds_read_b128 v[220:223], v158 offset:39936
	global_load_lds_dwordx4 v[230:231], off
	v_lshl_add_u64 v[230:231], s[30:31], 0, v[132:133]
	s_mov_b32 m0, s44
	s_nop 0
	global_load_lds_dwordx4 v[230:231], off
	s_waitcnt vmcnt(8)
	s_waitcnt lgkmcnt(0)
	s_barrier
	s_setprio 1
	s_waitcnt lgkmcnt(0)
	v_mfma_f32_16x16x32_bf16 v[124:127], v[146:149], v[192:195], v[124:127]
	v_mfma_f32_16x16x32_bf16 v[120:123], v[160:163], v[192:195], v[120:123]
	v_mfma_f32_16x16x32_bf16 v[108:111], v[146:149], v[200:203], v[108:111]
	v_mfma_f32_16x16x32_bf16 v[104:107], v[160:163], v[200:203], v[104:107]
	v_mfma_f32_16x16x32_bf16 v[92:95], v[146:149], v[208:211], v[92:95]
	v_mfma_f32_16x16x32_bf16 v[88:91], v[160:163], v[208:211], v[88:91]
	v_mfma_f32_16x16x32_bf16 v[76:79], v[146:149], v[216:219], v[76:79]
	v_mfma_f32_16x16x32_bf16 v[72:75], v[160:163], v[216:219], v[72:75]
	v_mfma_f32_16x16x32_bf16 v[124:127], v[150:153], v[196:199], v[124:127]
	v_mfma_f32_16x16x32_bf16 v[120:123], v[168:171], v[196:199], v[120:123]
	v_mfma_f32_16x16x32_bf16 v[108:111], v[150:153], v[204:207], v[108:111]
	v_mfma_f32_16x16x32_bf16 v[104:107], v[168:171], v[204:207], v[104:107]
	v_mfma_f32_16x16x32_bf16 v[92:95], v[150:153], v[212:215], v[92:95]
	v_mfma_f32_16x16x32_bf16 v[88:91], v[168:171], v[212:215], v[88:91]
	v_mfma_f32_16x16x32_bf16 v[76:79], v[150:153], v[220:223], v[76:79]
	v_mfma_f32_16x16x32_bf16 v[72:75], v[168:171], v[220:223], v[72:75]
	s_setprio 0
	s_setprio 1
	v_mfma_f32_16x16x32_bf16 v[116:119], v[172:175], v[192:195], v[116:119]
	v_mfma_f32_16x16x32_bf16 v[112:115], v[184:187], v[192:195], v[112:115]
	v_mfma_f32_16x16x32_bf16 v[100:103], v[172:175], v[200:203], v[100:103]
	v_mfma_f32_16x16x32_bf16 v[96:99], v[184:187], v[200:203], v[96:99]
	v_mfma_f32_16x16x32_bf16 v[84:87], v[172:175], v[208:211], v[84:87]
	v_mfma_f32_16x16x32_bf16 v[80:83], v[184:187], v[208:211], v[80:83]
	v_mfma_f32_16x16x32_bf16 v[68:71], v[172:175], v[216:219], v[68:71]
	v_mfma_f32_16x16x32_bf16 v[64:67], v[184:187], v[216:219], v[64:67]
	v_mfma_f32_16x16x32_bf16 v[116:119], v[180:183], v[196:199], v[116:119]
	v_mfma_f32_16x16x32_bf16 v[112:115], v[188:191], v[196:199], v[112:115]
	v_mfma_f32_16x16x32_bf16 v[100:103], v[180:183], v[204:207], v[100:103]
	v_mfma_f32_16x16x32_bf16 v[96:99], v[188:191], v[204:207], v[96:99]
	v_mfma_f32_16x16x32_bf16 v[84:87], v[180:183], v[212:215], v[84:87]
	v_mfma_f32_16x16x32_bf16 v[80:83], v[188:191], v[212:215], v[80:83]
	s_setprio 2
	s_barrier
; #define PG8_STAGE(bufoff, gbase, voff) do { _Pragma("unroll") for (int _i = 0; _i < 2; ++_i) \
;         __builtin_amdgcn_global_load_lds((const unsigned*)((const char*)(gbase) + (voff)[_i]), (LAS unsigned*)(lds + (bufoff) + ldsw + _i * 8192), 16, 0, 0); } while (0)
; #define PG8_LDA(dst, b, h) do { _Pragma("unroll") for (int m = 0; m < 4; ++m) _Pragma("unroll") for (int k = 0; k < 2; ++k) dst[m][k] = *(const LAS bf16x8*)(lds + PG8_SA(b, h) + aoff + m * 2048 + k * 1024); } while (0)
; #define PG8_MMA(ai, bj, At, Bt) do { __builtin_amdgcn_s_setprio(1); _Pragma("unroll") for (int m = 0; m < 4; ++m) _Pragma("unroll") for (int n = 0; n < 2; ++n) _Pragma("unroll") for (int k = 0; k < 2; ++k) \
;         acc[ai][bj][m][n] = __builtin_amdgcn_mfma_f32_16x16x32_bf16(Bt[n][k], At[m][k], acc[ai][bj][m][n], 0, 0, 0); __builtin_amdgcn_s_setprio(0); } while (0)
; #define PG8_WAIT_V(n) asm volatile("s_waitcnt vmcnt(" #n ")" ::: "memory")
; #define PG8_WAIT_L(n) asm volatile("s_waitcnt lgkmcnt(" #n ")" ::: "memory")
; #define PG8_BAR __builtin_amdgcn_s_barrier()
; #define PG8_SCHED __builtin_amdgcn_sched_barrier(0)
; template <class Epi, class Sched, bool ALIGN_EPI = true, bool SP2 = true>
; __device__ __forceinline__ void gemm_phase(LAS unsigned char* lds, const bf16_t* Ag, const bf16_t* Btg, const int K, const int lda, const int ldb, const Sched& S, const Epi& E) {
;     ...
;             PG8_LDA(At, 1, 1); PG8_STAGE(PG8_SB(1, 0), b3, voffB); PG8_STAGE(PG8_SB(1, 1), b3 + hstepB, voffB); PG8_STAGE(PG8_SA(1, 0), a3, voffA);
;             PG8_WAIT_V(8); PG8_WAIT_L(0); PG8_BAR; PG8_MMA(1, 0, At, B0); PG8_MMA(1, 1, At, B1); PG8_BAR; PG8_SCHED;
	v_mfma_f32_16x16x32_bf16 v[68:71], v[180:183], v[220:223], v[68:71]
	v_mfma_f32_16x16x32_bf16 v[64:67], v[188:191], v[220:223], v[64:67]
	s_setprio 0
	s_add_i32 s30, s60, s40
	v_lshl_add_u64 v[164:165], v[164:165], 0, s[6:7]
	s_mov_b32 m0, s30
	ds_read_b128 v[192:195], v158 offset:49152
	ds_read_b128 v[196:199], v158 offset:50176
	ds_read_b128 v[200:203], v158 offset:51200
	ds_read_b128 v[204:207], v158 offset:52224
	ds_read_b128 v[208:211], v158 offset:53248
	ds_read_b128 v[212:215], v158 offset:54272
	ds_read_b128 v[216:219], v158 offset:55296
	ds_read_b128 v[220:223], v158 offset:56320
	global_load_lds_dwordx4 v[164:165], off
	s_add_i32 m0, s30, 0x2000
	s_add_u32 s28, s28, 0x80080
	v_lshl_add_u64 v[164:165], v[224:225], 0, s[6:7]
	s_addc_u32 s29, s29, 0
	s_add_i32 s30, s61, s40
	global_load_lds_dwordx4 v[164:165], off
	v_lshl_add_u64 v[164:165], s[28:29], 0, v[130:131]
	s_mov_b32 m0, s30
	s_nop 0
	global_load_lds_dwordx4 v[164:165], off
	v_lshl_add_u64 v[164:165], s[28:29], 0, v[134:135]
	s_add_i32 m0, s30, 0x2000
	s_nop 0
	global_load_lds_dwordx4 v[164:165], off
	v_lshl_add_u64 v[164:165], v[226:227], 0, s[6:7]
	s_mov_b32 m0, s46
	s_nop 0
	global_load_lds_dwordx4 v[164:165], off
	v_lshl_add_u64 v[164:165], v[228:229], 0, s[6:7]
	s_mov_b32 m0, s47
	s_nop 0
	global_load_lds_dwordx4 v[164:165], off
	s_waitcnt vmcnt(8)
	s_waitcnt lgkmcnt(0)
	s_barrier
	s_setprio 1
	s_waitcnt lgkmcnt(0)
	v_mfma_f32_16x16x32_bf16 v[60:63], v[146:149], v[192:195], v[60:63]
	v_mfma_f32_16x16x32_bf16 v[56:59], v[160:163], v[192:195], v[56:59]
	v_mfma_f32_16x16x32_bf16 v[44:47], v[146:149], v[200:203], v[44:47]
	v_mfma_f32_16x16x32_bf16 v[40:43], v[160:163], v[200:203], v[40:43]
	v_mfma_f32_16x16x32_bf16 v[28:31], v[146:149], v[208:211], v[28:31]
	v_mfma_f32_16x16x32_bf16 v[24:27], v[160:163], v[208:211], v[24:27]
	v_mfma_f32_16x16x32_bf16 v[12:15], v[146:149], v[216:219], v[12:15]
	v_mfma_f32_16x16x32_bf16 v[8:11], v[160:163], v[216:219], v[8:11]
	v_mfma_f32_16x16x32_bf16 v[60:63], v[150:153], v[196:199], v[60:63]
	v_mfma_f32_16x16x32_bf16 v[56:59], v[168:171], v[196:199], v[56:59]
	v_mfma_f32_16x16x32_bf16 v[44:47], v[150:153], v[204:207], v[44:47]
	v_mfma_f32_16x16x32_bf16 v[40:43], v[168:171], v[204:207], v[40:43]
	v_mfma_f32_16x16x32_bf16 v[28:31], v[150:153], v[212:215], v[28:31]
	v_mfma_f32_16x16x32_bf16 v[24:27], v[168:171], v[212:215], v[24:27]
	v_mfma_f32_16x16x32_bf16 v[12:15], v[150:153], v[220:223], v[12:15]
	v_mfma_f32_16x16x32_bf16 v[8:11], v[168:171], v[220:223], v[8:11]
	s_setprio 0
	s_setprio 1
	v_mfma_f32_16x16x32_bf16 v[52:55], v[172:175], v[192:195], v[52:55]
	v_mfma_f32_16x16x32_bf16 v[48:51], v[184:187], v[192:195], v[48:51]
	v_mfma_f32_16x16x32_bf16 v[36:39], v[172:175], v[200:203], v[36:39]
	v_mfma_f32_16x16x32_bf16 v[32:35], v[184:187], v[200:203], v[32:35]
	v_mfma_f32_16x16x32_bf16 v[20:23], v[172:175], v[208:211], v[20:23]
	v_mfma_f32_16x16x32_bf16 v[16:19], v[184:187], v[208:211], v[16:19]
	v_mfma_f32_16x16x32_bf16 v[4:7], v[172:175], v[216:219], v[4:7]
	v_mfma_f32_16x16x32_bf16 v[0:3], v[184:187], v[216:219], v[0:3]
	v_mfma_f32_16x16x32_bf16 v[52:55], v[180:183], v[196:199], v[52:55]
	v_mfma_f32_16x16x32_bf16 v[48:51], v[188:191], v[196:199], v[48:51]
	v_mfma_f32_16x16x32_bf16 v[36:39], v[180:183], v[204:207], v[36:39]
	v_mfma_f32_16x16x32_bf16 v[32:35], v[188:191], v[204:207], v[32:35]
	v_mfma_f32_16x16x32_bf16 v[20:23], v[180:183], v[212:215], v[20:23]
	v_mfma_f32_16x16x32_bf16 v[16:19], v[188:191], v[212:215], v[16:19]
	s_setprio 2
	s_barrier
	v_mfma_f32_16x16x32_bf16 v[4:7], v[180:183], v[220:223], v[4:7]
	v_mfma_f32_16x16x32_bf16 v[0:3], v[188:191], v[220:223], v[0:3]
	s_setprio 0
	s_add_i32 s59, s59, 2
	s_add_u32 s26, s26, 0x100
	s_addc_u32 s27, s27, 0
	s_add_u32 s55, s55, 0x100
	s_addc_u32 s58, s58, 0
	s_cmp_gt_u32 s59, 13
	s_cbranch_scc0 .LBB0_890
	s_and_b64 vcc, exec, s[8:9]
	s_cbranch_vccz .LBB0_893
	s_barrier

; #define PG8_STAGE(bufoff, gbase, voff) do { _Pragma("unroll") for (int _i = 0; _i < 2; ++_i) \
;         __builtin_amdgcn_global_load_lds((const unsigned*)((const char*)(gbase) + (voff)[_i]), (LAS unsigned*)(lds + (bufoff) + ldsw + _i * 8192), 16, 0, 0); } while (0)
; #define PG8_LDA(dst, b, h) do { _Pragma("unroll") for (int m = 0; m < 4; ++m) _Pragma("unroll") for (int k = 0; k < 2; ++k) dst[m][k] = *(const LAS bf16x8*)(lds + PG8_SA(b, h) + aoff + m * 2048 + k * 1024); } while (0)
; #define PG8_LDB(dst, b, h) do { _Pragma("unroll") for (int n = 0; n < 2; ++n) _Pragma("unroll") for (int k = 0; k < 2; ++k) dst[n][k] = *(const LAS bf16x8*)(lds + PG8_SB(b, h) + boff + n * 2048 + k * 1024); } while (0)
; #define PG8_MMA(ai, bj, At, Bt) do { __builtin_amdgcn_s_setprio(1); _Pragma("unroll") for (int m = 0; m < 4; ++m) _Pragma("unroll") for (int n = 0; n < 2; ++n) _Pragma("unroll") for (int k = 0; k < 2; ++k) \
;         acc[ai][bj][m][n] = __builtin_amdgcn_mfma_f32_16x16x32_bf16(Bt[n][k], At[m][k], acc[ai][bj][m][n], 0, 0, 0); __builtin_amdgcn_s_setprio(0); } while (0)
; #define PG8_WAIT_V(n) asm volatile("s_waitcnt vmcnt(" #n ")" ::: "memory")
; #define PG8_WAIT_L(n) asm volatile("s_waitcnt lgkmcnt(" #n ")" ::: "memory")
; #define PG8_BAR __builtin_amdgcn_s_barrier()
; #define PG8_SCHED __builtin_amdgcn_sched_barrier(0)
; template <class Epi, class Sched, bool ALIGN_EPI = true, bool SP2 = true>
; __device__ __forceinline__ void gemm_phase(LAS unsigned char* lds, const bf16_t* Ag, const bf16_t* Btg, const int K, const int lda, const int ldb, const Sched& S, const Epi& E) {
;     ...
;             const bool last = (t == nt - 2);
;             const char* a1 = cA + (size_t)(t + 1) * kstep;
;             const char* a2 = last ? nA : cA + (size_t)(t + 2) * kstep; const char* b2 = last ? nB : cB + (size_t)(t + 2) * kstep;
;             const char* a3 = a2 + kstep; const char* b3 = b2 + kstep;
;             if constexpr (SP2) {
;             PG8_LDB(B0, 0, 0); PG8_LDB(B1, 0, 1); PG8_SCHED; PG8_LDA(At, 0, 0); PG8_STAGE(PG8_SA(1, 1), a1 + hstepA, voffA);
;             PG8_WAIT_V(8); PG8_WAIT_L(0); PG8_BAR; PG8_MMA(0, 0, At, B0); PG8_MMA(0, 1, At, B1); PG8_BAR; PG8_SCHED;
;             PG8_LDA(At, 0, 1); PG8_STAGE(PG8_SB(0, 0), b2, voffB); PG8_STAGE(PG8_SB(0, 1), b2 + hstepB, voffB); PG8_STAGE(PG8_SA(0, 0), a2, voffA);
.LBB0_969:
	ds_read_b128 v[152:155], v149
	ds_read_b128 v[156:159], v149 offset:1024
	ds_read_b128 v[160:163], v149 offset:2048
	ds_read_b128 v[168:171], v149 offset:3072
	ds_read_b128 v[172:175], v150
	ds_read_b128 v[180:183], v150 offset:1024
	ds_read_b128 v[184:187], v150 offset:2048
	ds_read_b128 v[188:191], v150 offset:3072
	s_add_u32 s26, s24, 0xfff80080
	s_addc_u32 s27, s25, -1
	s_cmp_eq_u32 s54, 28
	s_cselect_b32 s29, s33, s27
	s_cselect_b32 s28, s47, s26
	s_cselect_b32 s27, s50, s53
	s_cselect_b32 s26, s51, s52
	v_lshl_add_u64 v[146:147], s[24:25], 0, v[138:139]
	s_add_i32 m0, s34, 0xc000
	ds_read_b128 v[192:195], v151
	ds_read_b128 v[196:199], v151 offset:1024
	ds_read_b128 v[200:203], v151 offset:2048
	ds_read_b128 v[204:207], v151 offset:3072
	ds_read_b128 v[208:211], v151 offset:4096
	ds_read_b128 v[212:215], v151 offset:5120
	ds_read_b128 v[216:219], v151 offset:6144
	ds_read_b128 v[220:223], v151 offset:7168
	global_load_lds_dwordx4 v[146:147], off
	v_lshl_add_u64 v[146:147], s[24:25], 0, v[140:141]
	s_add_i32 m0, s34, 0xe000
	s_nop 0
	global_load_lds_dwordx4 v[146:147], off
	s_waitcnt vmcnt(8)
	s_waitcnt lgkmcnt(0)
	s_barrier
	s_setprio 1
	s_waitcnt lgkmcnt(0)
	v_mfma_f32_16x16x32_bf16 v[124:127], v[152:155], v[192:195], v[124:127]
	v_mfma_f32_16x16x32_bf16 v[120:123], v[160:163], v[192:195], v[120:123]
	v_mfma_f32_16x16x32_bf16 v[116:119], v[152:155], v[200:203], v[116:119]
	v_mfma_f32_16x16x32_bf16 v[108:111], v[160:163], v[200:203], v[108:111]
	v_mfma_f32_16x16x32_bf16 v[92:95], v[152:155], v[208:211], v[92:95]
	v_mfma_f32_16x16x32_bf16 v[88:91], v[160:163], v[208:211], v[88:91]
	v_mfma_f32_16x16x32_bf16 v[76:79], v[152:155], v[216:219], v[76:79]
	v_mfma_f32_16x16x32_bf16 v[72:75], v[160:163], v[216:219], v[72:75]
	v_mfma_f32_16x16x32_bf16 v[124:127], v[156:159], v[196:199], v[124:127]
	v_mfma_f32_16x16x32_bf16 v[120:123], v[168:171], v[196:199], v[120:123]
	v_mfma_f32_16x16x32_bf16 v[116:119], v[156:159], v[204:207], v[116:119]
	v_mfma_f32_16x16x32_bf16 v[108:111], v[168:171], v[204:207], v[108:111]
	v_mfma_f32_16x16x32_bf16 v[92:95], v[156:159], v[212:215], v[92:95]
	v_mfma_f32_16x16x32_bf16 v[88:91], v[168:171], v[212:215], v[88:91]
	v_mfma_f32_16x16x32_bf16 v[76:79], v[156:159], v[220:223], v[76:79]
	v_mfma_f32_16x16x32_bf16 v[72:75], v[168:171], v[220:223], v[72:75]
	s_setprio 0
	s_setprio 1
	v_mfma_f32_16x16x32_bf16 v[112:115], v[172:175], v[192:195], v[112:115]
	v_mfma_f32_16x16x32_bf16 v[104:107], v[184:187], v[192:195], v[104:107]
	v_mfma_f32_16x16x32_bf16 v[100:103], v[172:175], v[200:203], v[100:103]
	v_mfma_f32_16x16x32_bf16 v[96:99], v[184:187], v[200:203], v[96:99]
	v_mfma_f32_16x16x32_bf16 v[84:87], v[172:175], v[208:211], v[84:87]
	v_mfma_f32_16x16x32_bf16 v[80:83], v[184:187], v[208:211], v[80:83]
	v_mfma_f32_16x16x32_bf16 v[68:71], v[172:175], v[216:219], v[68:71]
	v_mfma_f32_16x16x32_bf16 v[64:67], v[184:187], v[216:219], v[64:67]
	v_mfma_f32_16x16x32_bf16 v[112:115], v[180:183], v[196:199], v[112:115]
	v_mfma_f32_16x16x32_bf16 v[104:107], v[188:191], v[196:199], v[104:107]
	v_mfma_f32_16x16x32_bf16 v[100:103], v[180:183], v[204:207], v[100:103]
	v_mfma_f32_16x16x32_bf16 v[96:99], v[188:191], v[204:207], v[96:99]
	v_mfma_f32_16x16x32_bf16 v[84:87], v[180:183], v[212:215], v[84:87]
	v_mfma_f32_16x16x32_bf16 v[80:83], v[188:191], v[212:215], v[80:83]
	s_setprio 2
	s_barrier
	v_mfma_f32_16x16x32_bf16 v[68:71], v[180:183], v[220:223], v[68:71]
	v_mfma_f32_16x16x32_bf16 v[64:67], v[188:191], v[220:223], v[64:67]
	s_setprio 0
	s_add_i32 s55, s44, s31
	v_lshl_add_u64 v[146:147], s[26:27], 0, v[130:131]
	s_mov_b32 m0, s55
	ds_read_b128 v[192:195], v151 offset:16384
	ds_read_b128 v[196:199], v151 offset:17408
	ds_read_b128 v[200:203], v151 offset:18432
	ds_read_b128 v[204:207], v151 offset:19456
	ds_read_b128 v[208:211], v151 offset:20480
	ds_read_b128 v[212:215], v151 offset:21504
	ds_read_b128 v[216:219], v151 offset:22528
	ds_read_b128 v[220:223], v151 offset:23552
	global_load_lds_dwordx4 v[146:147], off
	s_add_i32 m0, s55, 0x2000
	s_add_u32 s58, s26, 0x80000
	v_lshl_add_u64 v[164:165], s[26:27], 0, v[134:135]
	s_addc_u32 s59, s27, 0
	s_add_i32 s55, s45, s31
	global_load_lds_dwordx4 v[164:165], off
	v_lshl_add_u64 v[224:225], s[58:59], 0, v[130:131]
	s_mov_b32 m0, s55
	v_lshl_add_u64 v[226:227], s[28:29], 0, v[132:133]
	global_load_lds_dwordx4 v[224:225], off
	v_lshl_add_u64 v[224:225], s[58:59], 0, v[134:135]
	s_add_i32 m0, s55, 0x2000
	s_nop 0
	global_load_lds_dwordx4 v[224:225], off
	v_lshl_add_u64 v[224:225], s[28:29], 0, v[128:129]
	s_mov_b32 m0, s34
	s_nop 0
	global_load_lds_dwordx4 v[224:225], off
	s_mov_b32 m0, s35
	s_nop 0
	global_load_lds_dwordx4 v[226:227], off
	s_waitcnt vmcnt(8)
	s_waitcnt lgkmcnt(0)
	s_barrier
; #define PG8_STAGE(bufoff, gbase, voff) do { _Pragma("unroll") for (int _i = 0; _i < 2; ++_i) \
;         __builtin_amdgcn_global_load_lds((const unsigned*)((const char*)(gbase) + (voff)[_i]), (LAS unsigned*)(lds + (bufoff) + ldsw + _i * 8192), 16, 0, 0); } while (0)
; #define PG8_LDA(dst, b, h) do { _Pragma("unroll") for (int m = 0; m < 4; ++m) _Pragma("unroll") for (int k = 0; k < 2; ++k) dst[m][k] = *(const LAS bf16x8*)(lds + PG8_SA(b, h) + aoff + m * 2048 + k * 1024); } while (0)
; #define PG8_LDB(dst, b, h) do { _Pragma("unroll") for (int n = 0; n < 2; ++n) _Pragma("unroll") for (int k = 0; k < 2; ++k) dst[n][k] = *(const LAS bf16x8*)(lds + PG8_SB(b, h) + boff + n * 2048 + k * 1024); } while (0)
; #define PG8_MMA(ai, bj, At, Bt) do { __builtin_amdgcn_s_setprio(1); _Pragma("unroll") for (int m = 0; m < 4; ++m) _Pragma("unroll") for (int n = 0; n < 2; ++n) _Pragma("unroll") for (int k = 0; k < 2; ++k) \
;         acc[ai][bj][m][n] = __builtin_amdgcn_mfma_f32_16x16x32_bf16(Bt[n][k], At[m][k], acc[ai][bj][m][n], 0, 0, 0); __builtin_amdgcn_s_setprio(0); } while (0)
; #define PG8_WAIT_V(n) asm volatile("s_waitcnt vmcnt(" #n ")" ::: "memory")
; #define PG8_WAIT_L(n) asm volatile("s_waitcnt lgkmcnt(" #n ")" ::: "memory")
; #define PG8_BAR __builtin_amdgcn_s_barrier()
; #define PG8_SCHED __builtin_amdgcn_sched_barrier(0)
; template <class Epi, class Sched, bool ALIGN_EPI = true, bool SP2 = true>
; __device__ __forceinline__ void gemm_phase(LAS unsigned char* lds, const bf16_t* Ag, const bf16_t* Btg, const int K, const int lda, const int ldb, const Sched& S, const Epi& E) {
;     ...
;             PG8_WAIT_V(8); PG8_WAIT_L(0); PG8_BAR; PG8_MMA(1, 0, At, B0); PG8_MMA(1, 1, At, B1); PG8_BAR; PG8_SCHED;
;             PG8_LDB(B0, 1, 0); PG8_LDB(B1, 1, 1); PG8_SCHED; PG8_LDA(At, 1, 0); PG8_STAGE(PG8_SA(0, 1), a2 + hstepA, voffA);
;             PG8_WAIT_V(8); PG8_WAIT_L(0); PG8_BAR; PG8_MMA(0, 0, At, B0); PG8_MMA(0, 1, At, B1); PG8_BAR; PG8_SCHED;
	s_setprio 1
	s_waitcnt lgkmcnt(0)
	v_mfma_f32_16x16x32_bf16 v[60:63], v[152:155], v[192:195], v[60:63]
	v_mfma_f32_16x16x32_bf16 v[56:59], v[160:163], v[192:195], v[56:59]
	v_mfma_f32_16x16x32_bf16 v[44:47], v[152:155], v[200:203], v[44:47]
	v_mfma_f32_16x16x32_bf16 v[40:43], v[160:163], v[200:203], v[40:43]
	v_mfma_f32_16x16x32_bf16 v[28:31], v[152:155], v[208:211], v[28:31]
	v_mfma_f32_16x16x32_bf16 v[24:27], v[160:163], v[208:211], v[24:27]
	v_mfma_f32_16x16x32_bf16 v[12:15], v[152:155], v[216:219], v[12:15]
	v_mfma_f32_16x16x32_bf16 v[8:11], v[160:163], v[216:219], v[8:11]
	v_mfma_f32_16x16x32_bf16 v[60:63], v[156:159], v[196:199], v[60:63]
	v_mfma_f32_16x16x32_bf16 v[56:59], v[168:171], v[196:199], v[56:59]
	v_mfma_f32_16x16x32_bf16 v[44:47], v[156:159], v[204:207], v[44:47]
	v_mfma_f32_16x16x32_bf16 v[40:43], v[168:171], v[204:207], v[40:43]
	v_mfma_f32_16x16x32_bf16 v[28:31], v[156:159], v[212:215], v[28:31]
	v_mfma_f32_16x16x32_bf16 v[24:27], v[168:171], v[212:215], v[24:27]
	v_mfma_f32_16x16x32_bf16 v[12:15], v[156:159], v[220:223], v[12:15]
	v_mfma_f32_16x16x32_bf16 v[8:11], v[168:171], v[220:223], v[8:11]
	s_setprio 0
	s_setprio 1
	v_mfma_f32_16x16x32_bf16 v[52:55], v[172:175], v[192:195], v[52:55]
	v_mfma_f32_16x16x32_bf16 v[48:51], v[184:187], v[192:195], v[48:51]
	v_mfma_f32_16x16x32_bf16 v[36:39], v[172:175], v[200:203], v[36:39]
	v_mfma_f32_16x16x32_bf16 v[32:35], v[184:187], v[200:203], v[32:35]
	v_mfma_f32_16x16x32_bf16 v[20:23], v[172:175], v[208:211], v[20:23]
	v_mfma_f32_16x16x32_bf16 v[16:19], v[184:187], v[208:211], v[16:19]
	v_mfma_f32_16x16x32_bf16 v[4:7], v[172:175], v[216:219], v[4:7]
	v_mfma_f32_16x16x32_bf16 v[0:3], v[184:187], v[216:219], v[0:3]
	v_mfma_f32_16x16x32_bf16 v[52:55], v[180:183], v[196:199], v[52:55]
	v_mfma_f32_16x16x32_bf16 v[48:51], v[188:191], v[196:199], v[48:51]
	v_mfma_f32_16x16x32_bf16 v[36:39], v[180:183], v[204:207], v[36:39]
	v_mfma_f32_16x16x32_bf16 v[32:35], v[188:191], v[204:207], v[32:35]
	v_mfma_f32_16x16x32_bf16 v[20:23], v[180:183], v[212:215], v[20:23]
	v_mfma_f32_16x16x32_bf16 v[16:19], v[188:191], v[212:215], v[16:19]
	s_setprio 2
	s_barrier
	v_mfma_f32_16x16x32_bf16 v[4:7], v[180:183], v[220:223], v[4:7]
	v_mfma_f32_16x16x32_bf16 v[0:3], v[188:191], v[220:223], v[0:3]
	s_setprio 0
	s_add_i32 s55, 0, 0x18000
	s_add_i32 s58, 0, 0x1c000
	v_add_u32_e32 v168, s55, v148
	v_add_u32_e32 v188, s58, v148
	ds_read_b128 v[152:155], v168
	ds_read_b128 v[156:159], v168 offset:1024
	ds_read_b128 v[160:163], v168 offset:2048
	ds_read_b128 v[168:171], v168 offset:3072
	ds_read_b128 v[172:175], v188
	ds_read_b128 v[180:183], v188 offset:1024
	ds_read_b128 v[184:187], v188 offset:2048
	ds_read_b128 v[188:191], v188 offset:3072
	s_add_u32 s28, s28, 0x80000
	s_addc_u32 s29, s29, 0
	s_mov_b32 m0, s37
	v_lshl_add_u64 v[228:229], s[28:29], 0, v[128:129]
	ds_read_b128 v[192:195], v151 offset:32768
	ds_read_b128 v[196:199], v151 offset:33792
	ds_read_b128 v[200:203], v151 offset:34816
	ds_read_b128 v[204:207], v151 offset:35840
	ds_read_b128 v[208:211], v151 offset:36864
	ds_read_b128 v[212:215], v151 offset:37888
	ds_read_b128 v[216:219], v151 offset:38912
	ds_read_b128 v[220:223], v151 offset:39936
	global_load_lds_dwordx4 v[228:229], off
	v_lshl_add_u64 v[228:229], s[28:29], 0, v[132:133]
	s_mov_b32 m0, s38
	s_nop 0
	global_load_lds_dwordx4 v[228:229], off
	s_waitcnt vmcnt(8)
	s_waitcnt lgkmcnt(0)
	s_barrier
	s_setprio 1
	s_waitcnt lgkmcnt(0)
	v_mfma_f32_16x16x32_bf16 v[124:127], v[152:155], v[192:195], v[124:127]
	v_mfma_f32_16x16x32_bf16 v[120:123], v[160:163], v[192:195], v[120:123]
	v_mfma_f32_16x16x32_bf16 v[116:119], v[152:155], v[200:203], v[116:119]
	v_mfma_f32_16x16x32_bf16 v[108:111], v[160:163], v[200:203], v[108:111]
	v_mfma_f32_16x16x32_bf16 v[92:95], v[152:155], v[208:211], v[92:95]
	v_mfma_f32_16x16x32_bf16 v[88:91], v[160:163], v[208:211], v[88:91]
	v_mfma_f32_16x16x32_bf16 v[76:79], v[152:155], v[216:219], v[76:79]
	v_mfma_f32_16x16x32_bf16 v[72:75], v[160:163], v[216:219], v[72:75]
	v_mfma_f32_16x16x32_bf16 v[124:127], v[156:159], v[196:199], v[124:127]
	v_mfma_f32_16x16x32_bf16 v[120:123], v[168:171], v[196:199], v[120:123]
	v_mfma_f32_16x16x32_bf16 v[116:119], v[156:159], v[204:207], v[116:119]
	v_mfma_f32_16x16x32_bf16 v[108:111], v[168:171], v[204:207], v[108:111]
	v_mfma_f32_16x16x32_bf16 v[92:95], v[156:159], v[212:215], v[92:95]
	v_mfma_f32_16x16x32_bf16 v[88:91], v[168:171], v[212:215], v[88:91]
	v_mfma_f32_16x16x32_bf16 v[76:79], v[156:159], v[220:223], v[76:79]
	v_mfma_f32_16x16x32_bf16 v[72:75], v[168:171], v[220:223], v[72:75]
	s_setprio 0
	s_setprio 1
	v_mfma_f32_16x16x32_bf16 v[112:115], v[172:175], v[192:195], v[112:115]
	v_mfma_f32_16x16x32_bf16 v[104:107], v[184:187], v[192:195], v[104:107]
	v_mfma_f32_16x16x32_bf16 v[100:103], v[172:175], v[200:203], v[100:103]
	v_mfma_f32_16x16x32_bf16 v[96:99], v[184:187], v[200:203], v[96:99]
	v_mfma_f32_16x16x32_bf16 v[84:87], v[172:175], v[208:211], v[84:87]
	v_mfma_f32_16x16x32_bf16 v[80:83], v[184:187], v[208:211], v[80:83]
	v_mfma_f32_16x16x32_bf16 v[68:71], v[172:175], v[216:219], v[68:71]
	v_mfma_f32_16x16x32_bf16 v[64:67], v[184:187], v[216:219], v[64:67]
	v_mfma_f32_16x16x32_bf16 v[112:115], v[180:183], v[196:199], v[112:115]
	v_mfma_f32_16x16x32_bf16 v[104:107], v[188:191], v[196:199], v[104:107]
	v_mfma_f32_16x16x32_bf16 v[100:103], v[180:183], v[204:207], v[100:103]
	v_mfma_f32_16x16x32_bf16 v[96:99], v[188:191], v[204:207], v[96:99]
	v_mfma_f32_16x16x32_bf16 v[84:87], v[180:183], v[212:215], v[84:87]
	v_mfma_f32_16x16x32_bf16 v[80:83], v[188:191], v[212:215], v[80:83]
	s_setprio 2
	s_barrier
; #define PG8_STAGE(bufoff, gbase, voff) do { _Pragma("unroll") for (int _i = 0; _i < 2; ++_i) \
;         __builtin_amdgcn_global_load_lds((const unsigned*)((const char*)(gbase) + (voff)[_i]), (LAS unsigned*)(lds + (bufoff) + ldsw + _i * 8192), 16, 0, 0); } while (0)
; #define PG8_LDA(dst, b, h) do { _Pragma("unroll") for (int m = 0; m < 4; ++m) _Pragma("unroll") for (int k = 0; k < 2; ++k) dst[m][k] = *(const LAS bf16x8*)(lds + PG8_SA(b, h) + aoff + m * 2048 + k * 1024); } while (0)
; #define PG8_MMA(ai, bj, At, Bt) do { __builtin_amdgcn_s_setprio(1); _Pragma("unroll") for (int m = 0; m < 4; ++m) _Pragma("unroll") for (int n = 0; n < 2; ++n) _Pragma("unroll") for (int k = 0; k < 2; ++k) \
;         acc[ai][bj][m][n] = __builtin_amdgcn_mfma_f32_16x16x32_bf16(Bt[n][k], At[m][k], acc[ai][bj][m][n], 0, 0, 0); __builtin_amdgcn_s_setprio(0); } while (0)
; #define PG8_WAIT_V(n) asm volatile("s_waitcnt vmcnt(" #n ")" ::: "memory")
; #define PG8_WAIT_L(n) asm volatile("s_waitcnt lgkmcnt(" #n ")" ::: "memory")
; #define PG8_BAR __builtin_amdgcn_s_barrier()
; #define PG8_SCHED __builtin_amdgcn_sched_barrier(0)
; template <class Epi, class Sched, bool ALIGN_EPI = true, bool SP2 = true>
; __device__ __forceinline__ void gemm_phase(LAS unsigned char* lds, const bf16_t* Ag, const bf16_t* Btg, const int K, const int lda, const int ldb, const Sched& S, const Epi& E) {
;     ...
;             PG8_WAIT_V(8); PG8_WAIT_L(0); PG8_BAR; PG8_MMA(0, 0, At, B0); PG8_MMA(0, 1, At, B1); PG8_BAR; PG8_SCHED;
;             PG8_LDA(At, 1, 1); PG8_STAGE(PG8_SB(1, 0), b3, voffB); PG8_STAGE(PG8_SB(1, 1), b3 + hstepB, voffB); PG8_STAGE(PG8_SA(1, 0), a3, voffA);
;             PG8_WAIT_V(8); PG8_WAIT_L(0); PG8_BAR; PG8_MMA(1, 0, At, B0); PG8_MMA(1, 1, At, B1); PG8_BAR; PG8_SCHED;
	v_mfma_f32_16x16x32_bf16 v[68:71], v[180:183], v[220:223], v[68:71]
	v_mfma_f32_16x16x32_bf16 v[64:67], v[188:191], v[220:223], v[64:67]
	s_setprio 0
	s_add_i32 s28, s55, s31
	v_lshl_add_u64 v[146:147], v[146:147], 0, s[6:7]
	s_mov_b32 m0, s28
	ds_read_b128 v[192:195], v151 offset:49152
	ds_read_b128 v[196:199], v151 offset:50176
	ds_read_b128 v[200:203], v151 offset:51200
	ds_read_b128 v[204:207], v151 offset:52224
	ds_read_b128 v[208:211], v151 offset:53248
	ds_read_b128 v[212:215], v151 offset:54272
	ds_read_b128 v[216:219], v151 offset:55296
	ds_read_b128 v[220:223], v151 offset:56320
	global_load_lds_dwordx4 v[146:147], off
	s_add_i32 m0, s28, 0x2000
	s_add_u32 s26, s26, 0x80080
	v_lshl_add_u64 v[146:147], v[164:165], 0, s[6:7]
	s_addc_u32 s27, s27, 0
	s_add_i32 s28, s58, s31
	global_load_lds_dwordx4 v[146:147], off
	v_lshl_add_u64 v[146:147], s[26:27], 0, v[130:131]
	s_mov_b32 m0, s28
	s_nop 0
	global_load_lds_dwordx4 v[146:147], off
	v_lshl_add_u64 v[146:147], s[26:27], 0, v[134:135]
	s_add_i32 m0, s28, 0x2000
	s_nop 0
	global_load_lds_dwordx4 v[146:147], off
	v_lshl_add_u64 v[146:147], v[224:225], 0, s[6:7]
	s_mov_b32 m0, s40
	s_nop 0
	global_load_lds_dwordx4 v[146:147], off
	v_lshl_add_u64 v[146:147], v[226:227], 0, s[6:7]
	s_mov_b32 m0, s41
	s_nop 0
	global_load_lds_dwordx4 v[146:147], off
	s_waitcnt vmcnt(8)
	s_waitcnt lgkmcnt(0)
	s_barrier
	s_setprio 1
	s_waitcnt lgkmcnt(0)
	v_mfma_f32_16x16x32_bf16 v[60:63], v[152:155], v[192:195], v[60:63]
	v_mfma_f32_16x16x32_bf16 v[56:59], v[160:163], v[192:195], v[56:59]
	v_mfma_f32_16x16x32_bf16 v[44:47], v[152:155], v[200:203], v[44:47]
	v_mfma_f32_16x16x32_bf16 v[40:43], v[160:163], v[200:203], v[40:43]
	v_mfma_f32_16x16x32_bf16 v[28:31], v[152:155], v[208:211], v[28:31]
	v_mfma_f32_16x16x32_bf16 v[24:27], v[160:163], v[208:211], v[24:27]
	v_mfma_f32_16x16x32_bf16 v[12:15], v[152:155], v[216:219], v[12:15]
	v_mfma_f32_16x16x32_bf16 v[8:11], v[160:163], v[216:219], v[8:11]
	v_mfma_f32_16x16x32_bf16 v[60:63], v[156:159], v[196:199], v[60:63]
	v_mfma_f32_16x16x32_bf16 v[56:59], v[168:171], v[196:199], v[56:59]
	v_mfma_f32_16x16x32_bf16 v[44:47], v[156:159], v[204:207], v[44:47]
	v_mfma_f32_16x16x32_bf16 v[40:43], v[168:171], v[204:207], v[40:43]
	v_mfma_f32_16x16x32_bf16 v[28:31], v[156:159], v[212:215], v[28:31]
	v_mfma_f32_16x16x32_bf16 v[24:27], v[168:171], v[212:215], v[24:27]
	v_mfma_f32_16x16x32_bf16 v[12:15], v[156:159], v[220:223], v[12:15]
	v_mfma_f32_16x16x32_bf16 v[8:11], v[168:171], v[220:223], v[8:11]
	s_setprio 0
	s_setprio 1
	v_mfma_f32_16x16x32_bf16 v[52:55], v[172:175], v[192:195], v[52:55]
	v_mfma_f32_16x16x32_bf16 v[48:51], v[184:187], v[192:195], v[48:51]
	v_mfma_f32_16x16x32_bf16 v[36:39], v[172:175], v[200:203], v[36:39]
	v_mfma_f32_16x16x32_bf16 v[32:35], v[184:187], v[200:203], v[32:35]
	v_mfma_f32_16x16x32_bf16 v[20:23], v[172:175], v[208:211], v[20:23]
	v_mfma_f32_16x16x32_bf16 v[16:19], v[184:187], v[208:211], v[16:19]
	v_mfma_f32_16x16x32_bf16 v[4:7], v[172:175], v[216:219], v[4:7]
	v_mfma_f32_16x16x32_bf16 v[0:3], v[184:187], v[216:219], v[0:3]
	v_mfma_f32_16x16x32_bf16 v[52:55], v[180:183], v[196:199], v[52:55]
	v_mfma_f32_16x16x32_bf16 v[48:51], v[188:191], v[196:199], v[48:51]
	v_mfma_f32_16x16x32_bf16 v[36:39], v[180:183], v[204:207], v[36:39]
	v_mfma_f32_16x16x32_bf16 v[32:35], v[188:191], v[204:207], v[32:35]
	v_mfma_f32_16x16x32_bf16 v[20:23], v[180:183], v[212:215], v[20:23]
	v_mfma_f32_16x16x32_bf16 v[16:19], v[188:191], v[212:215], v[16:19]
	s_setprio 2
	s_barrier
	v_mfma_f32_16x16x32_bf16 v[4:7], v[180:183], v[220:223], v[4:7]
	v_mfma_f32_16x16x32_bf16 v[0:3], v[188:191], v[220:223], v[0:3]
	s_setprio 0
	s_add_i32 s54, s54, 2
	s_add_u32 s24, s24, 0x100
	s_addc_u32 s25, s25, 0
	s_add_u32 s52, s52, 0x100
	s_addc_u32 s53, s53, 0
	s_cmp_gt_u32 s54, 29
	s_cbranch_scc0 .LBB0_969
	s_and_b64 vcc, exec, s[8:9]
	s_cbranch_vccz .LBB0_972
	s_barrier

; #define PG8_STAGE(bufoff, gbase, voff) do { _Pragma("unroll") for (int _i = 0; _i < 2; ++_i) \
;         __builtin_amdgcn_global_load_lds((const unsigned*)((const char*)(gbase) + (voff)[_i]), (LAS unsigned*)(lds + (bufoff) + ldsw + _i * 8192), 16, 0, 0); } while (0)
; #define PG8_LDA(dst, b, h) do { _Pragma("unroll") for (int m = 0; m < 4; ++m) _Pragma("unroll") for (int k = 0; k < 2; ++k) dst[m][k] = *(const LAS bf16x8*)(lds + PG8_SA(b, h) + aoff + m * 2048 + k * 1024); } while (0)
; #define PG8_LDB(dst, b, h) do { _Pragma("unroll") for (int n = 0; n < 2; ++n) _Pragma("unroll") for (int k = 0; k < 2; ++k) dst[n][k] = *(const LAS bf16x8*)(lds + PG8_SB(b, h) + boff + n * 2048 + k * 1024); } while (0)
; #define PG8_MMA(ai, bj, At, Bt) do { __builtin_amdgcn_s_setprio(1); _Pragma("unroll") for (int m = 0; m < 4; ++m) _Pragma("unroll") for (int n = 0; n < 2; ++n) _Pragma("unroll") for (int k = 0; k < 2; ++k) \
;         acc[ai][bj][m][n] = __builtin_amdgcn_mfma_f32_16x16x32_bf16(Bt[n][k], At[m][k], acc[ai][bj][m][n], 0, 0, 0); __builtin_amdgcn_s_setprio(0); } while (0)
; #define PG8_WAIT_V(n) asm volatile("s_waitcnt vmcnt(" #n ")" ::: "memory")
; #define PG8_WAIT_L(n) asm volatile("s_waitcnt lgkmcnt(" #n ")" ::: "memory")
; #define PG8_BAR __builtin_amdgcn_s_barrier()
; #define PG8_SCHED __builtin_amdgcn_sched_barrier(0)
; template <class Epi, class Sched, bool ALIGN_EPI = true, bool SP2 = true>
; __device__ __forceinline__ void gemm_phase(LAS unsigned char* lds, const bf16_t* Ag, const bf16_t* Btg, const int K, const int lda, const int ldb, const Sched& S, const Epi& E) {
;     ...
;             const char* a2 = last ? nA : cA + (size_t)(t + 2) * kstep; const char* b2 = last ? nB : cB + (size_t)(t + 2) * kstep;
;             const char* a3 = a2 + kstep; const char* b3 = b2 + kstep;
;             if constexpr (SP2) {
;             PG8_LDB(B0, 0, 0); PG8_LDB(B1, 0, 1); PG8_SCHED; PG8_LDA(At, 0, 0); PG8_STAGE(PG8_SA(1, 1), a1 + hstepA, voffA);
;             PG8_WAIT_V(8); PG8_WAIT_L(0); PG8_BAR; PG8_MMA(0, 0, At, B0); PG8_MMA(0, 1, At, B1); PG8_BAR; PG8_SCHED;
;             PG8_LDA(At, 0, 1); PG8_STAGE(PG8_SB(0, 0), b2, voffB); PG8_STAGE(PG8_SB(0, 1), b2 + hstepB, voffB); PG8_STAGE(PG8_SA(0, 0), a2, voffA);
.LBB0_1236:
	ds_read_b128 v[152:155], v149
	ds_read_b128 v[156:159], v149 offset:1024
	ds_read_b128 v[160:163], v149 offset:2048
	ds_read_b128 v[168:171], v149 offset:3072
	ds_read_b128 v[172:175], v150
	ds_read_b128 v[180:183], v150 offset:1024
	ds_read_b128 v[184:187], v150 offset:2048
	ds_read_b128 v[188:191], v150 offset:3072
	s_add_u32 s44, s42, 0xfffc0080
	s_addc_u32 s45, s43, -1
	s_cmp_eq_u32 s70, 12
	s_cselect_b32 s51, s33, s45
	s_cselect_b32 s50, s65, s44
	s_cselect_b32 s45, s66, s69
	s_cselect_b32 s44, s67, s68
	v_lshl_add_u64 v[146:147], s[42:43], 0, v[138:139]
	s_add_i32 m0, s41, 0xc000
	ds_read_b128 v[192:195], v151
	ds_read_b128 v[196:199], v151 offset:1024
	ds_read_b128 v[200:203], v151 offset:2048
	ds_read_b128 v[204:207], v151 offset:3072
	ds_read_b128 v[208:211], v151 offset:4096
	ds_read_b128 v[212:215], v151 offset:5120
	ds_read_b128 v[216:219], v151 offset:6144
	ds_read_b128 v[220:223], v151 offset:7168
	global_load_lds_dwordx4 v[146:147], off
	v_lshl_add_u64 v[146:147], s[42:43], 0, v[140:141]
	s_add_i32 m0, s41, 0xe000
	s_nop 0
	global_load_lds_dwordx4 v[146:147], off
	s_waitcnt vmcnt(8)
	s_waitcnt lgkmcnt(0)
	s_barrier
	s_setprio 1
	s_waitcnt lgkmcnt(0)
	v_mfma_f32_16x16x32_bf16 v[124:127], v[152:155], v[192:195], v[124:127]
	v_mfma_f32_16x16x32_bf16 v[120:123], v[160:163], v[192:195], v[120:123]
	v_mfma_f32_16x16x32_bf16 v[116:119], v[152:155], v[200:203], v[116:119]
	v_mfma_f32_16x16x32_bf16 v[108:111], v[160:163], v[200:203], v[108:111]
	v_mfma_f32_16x16x32_bf16 v[92:95], v[152:155], v[208:211], v[92:95]
	v_mfma_f32_16x16x32_bf16 v[88:91], v[160:163], v[208:211], v[88:91]
	v_mfma_f32_16x16x32_bf16 v[76:79], v[152:155], v[216:219], v[76:79]
	v_mfma_f32_16x16x32_bf16 v[72:75], v[160:163], v[216:219], v[72:75]
	v_mfma_f32_16x16x32_bf16 v[124:127], v[156:159], v[196:199], v[124:127]
	v_mfma_f32_16x16x32_bf16 v[120:123], v[168:171], v[196:199], v[120:123]
	v_mfma_f32_16x16x32_bf16 v[116:119], v[156:159], v[204:207], v[116:119]
	v_mfma_f32_16x16x32_bf16 v[108:111], v[168:171], v[204:207], v[108:111]
	v_mfma_f32_16x16x32_bf16 v[92:95], v[156:159], v[212:215], v[92:95]
	v_mfma_f32_16x16x32_bf16 v[88:91], v[168:171], v[212:215], v[88:91]
	v_mfma_f32_16x16x32_bf16 v[76:79], v[156:159], v[220:223], v[76:79]
	v_mfma_f32_16x16x32_bf16 v[72:75], v[168:171], v[220:223], v[72:75]
	s_setprio 0
	s_setprio 1
	v_mfma_f32_16x16x32_bf16 v[112:115], v[172:175], v[192:195], v[112:115]
	v_mfma_f32_16x16x32_bf16 v[104:107], v[184:187], v[192:195], v[104:107]
	v_mfma_f32_16x16x32_bf16 v[100:103], v[172:175], v[200:203], v[100:103]
	v_mfma_f32_16x16x32_bf16 v[96:99], v[184:187], v[200:203], v[96:99]
	v_mfma_f32_16x16x32_bf16 v[84:87], v[172:175], v[208:211], v[84:87]
	v_mfma_f32_16x16x32_bf16 v[80:83], v[184:187], v[208:211], v[80:83]
	v_mfma_f32_16x16x32_bf16 v[68:71], v[172:175], v[216:219], v[68:71]
	v_mfma_f32_16x16x32_bf16 v[64:67], v[184:187], v[216:219], v[64:67]
	v_mfma_f32_16x16x32_bf16 v[112:115], v[180:183], v[196:199], v[112:115]
	v_mfma_f32_16x16x32_bf16 v[104:107], v[188:191], v[196:199], v[104:107]
	v_mfma_f32_16x16x32_bf16 v[100:103], v[180:183], v[204:207], v[100:103]
	v_mfma_f32_16x16x32_bf16 v[96:99], v[188:191], v[204:207], v[96:99]
	v_mfma_f32_16x16x32_bf16 v[84:87], v[180:183], v[212:215], v[84:87]
	v_mfma_f32_16x16x32_bf16 v[80:83], v[188:191], v[212:215], v[80:83]
	s_setprio 2
	s_barrier
	v_mfma_f32_16x16x32_bf16 v[68:71], v[180:183], v[220:223], v[68:71]
	v_mfma_f32_16x16x32_bf16 v[64:67], v[188:191], v[220:223], v[64:67]
	s_setprio 0
	s_add_i32 s71, s60, s40
	v_lshl_add_u64 v[146:147], s[44:45], 0, v[130:131]
	s_mov_b32 m0, s71
	ds_read_b128 v[192:195], v151 offset:16384
	ds_read_b128 v[196:199], v151 offset:17408
	ds_read_b128 v[200:203], v151 offset:18432
	ds_read_b128 v[204:207], v151 offset:19456
	ds_read_b128 v[208:211], v151 offset:20480
	ds_read_b128 v[212:215], v151 offset:21504
	ds_read_b128 v[216:219], v151 offset:22528
	ds_read_b128 v[220:223], v151 offset:23552
	global_load_lds_dwordx4 v[146:147], off
	s_add_i32 m0, s71, 0x2000
	s_add_u32 s72, s44, 0x40000
	v_lshl_add_u64 v[164:165], s[44:45], 0, v[134:135]
	s_addc_u32 s73, s45, 0
	s_add_i32 s71, s61, s40
	global_load_lds_dwordx4 v[164:165], off
	v_lshl_add_u64 v[224:225], s[72:73], 0, v[130:131]
	s_mov_b32 m0, s71
	v_lshl_add_u64 v[226:227], s[50:51], 0, v[132:133]
	global_load_lds_dwordx4 v[224:225], off
	v_lshl_add_u64 v[224:225], s[72:73], 0, v[134:135]
	s_add_i32 m0, s71, 0x2000
	s_nop 0
	global_load_lds_dwordx4 v[224:225], off
	v_lshl_add_u64 v[224:225], s[50:51], 0, v[128:129]
	s_mov_b32 m0, s41
	s_nop 0
	global_load_lds_dwordx4 v[224:225], off
	s_mov_b32 m0, s46
	s_nop 0
	global_load_lds_dwordx4 v[226:227], off
	s_waitcnt vmcnt(8)
	s_waitcnt lgkmcnt(0)
	s_barrier
; #define PG8_STAGE(bufoff, gbase, voff) do { _Pragma("unroll") for (int _i = 0; _i < 2; ++_i) \
;         __builtin_amdgcn_global_load_lds((const unsigned*)((const char*)(gbase) + (voff)[_i]), (LAS unsigned*)(lds + (bufoff) + ldsw + _i * 8192), 16, 0, 0); } while (0)
; #define PG8_LDA(dst, b, h) do { _Pragma("unroll") for (int m = 0; m < 4; ++m) _Pragma("unroll") for (int k = 0; k < 2; ++k) dst[m][k] = *(const LAS bf16x8*)(lds + PG8_SA(b, h) + aoff + m * 2048 + k * 1024); } while (0)
; #define PG8_LDB(dst, b, h) do { _Pragma("unroll") for (int n = 0; n < 2; ++n) _Pragma("unroll") for (int k = 0; k < 2; ++k) dst[n][k] = *(const LAS bf16x8*)(lds + PG8_SB(b, h) + boff + n * 2048 + k * 1024); } while (0)
; #define PG8_MMA(ai, bj, At, Bt) do { __builtin_amdgcn_s_setprio(1); _Pragma("unroll") for (int m = 0; m < 4; ++m) _Pragma("unroll") for (int n = 0; n < 2; ++n) _Pragma("unroll") for (int k = 0; k < 2; ++k) \
;         acc[ai][bj][m][n] = __builtin_amdgcn_mfma_f32_16x16x32_bf16(Bt[n][k], At[m][k], acc[ai][bj][m][n], 0, 0, 0); __builtin_amdgcn_s_setprio(0); } while (0)
; #define PG8_WAIT_V(n) asm volatile("s_waitcnt vmcnt(" #n ")" ::: "memory")
; #define PG8_WAIT_L(n) asm volatile("s_waitcnt lgkmcnt(" #n ")" ::: "memory")
; #define PG8_BAR __builtin_amdgcn_s_barrier()
; #define PG8_SCHED __builtin_amdgcn_sched_barrier(0)
; template <class Epi, class Sched, bool ALIGN_EPI = true, bool SP2 = true>
; __device__ __forceinline__ void gemm_phase(LAS unsigned char* lds, const bf16_t* Ag, const bf16_t* Btg, const int K, const int lda, const int ldb, const Sched& S, const Epi& E) {
;     ...
;             PG8_WAIT_V(8); PG8_WAIT_L(0); PG8_BAR; PG8_MMA(1, 0, At, B0); PG8_MMA(1, 1, At, B1); PG8_BAR; PG8_SCHED;
;             PG8_LDB(B0, 1, 0); PG8_LDB(B1, 1, 1); PG8_SCHED; PG8_LDA(At, 1, 0); PG8_STAGE(PG8_SA(0, 1), a2 + hstepA, voffA);
;             PG8_WAIT_V(8); PG8_WAIT_L(0); PG8_BAR; PG8_MMA(0, 0, At, B0); PG8_MMA(0, 1, At, B1); PG8_BAR; PG8_SCHED;
	s_setprio 1
	s_waitcnt lgkmcnt(0)
	v_mfma_f32_16x16x32_bf16 v[60:63], v[152:155], v[192:195], v[60:63]
	v_mfma_f32_16x16x32_bf16 v[56:59], v[160:163], v[192:195], v[56:59]
	v_mfma_f32_16x16x32_bf16 v[44:47], v[152:155], v[200:203], v[44:47]
	v_mfma_f32_16x16x32_bf16 v[40:43], v[160:163], v[200:203], v[40:43]
	v_mfma_f32_16x16x32_bf16 v[28:31], v[152:155], v[208:211], v[28:31]
	v_mfma_f32_16x16x32_bf16 v[24:27], v[160:163], v[208:211], v[24:27]
	v_mfma_f32_16x16x32_bf16 v[12:15], v[152:155], v[216:219], v[12:15]
	v_mfma_f32_16x16x32_bf16 v[8:11], v[160:163], v[216:219], v[8:11]
	v_mfma_f32_16x16x32_bf16 v[60:63], v[156:159], v[196:199], v[60:63]
	v_mfma_f32_16x16x32_bf16 v[56:59], v[168:171], v[196:199], v[56:59]
	v_mfma_f32_16x16x32_bf16 v[44:47], v[156:159], v[204:207], v[44:47]
	v_mfma_f32_16x16x32_bf16 v[40:43], v[168:171], v[204:207], v[40:43]
	v_mfma_f32_16x16x32_bf16 v[28:31], v[156:159], v[212:215], v[28:31]
	v_mfma_f32_16x16x32_bf16 v[24:27], v[168:171], v[212:215], v[24:27]
	v_mfma_f32_16x16x32_bf16 v[12:15], v[156:159], v[220:223], v[12:15]
	v_mfma_f32_16x16x32_bf16 v[8:11], v[168:171], v[220:223], v[8:11]
	s_setprio 0
	s_setprio 1
	v_mfma_f32_16x16x32_bf16 v[52:55], v[172:175], v[192:195], v[52:55]
	v_mfma_f32_16x16x32_bf16 v[48:51], v[184:187], v[192:195], v[48:51]
	v_mfma_f32_16x16x32_bf16 v[36:39], v[172:175], v[200:203], v[36:39]
	v_mfma_f32_16x16x32_bf16 v[32:35], v[184:187], v[200:203], v[32:35]
	v_mfma_f32_16x16x32_bf16 v[20:23], v[172:175], v[208:211], v[20:23]
	v_mfma_f32_16x16x32_bf16 v[16:19], v[184:187], v[208:211], v[16:19]
	v_mfma_f32_16x16x32_bf16 v[4:7], v[172:175], v[216:219], v[4:7]
	v_mfma_f32_16x16x32_bf16 v[0:3], v[184:187], v[216:219], v[0:3]
	v_mfma_f32_16x16x32_bf16 v[52:55], v[180:183], v[196:199], v[52:55]
	v_mfma_f32_16x16x32_bf16 v[48:51], v[188:191], v[196:199], v[48:51]
	v_mfma_f32_16x16x32_bf16 v[36:39], v[180:183], v[204:207], v[36:39]
	v_mfma_f32_16x16x32_bf16 v[32:35], v[188:191], v[204:207], v[32:35]
	v_mfma_f32_16x16x32_bf16 v[20:23], v[180:183], v[212:215], v[20:23]
	v_mfma_f32_16x16x32_bf16 v[16:19], v[188:191], v[212:215], v[16:19]
	s_setprio 2
	s_barrier
	v_mfma_f32_16x16x32_bf16 v[4:7], v[180:183], v[220:223], v[4:7]
	v_mfma_f32_16x16x32_bf16 v[0:3], v[188:191], v[220:223], v[0:3]
	s_setprio 0
	s_add_i32 s71, 0, 0x18000
	s_add_i32 s72, 0, 0x1c000
	v_add_u32_e32 v168, s71, v148
	v_add_u32_e32 v188, s72, v148
	ds_read_b128 v[152:155], v168
	ds_read_b128 v[156:159], v168 offset:1024
	ds_read_b128 v[160:163], v168 offset:2048
	ds_read_b128 v[168:171], v168 offset:3072
	ds_read_b128 v[172:175], v188
	ds_read_b128 v[180:183], v188 offset:1024
	ds_read_b128 v[184:187], v188 offset:2048
	ds_read_b128 v[188:191], v188 offset:3072
	s_add_u32 s50, s50, 0x40000
	s_addc_u32 s51, s51, 0
	s_mov_b32 m0, s47
	v_lshl_add_u64 v[228:229], s[50:51], 0, v[128:129]
	ds_read_b128 v[192:195], v151 offset:32768
	ds_read_b128 v[196:199], v151 offset:33792
	ds_read_b128 v[200:203], v151 offset:34816
	ds_read_b128 v[204:207], v151 offset:35840
	ds_read_b128 v[208:211], v151 offset:36864
	ds_read_b128 v[212:215], v151 offset:37888
	ds_read_b128 v[216:219], v151 offset:38912
	ds_read_b128 v[220:223], v151 offset:39936
	global_load_lds_dwordx4 v[228:229], off
	v_lshl_add_u64 v[228:229], s[50:51], 0, v[132:133]
	s_mov_b32 m0, s52
	s_nop 0
	global_load_lds_dwordx4 v[228:229], off
	s_waitcnt vmcnt(8)
	s_waitcnt lgkmcnt(0)
	s_barrier
	s_setprio 1
	s_waitcnt lgkmcnt(0)
	v_mfma_f32_16x16x32_bf16 v[124:127], v[152:155], v[192:195], v[124:127]
	v_mfma_f32_16x16x32_bf16 v[120:123], v[160:163], v[192:195], v[120:123]
	v_mfma_f32_16x16x32_bf16 v[116:119], v[152:155], v[200:203], v[116:119]
	v_mfma_f32_16x16x32_bf16 v[108:111], v[160:163], v[200:203], v[108:111]
	v_mfma_f32_16x16x32_bf16 v[92:95], v[152:155], v[208:211], v[92:95]
	v_mfma_f32_16x16x32_bf16 v[88:91], v[160:163], v[208:211], v[88:91]
	v_mfma_f32_16x16x32_bf16 v[76:79], v[152:155], v[216:219], v[76:79]
	v_mfma_f32_16x16x32_bf16 v[72:75], v[160:163], v[216:219], v[72:75]
	v_mfma_f32_16x16x32_bf16 v[124:127], v[156:159], v[196:199], v[124:127]
	v_mfma_f32_16x16x32_bf16 v[120:123], v[168:171], v[196:199], v[120:123]
	v_mfma_f32_16x16x32_bf16 v[116:119], v[156:159], v[204:207], v[116:119]
	v_mfma_f32_16x16x32_bf16 v[108:111], v[168:171], v[204:207], v[108:111]
	v_mfma_f32_16x16x32_bf16 v[92:95], v[156:159], v[212:215], v[92:95]
	v_mfma_f32_16x16x32_bf16 v[88:91], v[168:171], v[212:215], v[88:91]
	v_mfma_f32_16x16x32_bf16 v[76:79], v[156:159], v[220:223], v[76:79]
	v_mfma_f32_16x16x32_bf16 v[72:75], v[168:171], v[220:223], v[72:75]
	s_setprio 0
	s_setprio 1
	v_mfma_f32_16x16x32_bf16 v[112:115], v[172:175], v[192:195], v[112:115]
	v_mfma_f32_16x16x32_bf16 v[104:107], v[184:187], v[192:195], v[104:107]
	v_mfma_f32_16x16x32_bf16 v[100:103], v[172:175], v[200:203], v[100:103]
	v_mfma_f32_16x16x32_bf16 v[96:99], v[184:187], v[200:203], v[96:99]
	v_mfma_f32_16x16x32_bf16 v[84:87], v[172:175], v[208:211], v[84:87]
	v_mfma_f32_16x16x32_bf16 v[80:83], v[184:187], v[208:211], v[80:83]
	v_mfma_f32_16x16x32_bf16 v[68:71], v[172:175], v[216:219], v[68:71]
	v_mfma_f32_16x16x32_bf16 v[64:67], v[184:187], v[216:219], v[64:67]
	v_mfma_f32_16x16x32_bf16 v[112:115], v[180:183], v[196:199], v[112:115]
	v_mfma_f32_16x16x32_bf16 v[104:107], v[188:191], v[196:199], v[104:107]
	v_mfma_f32_16x16x32_bf16 v[100:103], v[180:183], v[204:207], v[100:103]
	v_mfma_f32_16x16x32_bf16 v[96:99], v[188:191], v[204:207], v[96:99]
	v_mfma_f32_16x16x32_bf16 v[84:87], v[180:183], v[212:215], v[84:87]
	v_mfma_f32_16x16x32_bf16 v[80:83], v[188:191], v[212:215], v[80:83]
	s_setprio 2
	s_barrier
; #define PG8_STAGE(bufoff, gbase, voff) do { _Pragma("unroll") for (int _i = 0; _i < 2; ++_i) \
;         __builtin_amdgcn_global_load_lds((const unsigned*)((const char*)(gbase) + (voff)[_i]), (LAS unsigned*)(lds + (bufoff) + ldsw + _i * 8192), 16, 0, 0); } while (0)
; #define PG8_LDA(dst, b, h) do { _Pragma("unroll") for (int m = 0; m < 4; ++m) _Pragma("unroll") for (int k = 0; k < 2; ++k) dst[m][k] = *(const LAS bf16x8*)(lds + PG8_SA(b, h) + aoff + m * 2048 + k * 1024); } while (0)
; #define PG8_MMA(ai, bj, At, Bt) do { __builtin_amdgcn_s_setprio(1); _Pragma("unroll") for (int m = 0; m < 4; ++m) _Pragma("unroll") for (int n = 0; n < 2; ++n) _Pragma("unroll") for (int k = 0; k < 2; ++k) \
;         acc[ai][bj][m][n] = __builtin_amdgcn_mfma_f32_16x16x32_bf16(Bt[n][k], At[m][k], acc[ai][bj][m][n], 0, 0, 0); __builtin_amdgcn_s_setprio(0); } while (0)
; #define PG8_WAIT_V(n) asm volatile("s_waitcnt vmcnt(" #n ")" ::: "memory")
; #define PG8_WAIT_L(n) asm volatile("s_waitcnt lgkmcnt(" #n ")" ::: "memory")
; #define PG8_BAR __builtin_amdgcn_s_barrier()
; #define PG8_SCHED __builtin_amdgcn_sched_barrier(0)
; template <class Epi, class Sched, bool ALIGN_EPI = true, bool SP2 = true>
; __device__ __forceinline__ void gemm_phase(LAS unsigned char* lds, const bf16_t* Ag, const bf16_t* Btg, const int K, const int lda, const int ldb, const Sched& S, const Epi& E) {
;     ...
;             PG8_WAIT_V(8); PG8_WAIT_L(0); PG8_BAR; PG8_MMA(0, 0, At, B0); PG8_MMA(0, 1, At, B1); PG8_BAR; PG8_SCHED;
;             PG8_LDA(At, 1, 1); PG8_STAGE(PG8_SB(1, 0), b3, voffB); PG8_STAGE(PG8_SB(1, 1), b3 + hstepB, voffB); PG8_STAGE(PG8_SA(1, 0), a3, voffA);
;             PG8_WAIT_V(8); PG8_WAIT_L(0); PG8_BAR; PG8_MMA(1, 0, At, B0); PG8_MMA(1, 1, At, B1); PG8_BAR; PG8_SCHED;
	v_mfma_f32_16x16x32_bf16 v[68:71], v[180:183], v[220:223], v[68:71]
	v_mfma_f32_16x16x32_bf16 v[64:67], v[188:191], v[220:223], v[64:67]
	s_setprio 0
	s_add_i32 s50, s71, s40
	v_lshl_add_u64 v[146:147], v[146:147], 0, s[8:9]
	s_mov_b32 m0, s50
	ds_read_b128 v[192:195], v151 offset:49152
	ds_read_b128 v[196:199], v151 offset:50176
	ds_read_b128 v[200:203], v151 offset:51200
	ds_read_b128 v[204:207], v151 offset:52224
	ds_read_b128 v[208:211], v151 offset:53248
	ds_read_b128 v[212:215], v151 offset:54272
	ds_read_b128 v[216:219], v151 offset:55296
	ds_read_b128 v[220:223], v151 offset:56320
	global_load_lds_dwordx4 v[146:147], off
	s_add_i32 m0, s50, 0x2000
	s_add_u32 s44, s44, 0x40080
	v_lshl_add_u64 v[146:147], v[164:165], 0, s[8:9]
	s_addc_u32 s45, s45, 0
	s_add_i32 s50, s72, s40
	global_load_lds_dwordx4 v[146:147], off
	v_lshl_add_u64 v[146:147], s[44:45], 0, v[130:131]
	s_mov_b32 m0, s50
	s_nop 0
	global_load_lds_dwordx4 v[146:147], off
	v_lshl_add_u64 v[146:147], s[44:45], 0, v[134:135]
	s_add_i32 m0, s50, 0x2000
	s_nop 0
	global_load_lds_dwordx4 v[146:147], off
	v_lshl_add_u64 v[146:147], v[224:225], 0, s[8:9]
	s_mov_b32 m0, s54
	s_nop 0
	global_load_lds_dwordx4 v[146:147], off
	v_lshl_add_u64 v[146:147], v[226:227], 0, s[8:9]
	s_mov_b32 m0, s55
	s_nop 0
	global_load_lds_dwordx4 v[146:147], off
	s_waitcnt vmcnt(8)
	s_waitcnt lgkmcnt(0)
	s_barrier
	s_setprio 1
	s_waitcnt lgkmcnt(0)
	v_mfma_f32_16x16x32_bf16 v[60:63], v[152:155], v[192:195], v[60:63]
	v_mfma_f32_16x16x32_bf16 v[56:59], v[160:163], v[192:195], v[56:59]
	v_mfma_f32_16x16x32_bf16 v[44:47], v[152:155], v[200:203], v[44:47]
	v_mfma_f32_16x16x32_bf16 v[40:43], v[160:163], v[200:203], v[40:43]
	v_mfma_f32_16x16x32_bf16 v[28:31], v[152:155], v[208:211], v[28:31]
	v_mfma_f32_16x16x32_bf16 v[24:27], v[160:163], v[208:211], v[24:27]
	v_mfma_f32_16x16x32_bf16 v[12:15], v[152:155], v[216:219], v[12:15]
	v_mfma_f32_16x16x32_bf16 v[8:11], v[160:163], v[216:219], v[8:11]
	v_mfma_f32_16x16x32_bf16 v[60:63], v[156:159], v[196:199], v[60:63]
	v_mfma_f32_16x16x32_bf16 v[56:59], v[168:171], v[196:199], v[56:59]
	v_mfma_f32_16x16x32_bf16 v[44:47], v[156:159], v[204:207], v[44:47]
	v_mfma_f32_16x16x32_bf16 v[40:43], v[168:171], v[204:207], v[40:43]
	v_mfma_f32_16x16x32_bf16 v[28:31], v[156:159], v[212:215], v[28:31]
	v_mfma_f32_16x16x32_bf16 v[24:27], v[168:171], v[212:215], v[24:27]
	v_mfma_f32_16x16x32_bf16 v[12:15], v[156:159], v[220:223], v[12:15]
	v_mfma_f32_16x16x32_bf16 v[8:11], v[168:171], v[220:223], v[8:11]
	s_setprio 0
	s_setprio 1
	v_mfma_f32_16x16x32_bf16 v[52:55], v[172:175], v[192:195], v[52:55]
	v_mfma_f32_16x16x32_bf16 v[48:51], v[184:187], v[192:195], v[48:51]
	v_mfma_f32_16x16x32_bf16 v[36:39], v[172:175], v[200:203], v[36:39]
	v_mfma_f32_16x16x32_bf16 v[32:35], v[184:187], v[200:203], v[32:35]
	v_mfma_f32_16x16x32_bf16 v[20:23], v[172:175], v[208:211], v[20:23]
	v_mfma_f32_16x16x32_bf16 v[16:19], v[184:187], v[208:211], v[16:19]
	v_mfma_f32_16x16x32_bf16 v[4:7], v[172:175], v[216:219], v[4:7]
	v_mfma_f32_16x16x32_bf16 v[0:3], v[184:187], v[216:219], v[0:3]
	v_mfma_f32_16x16x32_bf16 v[52:55], v[180:183], v[196:199], v[52:55]
	v_mfma_f32_16x16x32_bf16 v[48:51], v[188:191], v[196:199], v[48:51]
	v_mfma_f32_16x16x32_bf16 v[36:39], v[180:183], v[204:207], v[36:39]
	v_mfma_f32_16x16x32_bf16 v[32:35], v[188:191], v[204:207], v[32:35]
	v_mfma_f32_16x16x32_bf16 v[20:23], v[180:183], v[212:215], v[20:23]
	v_mfma_f32_16x16x32_bf16 v[16:19], v[188:191], v[212:215], v[16:19]
	s_setprio 2
	s_barrier
	v_mfma_f32_16x16x32_bf16 v[4:7], v[180:183], v[220:223], v[4:7]
	v_mfma_f32_16x16x32_bf16 v[0:3], v[188:191], v[220:223], v[0:3]
	s_setprio 0
	s_add_i32 s70, s70, 2
	s_add_u32 s42, s42, 0x100
	s_addc_u32 s43, s43, 0
	s_add_u32 s68, s68, 0x100
	s_addc_u32 s69, s69, 0
	s_cmp_gt_u32 s70, 13
	s_cbranch_scc0 .LBB0_1236
	v_readlane_b32 s80, v244, 16
	s_and_b64 vcc, exec, s[10:11]
	v_readlane_b32 s81, v244, 17
	s_cbranch_vccz .LBB0_1239
	s_barrier

; #define PG8_STAGE(bufoff, gbase, voff) do { _Pragma("unroll") for (int _i = 0; _i < 2; ++_i) \
;         __builtin_amdgcn_global_load_lds((const unsigned*)((const char*)(gbase) + (voff)[_i]), (LAS unsigned*)(lds + (bufoff) + ldsw + _i * 8192), 16, 0, 0); } while (0)
; #define PG8_LDA(dst, b, h) do { _Pragma("unroll") for (int m = 0; m < 4; ++m) _Pragma("unroll") for (int k = 0; k < 2; ++k) dst[m][k] = *(const LAS bf16x8*)(lds + PG8_SA(b, h) + aoff + m * 2048 + k * 1024); } while (0)
; #define PG8_LDB(dst, b, h) do { _Pragma("unroll") for (int n = 0; n < 2; ++n) _Pragma("unroll") for (int k = 0; k < 2; ++k) dst[n][k] = *(const LAS bf16x8*)(lds + PG8_SB(b, h) + boff + n * 2048 + k * 1024); } while (0)
; #define PG8_MMA(ai, bj, At, Bt) do { __builtin_amdgcn_s_setprio(1); _Pragma("unroll") for (int m = 0; m < 4; ++m) _Pragma("unroll") for (int n = 0; n < 2; ++n) _Pragma("unroll") for (int k = 0; k < 2; ++k) \
;         acc[ai][bj][m][n] = __builtin_amdgcn_mfma_f32_16x16x32_bf16(Bt[n][k], At[m][k], acc[ai][bj][m][n], 0, 0, 0); __builtin_amdgcn_s_setprio(0); } while (0)
; #define PG8_WAIT_V(n) asm volatile("s_waitcnt vmcnt(" #n ")" ::: "memory")
; #define PG8_WAIT_L(n) asm volatile("s_waitcnt lgkmcnt(" #n ")" ::: "memory")
; #define PG8_BAR __builtin_amdgcn_s_barrier()
; #define PG8_SCHED __builtin_amdgcn_sched_barrier(0)
; template <class Epi, class Sched, bool ALIGN_EPI = true, bool SP2 = true>
; __device__ __forceinline__ void gemm_phase(LAS unsigned char* lds, const bf16_t* Ag, const bf16_t* Btg, const int K, const int lda, const int ldb, const Sched& S, const Epi& E) {
;     ...
;             const char* a2 = last ? nA : cA + (size_t)(t + 2) * kstep; const char* b2 = last ? nB : cB + (size_t)(t + 2) * kstep;
;             const char* a3 = a2 + kstep; const char* b3 = b2 + kstep;
;             if constexpr (SP2) {
;             PG8_LDB(B0, 0, 0); PG8_LDB(B1, 0, 1); PG8_SCHED; PG8_LDA(At, 0, 0); PG8_STAGE(PG8_SA(1, 1), a1 + hstepA, voffA);
;             PG8_WAIT_V(8); PG8_WAIT_L(0); PG8_BAR; PG8_MMA(0, 0, At, B0); PG8_MMA(0, 1, At, B1); PG8_BAR; PG8_SCHED;
;             PG8_LDA(At, 0, 1); PG8_STAGE(PG8_SB(0, 0), b2, voffB); PG8_STAGE(PG8_SB(0, 1), b2 + hstepB, voffB); PG8_STAGE(PG8_SA(0, 0), a2, voffA);
.LBB0_1369:
	ds_read_b128 v[152:155], v149
	ds_read_b128 v[156:159], v149 offset:1024
	ds_read_b128 v[160:163], v149 offset:2048
	ds_read_b128 v[168:171], v149 offset:3072
	ds_read_b128 v[172:175], v150
	ds_read_b128 v[180:183], v150 offset:1024
	ds_read_b128 v[184:187], v150 offset:2048
	ds_read_b128 v[188:191], v150 offset:3072
	s_add_u32 s26, s24, 0xfff80080
	s_addc_u32 s27, s25, -1
	s_cmp_eq_u32 s58, 28
	s_cselect_b32 s29, s52, s27
	s_cselect_b32 s28, s53, s26
	s_cselect_b32 s27, s54, s57
	s_cselect_b32 s26, s55, s56
	v_lshl_add_u64 v[146:147], s[24:25], 0, v[138:139]
	s_add_i32 m0, s34, 0xc000
	ds_read_b128 v[192:195], v151
	ds_read_b128 v[196:199], v151 offset:1024
	ds_read_b128 v[200:203], v151 offset:2048
	ds_read_b128 v[204:207], v151 offset:3072
	ds_read_b128 v[208:211], v151 offset:4096
	ds_read_b128 v[212:215], v151 offset:5120
	ds_read_b128 v[216:219], v151 offset:6144
	ds_read_b128 v[220:223], v151 offset:7168
	global_load_lds_dwordx4 v[146:147], off
	v_lshl_add_u64 v[146:147], s[24:25], 0, v[140:141]
	s_add_i32 m0, s34, 0xe000
	s_nop 0
	global_load_lds_dwordx4 v[146:147], off
	s_waitcnt vmcnt(8)
	s_waitcnt lgkmcnt(0)
	s_barrier
	s_setprio 1
	s_waitcnt lgkmcnt(0)
	v_mfma_f32_16x16x32_bf16 v[124:127], v[152:155], v[192:195], v[124:127]
	v_mfma_f32_16x16x32_bf16 v[120:123], v[160:163], v[192:195], v[120:123]
	v_mfma_f32_16x16x32_bf16 v[108:111], v[152:155], v[200:203], v[108:111]
	v_mfma_f32_16x16x32_bf16 v[104:107], v[160:163], v[200:203], v[104:107]
	v_mfma_f32_16x16x32_bf16 v[92:95], v[152:155], v[208:211], v[92:95]
	v_mfma_f32_16x16x32_bf16 v[88:91], v[160:163], v[208:211], v[88:91]
	v_mfma_f32_16x16x32_bf16 v[76:79], v[152:155], v[216:219], v[76:79]
	v_mfma_f32_16x16x32_bf16 v[72:75], v[160:163], v[216:219], v[72:75]
	v_mfma_f32_16x16x32_bf16 v[124:127], v[156:159], v[196:199], v[124:127]
	v_mfma_f32_16x16x32_bf16 v[120:123], v[168:171], v[196:199], v[120:123]
	v_mfma_f32_16x16x32_bf16 v[108:111], v[156:159], v[204:207], v[108:111]
	v_mfma_f32_16x16x32_bf16 v[104:107], v[168:171], v[204:207], v[104:107]
	v_mfma_f32_16x16x32_bf16 v[92:95], v[156:159], v[212:215], v[92:95]
	v_mfma_f32_16x16x32_bf16 v[88:91], v[168:171], v[212:215], v[88:91]
	v_mfma_f32_16x16x32_bf16 v[76:79], v[156:159], v[220:223], v[76:79]
	v_mfma_f32_16x16x32_bf16 v[72:75], v[168:171], v[220:223], v[72:75]
	s_setprio 0
	s_setprio 1
	v_mfma_f32_16x16x32_bf16 v[116:119], v[172:175], v[192:195], v[116:119]
	v_mfma_f32_16x16x32_bf16 v[112:115], v[184:187], v[192:195], v[112:115]
	v_mfma_f32_16x16x32_bf16 v[100:103], v[172:175], v[200:203], v[100:103]
	v_mfma_f32_16x16x32_bf16 v[96:99], v[184:187], v[200:203], v[96:99]
	v_mfma_f32_16x16x32_bf16 v[84:87], v[172:175], v[208:211], v[84:87]
	v_mfma_f32_16x16x32_bf16 v[80:83], v[184:187], v[208:211], v[80:83]
	v_mfma_f32_16x16x32_bf16 v[68:71], v[172:175], v[216:219], v[68:71]
	v_mfma_f32_16x16x32_bf16 v[64:67], v[184:187], v[216:219], v[64:67]
	v_mfma_f32_16x16x32_bf16 v[116:119], v[180:183], v[196:199], v[116:119]
	v_mfma_f32_16x16x32_bf16 v[112:115], v[188:191], v[196:199], v[112:115]
	v_mfma_f32_16x16x32_bf16 v[100:103], v[180:183], v[204:207], v[100:103]
	v_mfma_f32_16x16x32_bf16 v[96:99], v[188:191], v[204:207], v[96:99]
	v_mfma_f32_16x16x32_bf16 v[84:87], v[180:183], v[212:215], v[84:87]
	v_mfma_f32_16x16x32_bf16 v[80:83], v[188:191], v[212:215], v[80:83]
	s_setprio 2
	s_barrier
	v_mfma_f32_16x16x32_bf16 v[68:71], v[180:183], v[220:223], v[68:71]
	v_mfma_f32_16x16x32_bf16 v[64:67], v[188:191], v[220:223], v[64:67]
	s_setprio 0
	s_add_i32 s59, s43, s30
	v_lshl_add_u64 v[146:147], s[26:27], 0, v[132:133]
	s_mov_b32 m0, s59
	ds_read_b128 v[192:195], v151 offset:16384
	ds_read_b128 v[196:199], v151 offset:17408
	ds_read_b128 v[200:203], v151 offset:18432
	ds_read_b128 v[204:207], v151 offset:19456
	ds_read_b128 v[208:211], v151 offset:20480
	ds_read_b128 v[212:215], v151 offset:21504
	ds_read_b128 v[216:219], v151 offset:22528
	ds_read_b128 v[220:223], v151 offset:23552
	global_load_lds_dwordx4 v[146:147], off
	s_add_i32 m0, s59, 0x2000
	s_add_u32 s60, s26, 0x80000
	v_lshl_add_u64 v[164:165], s[26:27], 0, v[128:129]
	s_addc_u32 s61, s27, 0
	s_add_i32 s59, s44, s30
	global_load_lds_dwordx4 v[164:165], off
	v_lshl_add_u64 v[224:225], s[60:61], 0, v[132:133]
	s_mov_b32 m0, s59
	v_lshl_add_u64 v[226:227], s[28:29], 0, v[130:131]
	global_load_lds_dwordx4 v[224:225], off
	v_lshl_add_u64 v[224:225], s[60:61], 0, v[128:129]
	s_add_i32 m0, s59, 0x2000
	s_nop 0
	global_load_lds_dwordx4 v[224:225], off
	v_lshl_add_u64 v[224:225], s[28:29], 0, v[134:135]
	s_mov_b32 m0, s34
	s_nop 0
	global_load_lds_dwordx4 v[224:225], off
	s_mov_b32 m0, s35
	s_nop 0
	global_load_lds_dwordx4 v[226:227], off
	s_waitcnt vmcnt(8)
	s_waitcnt lgkmcnt(0)
	s_barrier
; #define PG8_STAGE(bufoff, gbase, voff) do { _Pragma("unroll") for (int _i = 0; _i < 2; ++_i) \
;         __builtin_amdgcn_global_load_lds((const unsigned*)((const char*)(gbase) + (voff)[_i]), (LAS unsigned*)(lds + (bufoff) + ldsw + _i * 8192), 16, 0, 0); } while (0)
; #define PG8_LDA(dst, b, h) do { _Pragma("unroll") for (int m = 0; m < 4; ++m) _Pragma("unroll") for (int k = 0; k < 2; ++k) dst[m][k] = *(const LAS bf16x8*)(lds + PG8_SA(b, h) + aoff + m * 2048 + k * 1024); } while (0)
; #define PG8_LDB(dst, b, h) do { _Pragma("unroll") for (int n = 0; n < 2; ++n) _Pragma("unroll") for (int k = 0; k < 2; ++k) dst[n][k] = *(const LAS bf16x8*)(lds + PG8_SB(b, h) + boff + n * 2048 + k * 1024); } while (0)
; #define PG8_MMA(ai, bj, At, Bt) do { __builtin_amdgcn_s_setprio(1); _Pragma("unroll") for (int m = 0; m < 4; ++m) _Pragma("unroll") for (int n = 0; n < 2; ++n) _Pragma("unroll") for (int k = 0; k < 2; ++k) \
;         acc[ai][bj][m][n] = __builtin_amdgcn_mfma_f32_16x16x32_bf16(Bt[n][k], At[m][k], acc[ai][bj][m][n], 0, 0, 0); __builtin_amdgcn_s_setprio(0); } while (0)
; #define PG8_WAIT_V(n) asm volatile("s_waitcnt vmcnt(" #n ")" ::: "memory")
; #define PG8_WAIT_L(n) asm volatile("s_waitcnt lgkmcnt(" #n ")" ::: "memory")
; #define PG8_BAR __builtin_amdgcn_s_barrier()
; #define PG8_SCHED __builtin_amdgcn_sched_barrier(0)
; template <class Epi, class Sched, bool ALIGN_EPI = true, bool SP2 = true>
; __device__ __forceinline__ void gemm_phase(LAS unsigned char* lds, const bf16_t* Ag, const bf16_t* Btg, const int K, const int lda, const int ldb, const Sched& S, const Epi& E) {
;     ...
;             PG8_WAIT_V(8); PG8_WAIT_L(0); PG8_BAR; PG8_MMA(1, 0, At, B0); PG8_MMA(1, 1, At, B1); PG8_BAR; PG8_SCHED;
;             PG8_LDB(B0, 1, 0); PG8_LDB(B1, 1, 1); PG8_SCHED; PG8_LDA(At, 1, 0); PG8_STAGE(PG8_SA(0, 1), a2 + hstepA, voffA);
;             PG8_WAIT_V(8); PG8_WAIT_L(0); PG8_BAR; PG8_MMA(0, 0, At, B0); PG8_MMA(0, 1, At, B1); PG8_BAR; PG8_SCHED;
	s_setprio 1
	s_waitcnt lgkmcnt(0)
	v_mfma_f32_16x16x32_bf16 v[60:63], v[152:155], v[192:195], v[60:63]
	v_mfma_f32_16x16x32_bf16 v[56:59], v[160:163], v[192:195], v[56:59]
	v_mfma_f32_16x16x32_bf16 v[44:47], v[152:155], v[200:203], v[44:47]
	v_mfma_f32_16x16x32_bf16 v[40:43], v[160:163], v[200:203], v[40:43]
	v_mfma_f32_16x16x32_bf16 v[28:31], v[152:155], v[208:211], v[28:31]
	v_mfma_f32_16x16x32_bf16 v[24:27], v[160:163], v[208:211], v[24:27]
	v_mfma_f32_16x16x32_bf16 v[12:15], v[152:155], v[216:219], v[12:15]
	v_mfma_f32_16x16x32_bf16 v[8:11], v[160:163], v[216:219], v[8:11]
	v_mfma_f32_16x16x32_bf16 v[60:63], v[156:159], v[196:199], v[60:63]
	v_mfma_f32_16x16x32_bf16 v[56:59], v[168:171], v[196:199], v[56:59]
	v_mfma_f32_16x16x32_bf16 v[44:47], v[156:159], v[204:207], v[44:47]
	v_mfma_f32_16x16x32_bf16 v[40:43], v[168:171], v[204:207], v[40:43]
	v_mfma_f32_16x16x32_bf16 v[28:31], v[156:159], v[212:215], v[28:31]
	v_mfma_f32_16x16x32_bf16 v[24:27], v[168:171], v[212:215], v[24:27]
	v_mfma_f32_16x16x32_bf16 v[12:15], v[156:159], v[220:223], v[12:15]
	v_mfma_f32_16x16x32_bf16 v[8:11], v[168:171], v[220:223], v[8:11]
	s_setprio 0
	s_setprio 1
	v_mfma_f32_16x16x32_bf16 v[52:55], v[172:175], v[192:195], v[52:55]
	v_mfma_f32_16x16x32_bf16 v[48:51], v[184:187], v[192:195], v[48:51]
	v_mfma_f32_16x16x32_bf16 v[36:39], v[172:175], v[200:203], v[36:39]
	v_mfma_f32_16x16x32_bf16 v[32:35], v[184:187], v[200:203], v[32:35]
	v_mfma_f32_16x16x32_bf16 v[20:23], v[172:175], v[208:211], v[20:23]
	v_mfma_f32_16x16x32_bf16 v[16:19], v[184:187], v[208:211], v[16:19]
	v_mfma_f32_16x16x32_bf16 v[4:7], v[172:175], v[216:219], v[4:7]
	v_mfma_f32_16x16x32_bf16 v[0:3], v[184:187], v[216:219], v[0:3]
	v_mfma_f32_16x16x32_bf16 v[52:55], v[180:183], v[196:199], v[52:55]
	v_mfma_f32_16x16x32_bf16 v[48:51], v[188:191], v[196:199], v[48:51]
	v_mfma_f32_16x16x32_bf16 v[36:39], v[180:183], v[204:207], v[36:39]
	v_mfma_f32_16x16x32_bf16 v[32:35], v[188:191], v[204:207], v[32:35]
	v_mfma_f32_16x16x32_bf16 v[20:23], v[180:183], v[212:215], v[20:23]
	v_mfma_f32_16x16x32_bf16 v[16:19], v[188:191], v[212:215], v[16:19]
	s_setprio 2
	s_barrier
	v_mfma_f32_16x16x32_bf16 v[4:7], v[180:183], v[220:223], v[4:7]
	v_mfma_f32_16x16x32_bf16 v[0:3], v[188:191], v[220:223], v[0:3]
	s_setprio 0
	s_add_i32 s59, 0, 0x18000
	v_add_u32_e32 v167, s59, v148
	s_add_i32 s60, 0, 0x1c000
	ds_read_b128 v[152:155], v167
	ds_read_b128 v[156:159], v167 offset:1024
	ds_read_b128 v[160:163], v167 offset:2048
	ds_read_b128 v[168:171], v167 offset:3072
	v_add_u32_e32 v167, s60, v148
	ds_read_b128 v[172:175], v167
	ds_read_b128 v[180:183], v167 offset:1024
	ds_read_b128 v[184:187], v167 offset:2048
	ds_read_b128 v[188:191], v167 offset:3072
	s_add_u32 s28, s28, 0x80000
	s_addc_u32 s29, s29, 0
	s_mov_b32 m0, s37
	v_lshl_add_u64 v[228:229], s[28:29], 0, v[134:135]
	ds_read_b128 v[192:195], v151 offset:32768
	ds_read_b128 v[196:199], v151 offset:33792
	ds_read_b128 v[200:203], v151 offset:34816
	ds_read_b128 v[204:207], v151 offset:35840
	ds_read_b128 v[208:211], v151 offset:36864
	ds_read_b128 v[212:215], v151 offset:37888
	ds_read_b128 v[216:219], v151 offset:38912
	ds_read_b128 v[220:223], v151 offset:39936
	global_load_lds_dwordx4 v[228:229], off
	v_lshl_add_u64 v[228:229], s[28:29], 0, v[130:131]
	s_mov_b32 m0, s38
	s_nop 0
	global_load_lds_dwordx4 v[228:229], off
	s_waitcnt vmcnt(8)
	s_waitcnt lgkmcnt(0)
	s_barrier
	s_setprio 1
	s_waitcnt lgkmcnt(0)
	v_mfma_f32_16x16x32_bf16 v[124:127], v[152:155], v[192:195], v[124:127]
	v_mfma_f32_16x16x32_bf16 v[120:123], v[160:163], v[192:195], v[120:123]
	v_mfma_f32_16x16x32_bf16 v[108:111], v[152:155], v[200:203], v[108:111]
	v_mfma_f32_16x16x32_bf16 v[104:107], v[160:163], v[200:203], v[104:107]
	v_mfma_f32_16x16x32_bf16 v[92:95], v[152:155], v[208:211], v[92:95]
	v_mfma_f32_16x16x32_bf16 v[88:91], v[160:163], v[208:211], v[88:91]
	v_mfma_f32_16x16x32_bf16 v[76:79], v[152:155], v[216:219], v[76:79]
	v_mfma_f32_16x16x32_bf16 v[72:75], v[160:163], v[216:219], v[72:75]
	v_mfma_f32_16x16x32_bf16 v[124:127], v[156:159], v[196:199], v[124:127]
	v_mfma_f32_16x16x32_bf16 v[120:123], v[168:171], v[196:199], v[120:123]
	v_mfma_f32_16x16x32_bf16 v[108:111], v[156:159], v[204:207], v[108:111]
	v_mfma_f32_16x16x32_bf16 v[104:107], v[168:171], v[204:207], v[104:107]
	v_mfma_f32_16x16x32_bf16 v[92:95], v[156:159], v[212:215], v[92:95]
	v_mfma_f32_16x16x32_bf16 v[88:91], v[168:171], v[212:215], v[88:91]
	v_mfma_f32_16x16x32_bf16 v[76:79], v[156:159], v[220:223], v[76:79]
	v_mfma_f32_16x16x32_bf16 v[72:75], v[168:171], v[220:223], v[72:75]
	s_setprio 0
	s_setprio 1
	v_mfma_f32_16x16x32_bf16 v[116:119], v[172:175], v[192:195], v[116:119]
	v_mfma_f32_16x16x32_bf16 v[112:115], v[184:187], v[192:195], v[112:115]
	v_mfma_f32_16x16x32_bf16 v[100:103], v[172:175], v[200:203], v[100:103]
	v_mfma_f32_16x16x32_bf16 v[96:99], v[184:187], v[200:203], v[96:99]
	v_mfma_f32_16x16x32_bf16 v[84:87], v[172:175], v[208:211], v[84:87]
	v_mfma_f32_16x16x32_bf16 v[80:83], v[184:187], v[208:211], v[80:83]
	v_mfma_f32_16x16x32_bf16 v[68:71], v[172:175], v[216:219], v[68:71]
	v_mfma_f32_16x16x32_bf16 v[64:67], v[184:187], v[216:219], v[64:67]
	v_mfma_f32_16x16x32_bf16 v[116:119], v[180:183], v[196:199], v[116:119]
	v_mfma_f32_16x16x32_bf16 v[112:115], v[188:191], v[196:199], v[112:115]
	v_mfma_f32_16x16x32_bf16 v[100:103], v[180:183], v[204:207], v[100:103]
	v_mfma_f32_16x16x32_bf16 v[96:99], v[188:191], v[204:207], v[96:99]
	v_mfma_f32_16x16x32_bf16 v[84:87], v[180:183], v[212:215], v[84:87]
	v_mfma_f32_16x16x32_bf16 v[80:83], v[188:191], v[212:215], v[80:83]
	s_setprio 2
	s_barrier
; #define PG8_STAGE(bufoff, gbase, voff) do { _Pragma("unroll") for (int _i = 0; _i < 2; ++_i) \
;         __builtin_amdgcn_global_load_lds((const unsigned*)((const char*)(gbase) + (voff)[_i]), (LAS unsigned*)(lds + (bufoff) + ldsw + _i * 8192), 16, 0, 0); } while (0)
; #define PG8_LDA(dst, b, h) do { _Pragma("unroll") for (int m = 0; m < 4; ++m) _Pragma("unroll") for (int k = 0; k < 2; ++k) dst[m][k] = *(const LAS bf16x8*)(lds + PG8_SA(b, h) + aoff + m * 2048 + k * 1024); } while (0)
; #define PG8_MMA(ai, bj, At, Bt) do { __builtin_amdgcn_s_setprio(1); _Pragma("unroll") for (int m = 0; m < 4; ++m) _Pragma("unroll") for (int n = 0; n < 2; ++n) _Pragma("unroll") for (int k = 0; k < 2; ++k) \
;         acc[ai][bj][m][n] = __builtin_amdgcn_mfma_f32_16x16x32_bf16(Bt[n][k], At[m][k], acc[ai][bj][m][n], 0, 0, 0); __builtin_amdgcn_s_setprio(0); } while (0)
; #define PG8_WAIT_V(n) asm volatile("s_waitcnt vmcnt(" #n ")" ::: "memory")
; #define PG8_WAIT_L(n) asm volatile("s_waitcnt lgkmcnt(" #n ")" ::: "memory")
; #define PG8_BAR __builtin_amdgcn_s_barrier()
; #define PG8_SCHED __builtin_amdgcn_sched_barrier(0)
; template <class Epi, class Sched, bool ALIGN_EPI = true, bool SP2 = true>
; __device__ __forceinline__ void gemm_phase(LAS unsigned char* lds, const bf16_t* Ag, const bf16_t* Btg, const int K, const int lda, const int ldb, const Sched& S, const Epi& E) {
;     ...
;             PG8_WAIT_V(8); PG8_WAIT_L(0); PG8_BAR; PG8_MMA(0, 0, At, B0); PG8_MMA(0, 1, At, B1); PG8_BAR; PG8_SCHED;
;             PG8_LDA(At, 1, 1); PG8_STAGE(PG8_SB(1, 0), b3, voffB); PG8_STAGE(PG8_SB(1, 1), b3 + hstepB, voffB); PG8_STAGE(PG8_SA(1, 0), a3, voffA);
;             PG8_WAIT_V(8); PG8_WAIT_L(0); PG8_BAR; PG8_MMA(1, 0, At, B0); PG8_MMA(1, 1, At, B1); PG8_BAR; PG8_SCHED;
	v_mfma_f32_16x16x32_bf16 v[68:71], v[180:183], v[220:223], v[68:71]
	v_mfma_f32_16x16x32_bf16 v[64:67], v[188:191], v[220:223], v[64:67]
	s_setprio 0
	s_add_i32 s28, s59, s30
	v_lshl_add_u64 v[146:147], v[146:147], 0, s[8:9]
	s_mov_b32 m0, s28
	ds_read_b128 v[192:195], v151 offset:49152
	ds_read_b128 v[196:199], v151 offset:50176
	ds_read_b128 v[200:203], v151 offset:51200
	ds_read_b128 v[204:207], v151 offset:52224
	ds_read_b128 v[208:211], v151 offset:53248
	ds_read_b128 v[212:215], v151 offset:54272
	ds_read_b128 v[216:219], v151 offset:55296
	ds_read_b128 v[220:223], v151 offset:56320
	global_load_lds_dwordx4 v[146:147], off
	s_add_i32 m0, s28, 0x2000
	s_add_u32 s26, s26, 0x80080
	v_lshl_add_u64 v[146:147], v[164:165], 0, s[8:9]
	s_addc_u32 s27, s27, 0
	s_add_i32 s28, s60, s30
	global_load_lds_dwordx4 v[146:147], off
	v_lshl_add_u64 v[146:147], s[26:27], 0, v[132:133]
	s_mov_b32 m0, s28
	s_nop 0
	global_load_lds_dwordx4 v[146:147], off
	v_lshl_add_u64 v[146:147], s[26:27], 0, v[128:129]
	s_add_i32 m0, s28, 0x2000
	s_nop 0
	global_load_lds_dwordx4 v[146:147], off
	v_lshl_add_u64 v[146:147], v[224:225], 0, s[8:9]
	s_mov_b32 m0, s39
	s_nop 0
	global_load_lds_dwordx4 v[146:147], off
	v_lshl_add_u64 v[146:147], v[226:227], 0, s[8:9]
	s_mov_b32 m0, s40
	s_nop 0
	global_load_lds_dwordx4 v[146:147], off
	s_waitcnt vmcnt(8)
	s_waitcnt lgkmcnt(0)
	s_barrier
	s_setprio 1
	s_waitcnt lgkmcnt(0)
	v_mfma_f32_16x16x32_bf16 v[60:63], v[152:155], v[192:195], v[60:63]
	v_mfma_f32_16x16x32_bf16 v[56:59], v[160:163], v[192:195], v[56:59]
	v_mfma_f32_16x16x32_bf16 v[44:47], v[152:155], v[200:203], v[44:47]
	v_mfma_f32_16x16x32_bf16 v[40:43], v[160:163], v[200:203], v[40:43]
	v_mfma_f32_16x16x32_bf16 v[28:31], v[152:155], v[208:211], v[28:31]
	v_mfma_f32_16x16x32_bf16 v[24:27], v[160:163], v[208:211], v[24:27]
	v_mfma_f32_16x16x32_bf16 v[12:15], v[152:155], v[216:219], v[12:15]
	v_mfma_f32_16x16x32_bf16 v[8:11], v[160:163], v[216:219], v[8:11]
	v_mfma_f32_16x16x32_bf16 v[60:63], v[156:159], v[196:199], v[60:63]
	v_mfma_f32_16x16x32_bf16 v[56:59], v[168:171], v[196:199], v[56:59]
	v_mfma_f32_16x16x32_bf16 v[44:47], v[156:159], v[204:207], v[44:47]
	v_mfma_f32_16x16x32_bf16 v[40:43], v[168:171], v[204:207], v[40:43]
	v_mfma_f32_16x16x32_bf16 v[28:31], v[156:159], v[212:215], v[28:31]
	v_mfma_f32_16x16x32_bf16 v[24:27], v[168:171], v[212:215], v[24:27]
	v_mfma_f32_16x16x32_bf16 v[12:15], v[156:159], v[220:223], v[12:15]
	v_mfma_f32_16x16x32_bf16 v[8:11], v[168:171], v[220:223], v[8:11]
	s_setprio 0
	s_setprio 1
	v_mfma_f32_16x16x32_bf16 v[52:55], v[172:175], v[192:195], v[52:55]
	v_mfma_f32_16x16x32_bf16 v[48:51], v[184:187], v[192:195], v[48:51]
	v_mfma_f32_16x16x32_bf16 v[36:39], v[172:175], v[200:203], v[36:39]
	v_mfma_f32_16x16x32_bf16 v[32:35], v[184:187], v[200:203], v[32:35]
	v_mfma_f32_16x16x32_bf16 v[20:23], v[172:175], v[208:211], v[20:23]
	v_mfma_f32_16x16x32_bf16 v[16:19], v[184:187], v[208:211], v[16:19]
	v_mfma_f32_16x16x32_bf16 v[4:7], v[172:175], v[216:219], v[4:7]
	v_mfma_f32_16x16x32_bf16 v[0:3], v[184:187], v[216:219], v[0:3]
	v_mfma_f32_16x16x32_bf16 v[52:55], v[180:183], v[196:199], v[52:55]
	v_mfma_f32_16x16x32_bf16 v[48:51], v[188:191], v[196:199], v[48:51]
	v_mfma_f32_16x16x32_bf16 v[36:39], v[180:183], v[204:207], v[36:39]
	v_mfma_f32_16x16x32_bf16 v[32:35], v[188:191], v[204:207], v[32:35]
	v_mfma_f32_16x16x32_bf16 v[20:23], v[180:183], v[212:215], v[20:23]
	v_mfma_f32_16x16x32_bf16 v[16:19], v[188:191], v[212:215], v[16:19]
	s_setprio 2
	s_barrier
	v_mfma_f32_16x16x32_bf16 v[4:7], v[180:183], v[220:223], v[4:7]
	v_mfma_f32_16x16x32_bf16 v[0:3], v[188:191], v[220:223], v[0:3]
	s_setprio 0
	s_add_i32 s58, s58, 2
	s_add_u32 s24, s24, 0x100
	s_addc_u32 s25, s25, 0
	s_add_u32 s56, s56, 0x100
	s_addc_u32 s57, s57, 0
	s_cmp_gt_u32 s58, 29
	s_cbranch_scc0 .LBB0_1369
	s_and_b64 vcc, exec, s[10:11]
	s_cbranch_vccz .LBB0_1372
	s_barrier

; #define PG8_STAGE(bufoff, gbase, voff) do { _Pragma("unroll") for (int _i = 0; _i < 2; ++_i) \
;         __builtin_amdgcn_global_load_lds((const unsigned*)((const char*)(gbase) + (voff)[_i]), (LAS unsigned*)(lds + (bufoff) + ldsw + _i * 8192), 16, 0, 0); } while (0)
; #define PG8_LDA(dst, b, h) do { _Pragma("unroll") for (int m = 0; m < 4; ++m) _Pragma("unroll") for (int k = 0; k < 2; ++k) dst[m][k] = *(const LAS bf16x8*)(lds + PG8_SA(b, h) + aoff + m * 2048 + k * 1024); } while (0)
; #define PG8_LDB(dst, b, h) do { _Pragma("unroll") for (int n = 0; n < 2; ++n) _Pragma("unroll") for (int k = 0; k < 2; ++k) dst[n][k] = *(const LAS bf16x8*)(lds + PG8_SB(b, h) + boff + n * 2048 + k * 1024); } while (0)
; #define PG8_MMA(ai, bj, At, Bt) do { __builtin_amdgcn_s_setprio(1); _Pragma("unroll") for (int m = 0; m < 4; ++m) _Pragma("unroll") for (int n = 0; n < 2; ++n) _Pragma("unroll") for (int k = 0; k < 2; ++k) \
;         acc[ai][bj][m][n] = __builtin_amdgcn_mfma_f32_16x16x32_bf16(Bt[n][k], At[m][k], acc[ai][bj][m][n], 0, 0, 0); __builtin_amdgcn_s_setprio(0); } while (0)
; #define PG8_WAIT_V(n) asm volatile("s_waitcnt vmcnt(" #n ")" ::: "memory")
; #define PG8_WAIT_L(n) asm volatile("s_waitcnt lgkmcnt(" #n ")" ::: "memory")
; #define PG8_BAR __builtin_amdgcn_s_barrier()
; #define PG8_SCHED __builtin_amdgcn_sched_barrier(0)
; template <class Epi, class Sched, bool ALIGN_EPI = true, bool SP2 = true>
; __device__ __forceinline__ void gemm_phase(LAS unsigned char* lds, const bf16_t* Ag, const bf16_t* Btg, const int K, const int lda, const int ldb, const Sched& S, const Epi& E) {
;     ...
;             const char* a2 = last ? nA : cA + (size_t)(t + 2) * kstep; const char* b2 = last ? nB : cB + (size_t)(t + 2) * kstep;
;             const char* a3 = a2 + kstep; const char* b3 = b2 + kstep;
;             if constexpr (SP2) {
;             PG8_LDB(B0, 0, 0); PG8_LDB(B1, 0, 1); PG8_SCHED; PG8_LDA(At, 0, 0); PG8_STAGE(PG8_SA(1, 1), a1 + hstepA, voffA);
;             PG8_WAIT_V(8); PG8_WAIT_L(0); PG8_BAR; PG8_MMA(0, 0, At, B0); PG8_MMA(0, 1, At, B1); PG8_BAR; PG8_SCHED;
;             PG8_LDA(At, 0, 1); PG8_STAGE(PG8_SB(0, 0), b2, voffB); PG8_STAGE(PG8_SB(0, 1), b2 + hstepB, voffB); PG8_STAGE(PG8_SA(0, 0), a2, voffA);
.LBB0_1448:
	ds_read_b128 v[152:155], v149
	ds_read_b128 v[156:159], v149 offset:1024
	ds_read_b128 v[160:163], v149 offset:2048
	ds_read_b128 v[164:167], v149 offset:3072
	ds_read_b128 v[168:171], v150
	ds_read_b128 v[172:175], v150 offset:1024
	ds_read_b128 v[178:181], v150 offset:2048
	ds_read_b128 v[182:185], v150 offset:3072
	s_add_u32 s54, s52, 0xffea0080
	s_addc_u32 s55, s53, -1
	s_cmpk_eq_i32 s79, 0x54
	s_cselect_b32 s57, s33, s55
	s_cselect_b32 s56, s74, s54
	s_cselect_b32 s55, s75, s78
	s_cselect_b32 s54, s76, s77
	v_lshl_add_u64 v[146:147], s[52:53], 0, v[138:139]
	s_add_i32 m0, s41, 0xc000
	ds_read_b128 v[186:189], v151
	ds_read_b128 v[190:193], v151 offset:1024
	ds_read_b128 v[194:197], v151 offset:2048
	ds_read_b128 v[198:201], v151 offset:3072
	ds_read_b128 v[202:205], v151 offset:4096
	ds_read_b128 v[206:209], v151 offset:5120
	ds_read_b128 v[210:213], v151 offset:6144
	ds_read_b128 v[214:217], v151 offset:7168
	global_load_lds_dwordx4 v[146:147], off
	v_lshl_add_u64 v[146:147], s[52:53], 0, v[140:141]
	s_add_i32 m0, s41, 0xe000
	s_nop 0
	global_load_lds_dwordx4 v[146:147], off
	s_waitcnt vmcnt(8)
	s_waitcnt lgkmcnt(0)
	s_barrier
	s_setprio 1
	s_waitcnt lgkmcnt(0)
	v_mfma_f32_16x16x32_bf16 v[124:127], v[152:155], v[186:189], v[124:127]
	v_mfma_f32_16x16x32_bf16 v[120:123], v[160:163], v[186:189], v[120:123]
	v_mfma_f32_16x16x32_bf16 v[108:111], v[152:155], v[194:197], v[108:111]
	v_mfma_f32_16x16x32_bf16 v[104:107], v[160:163], v[194:197], v[104:107]
	v_mfma_f32_16x16x32_bf16 v[92:95], v[152:155], v[202:205], v[92:95]
	v_mfma_f32_16x16x32_bf16 v[88:91], v[160:163], v[202:205], v[88:91]
	v_mfma_f32_16x16x32_bf16 v[76:79], v[152:155], v[210:213], v[76:79]
	v_mfma_f32_16x16x32_bf16 v[72:75], v[160:163], v[210:213], v[72:75]
	v_mfma_f32_16x16x32_bf16 v[124:127], v[156:159], v[190:193], v[124:127]
	v_mfma_f32_16x16x32_bf16 v[120:123], v[164:167], v[190:193], v[120:123]
	v_mfma_f32_16x16x32_bf16 v[108:111], v[156:159], v[198:201], v[108:111]
	v_mfma_f32_16x16x32_bf16 v[104:107], v[164:167], v[198:201], v[104:107]
	v_mfma_f32_16x16x32_bf16 v[92:95], v[156:159], v[206:209], v[92:95]
	v_mfma_f32_16x16x32_bf16 v[88:91], v[164:167], v[206:209], v[88:91]
	v_mfma_f32_16x16x32_bf16 v[76:79], v[156:159], v[214:217], v[76:79]
	v_mfma_f32_16x16x32_bf16 v[72:75], v[164:167], v[214:217], v[72:75]
	s_setprio 0
	s_setprio 1
	v_mfma_f32_16x16x32_bf16 v[116:119], v[168:171], v[186:189], v[116:119]
	v_mfma_f32_16x16x32_bf16 v[112:115], v[178:181], v[186:189], v[112:115]
	v_mfma_f32_16x16x32_bf16 v[100:103], v[168:171], v[194:197], v[100:103]
	v_mfma_f32_16x16x32_bf16 v[96:99], v[178:181], v[194:197], v[96:99]
	v_mfma_f32_16x16x32_bf16 v[84:87], v[168:171], v[202:205], v[84:87]
	v_mfma_f32_16x16x32_bf16 v[80:83], v[178:181], v[202:205], v[80:83]
	v_mfma_f32_16x16x32_bf16 v[68:71], v[168:171], v[210:213], v[68:71]
	v_mfma_f32_16x16x32_bf16 v[64:67], v[178:181], v[210:213], v[64:67]
	v_mfma_f32_16x16x32_bf16 v[116:119], v[172:175], v[190:193], v[116:119]
	v_mfma_f32_16x16x32_bf16 v[112:115], v[182:185], v[190:193], v[112:115]
	v_mfma_f32_16x16x32_bf16 v[100:103], v[172:175], v[198:201], v[100:103]
	v_mfma_f32_16x16x32_bf16 v[96:99], v[182:185], v[198:201], v[96:99]
	v_mfma_f32_16x16x32_bf16 v[84:87], v[172:175], v[206:209], v[84:87]
	v_mfma_f32_16x16x32_bf16 v[80:83], v[182:185], v[206:209], v[80:83]
	s_setprio 2
	s_barrier
	v_mfma_f32_16x16x32_bf16 v[68:71], v[172:175], v[214:217], v[68:71]
	v_mfma_f32_16x16x32_bf16 v[64:67], v[182:185], v[214:217], v[64:67]
	s_setprio 0
	s_add_i32 s80, s66, s40
	v_lshl_add_u64 v[146:147], s[54:55], 0, v[130:131]
	s_mov_b32 m0, s80
	ds_read_b128 v[186:189], v151 offset:16384
	ds_read_b128 v[190:193], v151 offset:17408
	ds_read_b128 v[194:197], v151 offset:18432
	ds_read_b128 v[198:201], v151 offset:19456
	ds_read_b128 v[202:205], v151 offset:20480
	ds_read_b128 v[206:209], v151 offset:21504
	ds_read_b128 v[210:213], v151 offset:22528
	ds_read_b128 v[214:217], v151 offset:23552
	global_load_lds_dwordx4 v[146:147], off
	s_add_i32 m0, s80, 0x2000
	s_add_u32 s80, s54, 0x160000
	v_lshl_add_u64 v[218:219], s[54:55], 0, v[134:135]
	s_addc_u32 s81, s55, 0
	s_add_i32 s82, s67, s40
	global_load_lds_dwordx4 v[218:219], off
	v_lshl_add_u64 v[220:221], s[80:81], 0, v[130:131]
	s_mov_b32 m0, s82
	v_lshl_add_u64 v[222:223], s[56:57], 0, v[132:133]
	global_load_lds_dwordx4 v[220:221], off
	v_lshl_add_u64 v[220:221], s[80:81], 0, v[134:135]
	s_add_i32 m0, s82, 0x2000
	s_nop 0
	global_load_lds_dwordx4 v[220:221], off
	v_lshl_add_u64 v[220:221], s[56:57], 0, v[128:129]
	s_mov_b32 m0, s41
	s_nop 0
	global_load_lds_dwordx4 v[220:221], off
	s_mov_b32 m0, s58
	s_nop 0
	global_load_lds_dwordx4 v[222:223], off
	s_waitcnt vmcnt(8)
	s_waitcnt lgkmcnt(0)
	s_barrier
; #define PG8_STAGE(bufoff, gbase, voff) do { _Pragma("unroll") for (int _i = 0; _i < 2; ++_i) \
;         __builtin_amdgcn_global_load_lds((const unsigned*)((const char*)(gbase) + (voff)[_i]), (LAS unsigned*)(lds + (bufoff) + ldsw + _i * 8192), 16, 0, 0); } while (0)
; #define PG8_LDA(dst, b, h) do { _Pragma("unroll") for (int m = 0; m < 4; ++m) _Pragma("unroll") for (int k = 0; k < 2; ++k) dst[m][k] = *(const LAS bf16x8*)(lds + PG8_SA(b, h) + aoff + m * 2048 + k * 1024); } while (0)
; #define PG8_LDB(dst, b, h) do { _Pragma("unroll") for (int n = 0; n < 2; ++n) _Pragma("unroll") for (int k = 0; k < 2; ++k) dst[n][k] = *(const LAS bf16x8*)(lds + PG8_SB(b, h) + boff + n * 2048 + k * 1024); } while (0)
; #define PG8_MMA(ai, bj, At, Bt) do { __builtin_amdgcn_s_setprio(1); _Pragma("unroll") for (int m = 0; m < 4; ++m) _Pragma("unroll") for (int n = 0; n < 2; ++n) _Pragma("unroll") for (int k = 0; k < 2; ++k) \
;         acc[ai][bj][m][n] = __builtin_amdgcn_mfma_f32_16x16x32_bf16(Bt[n][k], At[m][k], acc[ai][bj][m][n], 0, 0, 0); __builtin_amdgcn_s_setprio(0); } while (0)
; #define PG8_WAIT_V(n) asm volatile("s_waitcnt vmcnt(" #n ")" ::: "memory")
; #define PG8_WAIT_L(n) asm volatile("s_waitcnt lgkmcnt(" #n ")" ::: "memory")
; #define PG8_BAR __builtin_amdgcn_s_barrier()
; #define PG8_SCHED __builtin_amdgcn_sched_barrier(0)
; template <class Epi, class Sched, bool ALIGN_EPI = true, bool SP2 = true>
; __device__ __forceinline__ void gemm_phase(LAS unsigned char* lds, const bf16_t* Ag, const bf16_t* Btg, const int K, const int lda, const int ldb, const Sched& S, const Epi& E) {
;     ...
;             PG8_WAIT_V(8); PG8_WAIT_L(0); PG8_BAR; PG8_MMA(1, 0, At, B0); PG8_MMA(1, 1, At, B1); PG8_BAR; PG8_SCHED;
;             PG8_LDB(B0, 1, 0); PG8_LDB(B1, 1, 1); PG8_SCHED; PG8_LDA(At, 1, 0); PG8_STAGE(PG8_SA(0, 1), a2 + hstepA, voffA);
;             PG8_WAIT_V(8); PG8_WAIT_L(0); PG8_BAR; PG8_MMA(0, 0, At, B0); PG8_MMA(0, 1, At, B1); PG8_BAR; PG8_SCHED;
	s_setprio 1
	s_waitcnt lgkmcnt(0)
	v_mfma_f32_16x16x32_bf16 v[60:63], v[152:155], v[186:189], v[60:63]
	v_mfma_f32_16x16x32_bf16 v[56:59], v[160:163], v[186:189], v[56:59]
	v_mfma_f32_16x16x32_bf16 v[44:47], v[152:155], v[194:197], v[44:47]
	v_mfma_f32_16x16x32_bf16 v[40:43], v[160:163], v[194:197], v[40:43]
	v_mfma_f32_16x16x32_bf16 v[28:31], v[152:155], v[202:205], v[28:31]
	v_mfma_f32_16x16x32_bf16 v[24:27], v[160:163], v[202:205], v[24:27]
	v_mfma_f32_16x16x32_bf16 v[12:15], v[152:155], v[210:213], v[12:15]
	v_mfma_f32_16x16x32_bf16 v[8:11], v[160:163], v[210:213], v[8:11]
	v_mfma_f32_16x16x32_bf16 v[60:63], v[156:159], v[190:193], v[60:63]
	v_mfma_f32_16x16x32_bf16 v[56:59], v[164:167], v[190:193], v[56:59]
	v_mfma_f32_16x16x32_bf16 v[44:47], v[156:159], v[198:201], v[44:47]
	v_mfma_f32_16x16x32_bf16 v[40:43], v[164:167], v[198:201], v[40:43]
	v_mfma_f32_16x16x32_bf16 v[28:31], v[156:159], v[206:209], v[28:31]
	v_mfma_f32_16x16x32_bf16 v[24:27], v[164:167], v[206:209], v[24:27]
	v_mfma_f32_16x16x32_bf16 v[12:15], v[156:159], v[214:217], v[12:15]
	v_mfma_f32_16x16x32_bf16 v[8:11], v[164:167], v[214:217], v[8:11]
	s_setprio 0
	s_setprio 1
	v_mfma_f32_16x16x32_bf16 v[52:55], v[168:171], v[186:189], v[52:55]
	v_mfma_f32_16x16x32_bf16 v[48:51], v[178:181], v[186:189], v[48:51]
	v_mfma_f32_16x16x32_bf16 v[36:39], v[168:171], v[194:197], v[36:39]
	v_mfma_f32_16x16x32_bf16 v[32:35], v[178:181], v[194:197], v[32:35]
	v_mfma_f32_16x16x32_bf16 v[20:23], v[168:171], v[202:205], v[20:23]
	v_mfma_f32_16x16x32_bf16 v[16:19], v[178:181], v[202:205], v[16:19]
	v_mfma_f32_16x16x32_bf16 v[4:7], v[168:171], v[210:213], v[4:7]
	v_mfma_f32_16x16x32_bf16 v[0:3], v[178:181], v[210:213], v[0:3]
	v_mfma_f32_16x16x32_bf16 v[52:55], v[172:175], v[190:193], v[52:55]
	v_mfma_f32_16x16x32_bf16 v[48:51], v[182:185], v[190:193], v[48:51]
	v_mfma_f32_16x16x32_bf16 v[36:39], v[172:175], v[198:201], v[36:39]
	v_mfma_f32_16x16x32_bf16 v[32:35], v[182:185], v[198:201], v[32:35]
	v_mfma_f32_16x16x32_bf16 v[20:23], v[172:175], v[206:209], v[20:23]
	v_mfma_f32_16x16x32_bf16 v[16:19], v[182:185], v[206:209], v[16:19]
	s_setprio 2
	s_barrier
	v_mfma_f32_16x16x32_bf16 v[4:7], v[172:175], v[214:217], v[4:7]
	v_mfma_f32_16x16x32_bf16 v[0:3], v[182:185], v[214:217], v[0:3]
	s_setprio 0
	s_add_i32 s80, 0, 0x18000
	s_add_i32 s81, 0, 0x1c000
	v_add_u32_e32 v164, s80, v148
	v_add_u32_e32 v177, s81, v148
	ds_read_b128 v[152:155], v164
	ds_read_b128 v[156:159], v164 offset:1024
	ds_read_b128 v[160:163], v164 offset:2048
	ds_read_b128 v[164:167], v164 offset:3072
	ds_read_b128 v[168:171], v177
	ds_read_b128 v[172:175], v177 offset:1024
	ds_read_b128 v[178:181], v177 offset:2048
	ds_read_b128 v[182:185], v177 offset:3072
	s_add_u32 s56, s56, 0x160000
	s_addc_u32 s57, s57, 0
	s_mov_b32 m0, s59
	v_lshl_add_u64 v[224:225], s[56:57], 0, v[128:129]
	ds_read_b128 v[186:189], v151 offset:32768
	ds_read_b128 v[190:193], v151 offset:33792
	ds_read_b128 v[194:197], v151 offset:34816
	ds_read_b128 v[198:201], v151 offset:35840
	ds_read_b128 v[202:205], v151 offset:36864
	ds_read_b128 v[206:209], v151 offset:37888
	ds_read_b128 v[210:213], v151 offset:38912
	ds_read_b128 v[214:217], v151 offset:39936
	global_load_lds_dwordx4 v[224:225], off
	v_lshl_add_u64 v[224:225], s[56:57], 0, v[132:133]
	s_mov_b32 m0, s60
	s_nop 0
	global_load_lds_dwordx4 v[224:225], off
	s_waitcnt vmcnt(8)
	s_waitcnt lgkmcnt(0)
	s_barrier
	s_setprio 1
	s_waitcnt lgkmcnt(0)
	v_mfma_f32_16x16x32_bf16 v[124:127], v[152:155], v[186:189], v[124:127]
	v_mfma_f32_16x16x32_bf16 v[120:123], v[160:163], v[186:189], v[120:123]
	v_mfma_f32_16x16x32_bf16 v[108:111], v[152:155], v[194:197], v[108:111]
	v_mfma_f32_16x16x32_bf16 v[104:107], v[160:163], v[194:197], v[104:107]
	v_mfma_f32_16x16x32_bf16 v[92:95], v[152:155], v[202:205], v[92:95]
	v_mfma_f32_16x16x32_bf16 v[88:91], v[160:163], v[202:205], v[88:91]
	v_mfma_f32_16x16x32_bf16 v[76:79], v[152:155], v[210:213], v[76:79]
	v_mfma_f32_16x16x32_bf16 v[72:75], v[160:163], v[210:213], v[72:75]
	v_mfma_f32_16x16x32_bf16 v[124:127], v[156:159], v[190:193], v[124:127]
	v_mfma_f32_16x16x32_bf16 v[120:123], v[164:167], v[190:193], v[120:123]
	v_mfma_f32_16x16x32_bf16 v[108:111], v[156:159], v[198:201], v[108:111]
	v_mfma_f32_16x16x32_bf16 v[104:107], v[164:167], v[198:201], v[104:107]
	v_mfma_f32_16x16x32_bf16 v[92:95], v[156:159], v[206:209], v[92:95]
	v_mfma_f32_16x16x32_bf16 v[88:91], v[164:167], v[206:209], v[88:91]
	v_mfma_f32_16x16x32_bf16 v[76:79], v[156:159], v[214:217], v[76:79]
	v_mfma_f32_16x16x32_bf16 v[72:75], v[164:167], v[214:217], v[72:75]
	s_setprio 0
	s_setprio 1
	v_mfma_f32_16x16x32_bf16 v[116:119], v[168:171], v[186:189], v[116:119]
	v_mfma_f32_16x16x32_bf16 v[112:115], v[178:181], v[186:189], v[112:115]
	v_mfma_f32_16x16x32_bf16 v[100:103], v[168:171], v[194:197], v[100:103]
	v_mfma_f32_16x16x32_bf16 v[96:99], v[178:181], v[194:197], v[96:99]
	v_mfma_f32_16x16x32_bf16 v[84:87], v[168:171], v[202:205], v[84:87]
	v_mfma_f32_16x16x32_bf16 v[80:83], v[178:181], v[202:205], v[80:83]
	v_mfma_f32_16x16x32_bf16 v[68:71], v[168:171], v[210:213], v[68:71]
	v_mfma_f32_16x16x32_bf16 v[64:67], v[178:181], v[210:213], v[64:67]
	v_mfma_f32_16x16x32_bf16 v[116:119], v[172:175], v[190:193], v[116:119]
	v_mfma_f32_16x16x32_bf16 v[112:115], v[182:185], v[190:193], v[112:115]
	v_mfma_f32_16x16x32_bf16 v[100:103], v[172:175], v[198:201], v[100:103]
	v_mfma_f32_16x16x32_bf16 v[96:99], v[182:185], v[198:201], v[96:99]
	v_mfma_f32_16x16x32_bf16 v[84:87], v[172:175], v[206:209], v[84:87]
	v_mfma_f32_16x16x32_bf16 v[80:83], v[182:185], v[206:209], v[80:83]
	s_setprio 2
	s_barrier
; #define PG8_STAGE(bufoff, gbase, voff) do { _Pragma("unroll") for (int _i = 0; _i < 2; ++_i) \
;         __builtin_amdgcn_global_load_lds((const unsigned*)((const char*)(gbase) + (voff)[_i]), (LAS unsigned*)(lds + (bufoff) + ldsw + _i * 8192), 16, 0, 0); } while (0)
; #define PG8_LDA(dst, b, h) do { _Pragma("unroll") for (int m = 0; m < 4; ++m) _Pragma("unroll") for (int k = 0; k < 2; ++k) dst[m][k] = *(const LAS bf16x8*)(lds + PG8_SA(b, h) + aoff + m * 2048 + k * 1024); } while (0)
; #define PG8_MMA(ai, bj, At, Bt) do { __builtin_amdgcn_s_setprio(1); _Pragma("unroll") for (int m = 0; m < 4; ++m) _Pragma("unroll") for (int n = 0; n < 2; ++n) _Pragma("unroll") for (int k = 0; k < 2; ++k) \
;         acc[ai][bj][m][n] = __builtin_amdgcn_mfma_f32_16x16x32_bf16(Bt[n][k], At[m][k], acc[ai][bj][m][n], 0, 0, 0); __builtin_amdgcn_s_setprio(0); } while (0)
; #define PG8_WAIT_V(n) asm volatile("s_waitcnt vmcnt(" #n ")" ::: "memory")
; #define PG8_WAIT_L(n) asm volatile("s_waitcnt lgkmcnt(" #n ")" ::: "memory")
; #define PG8_BAR __builtin_amdgcn_s_barrier()
; #define PG8_SCHED __builtin_amdgcn_sched_barrier(0)
; template <class Epi, class Sched, bool ALIGN_EPI = true, bool SP2 = true>
; __device__ __forceinline__ void gemm_phase(LAS unsigned char* lds, const bf16_t* Ag, const bf16_t* Btg, const int K, const int lda, const int ldb, const Sched& S, const Epi& E) {
;     ...
;             PG8_WAIT_V(8); PG8_WAIT_L(0); PG8_BAR; PG8_MMA(0, 0, At, B0); PG8_MMA(0, 1, At, B1); PG8_BAR; PG8_SCHED;
;             PG8_LDA(At, 1, 1); PG8_STAGE(PG8_SB(1, 0), b3, voffB); PG8_STAGE(PG8_SB(1, 1), b3 + hstepB, voffB); PG8_STAGE(PG8_SA(1, 0), a3, voffA);
;             PG8_WAIT_V(8); PG8_WAIT_L(0); PG8_BAR; PG8_MMA(1, 0, At, B0); PG8_MMA(1, 1, At, B1); PG8_BAR; PG8_SCHED;
	v_mfma_f32_16x16x32_bf16 v[68:71], v[172:175], v[214:217], v[68:71]
	v_mfma_f32_16x16x32_bf16 v[64:67], v[182:185], v[214:217], v[64:67]
	s_setprio 0
	s_add_i32 s56, s80, s40
	v_lshl_add_u64 v[146:147], v[146:147], 0, s[6:7]
	s_mov_b32 m0, s56
	ds_read_b128 v[186:189], v151 offset:49152
	ds_read_b128 v[190:193], v151 offset:50176
	ds_read_b128 v[194:197], v151 offset:51200
	ds_read_b128 v[198:201], v151 offset:52224
	ds_read_b128 v[202:205], v151 offset:53248
	ds_read_b128 v[206:209], v151 offset:54272
	ds_read_b128 v[210:213], v151 offset:55296
	ds_read_b128 v[214:217], v151 offset:56320
	global_load_lds_dwordx4 v[146:147], off
	s_add_i32 m0, s56, 0x2000
	s_add_u32 s54, s54, 0x160080
	v_lshl_add_u64 v[146:147], v[218:219], 0, s[6:7]
	s_addc_u32 s55, s55, 0
	s_add_i32 s56, s81, s40
	global_load_lds_dwordx4 v[146:147], off
	v_lshl_add_u64 v[146:147], s[54:55], 0, v[130:131]
	s_mov_b32 m0, s56
	s_nop 0
	global_load_lds_dwordx4 v[146:147], off
	v_lshl_add_u64 v[146:147], s[54:55], 0, v[134:135]
	s_add_i32 m0, s56, 0x2000
	s_nop 0
	global_load_lds_dwordx4 v[146:147], off
	v_lshl_add_u64 v[146:147], v[220:221], 0, s[6:7]
	s_mov_b32 m0, s62
	s_nop 0
	global_load_lds_dwordx4 v[146:147], off
	v_lshl_add_u64 v[146:147], v[222:223], 0, s[6:7]
	s_mov_b32 m0, s63
	s_nop 0
	global_load_lds_dwordx4 v[146:147], off
	s_waitcnt vmcnt(8)
	s_waitcnt lgkmcnt(0)
	s_barrier
	s_setprio 1
	s_waitcnt lgkmcnt(0)
	v_mfma_f32_16x16x32_bf16 v[60:63], v[152:155], v[186:189], v[60:63]
	v_mfma_f32_16x16x32_bf16 v[56:59], v[160:163], v[186:189], v[56:59]
	v_mfma_f32_16x16x32_bf16 v[44:47], v[152:155], v[194:197], v[44:47]
	v_mfma_f32_16x16x32_bf16 v[40:43], v[160:163], v[194:197], v[40:43]
	v_mfma_f32_16x16x32_bf16 v[28:31], v[152:155], v[202:205], v[28:31]
	v_mfma_f32_16x16x32_bf16 v[24:27], v[160:163], v[202:205], v[24:27]
	v_mfma_f32_16x16x32_bf16 v[12:15], v[152:155], v[210:213], v[12:15]
	v_mfma_f32_16x16x32_bf16 v[8:11], v[160:163], v[210:213], v[8:11]
	v_mfma_f32_16x16x32_bf16 v[60:63], v[156:159], v[190:193], v[60:63]
	v_mfma_f32_16x16x32_bf16 v[56:59], v[164:167], v[190:193], v[56:59]
	v_mfma_f32_16x16x32_bf16 v[44:47], v[156:159], v[198:201], v[44:47]
	v_mfma_f32_16x16x32_bf16 v[40:43], v[164:167], v[198:201], v[40:43]
	v_mfma_f32_16x16x32_bf16 v[28:31], v[156:159], v[206:209], v[28:31]
	v_mfma_f32_16x16x32_bf16 v[24:27], v[164:167], v[206:209], v[24:27]
	v_mfma_f32_16x16x32_bf16 v[12:15], v[156:159], v[214:217], v[12:15]
	v_mfma_f32_16x16x32_bf16 v[8:11], v[164:167], v[214:217], v[8:11]
	s_setprio 0
	s_setprio 1
	v_mfma_f32_16x16x32_bf16 v[52:55], v[168:171], v[186:189], v[52:55]
	v_mfma_f32_16x16x32_bf16 v[48:51], v[178:181], v[186:189], v[48:51]
	v_mfma_f32_16x16x32_bf16 v[36:39], v[168:171], v[194:197], v[36:39]
	v_mfma_f32_16x16x32_bf16 v[32:35], v[178:181], v[194:197], v[32:35]
	v_mfma_f32_16x16x32_bf16 v[20:23], v[168:171], v[202:205], v[20:23]
	v_mfma_f32_16x16x32_bf16 v[16:19], v[178:181], v[202:205], v[16:19]
	v_mfma_f32_16x16x32_bf16 v[4:7], v[168:171], v[210:213], v[4:7]
	v_mfma_f32_16x16x32_bf16 v[0:3], v[178:181], v[210:213], v[0:3]
	v_mfma_f32_16x16x32_bf16 v[52:55], v[172:175], v[190:193], v[52:55]
	v_mfma_f32_16x16x32_bf16 v[48:51], v[182:185], v[190:193], v[48:51]
	v_mfma_f32_16x16x32_bf16 v[36:39], v[172:175], v[198:201], v[36:39]
	v_mfma_f32_16x16x32_bf16 v[32:35], v[182:185], v[198:201], v[32:35]
	v_mfma_f32_16x16x32_bf16 v[20:23], v[172:175], v[206:209], v[20:23]
	v_mfma_f32_16x16x32_bf16 v[16:19], v[182:185], v[206:209], v[16:19]
	s_setprio 2
	s_barrier
	v_mfma_f32_16x16x32_bf16 v[4:7], v[172:175], v[214:217], v[4:7]
	v_mfma_f32_16x16x32_bf16 v[0:3], v[182:185], v[214:217], v[0:3]
	s_setprio 0
	s_add_i32 s79, s79, 2
	s_add_u32 s52, s52, 0x100
	s_addc_u32 s53, s53, 0
	s_add_u32 s77, s77, 0x100
	s_addc_u32 s78, s78, 0
	s_cmpk_gt_u32 s79, 0x55
	s_cbranch_scc0 .LBB0_1448
	s_and_b64 vcc, exec, s[8:9]
	s_cbranch_vccz .LBB0_1451
	s_barrier
